# v66 + lever 4: one static s_setprio 1 for the trailing (wr==1) half over each K-loop, reset after the loop
# baseline (speedup 1.0000x reference)
; template <class Epi, class Sched, bool ALIGN_EPI = false, bool SP2 = false>
; __device__ __forceinline__ void gemm_phase(PG8_LAS unsigned char* lds, const Gemm g, const Sched& S, const Epi& E, const int wv) {
;     ...
; #pragma unroll
;         for (int a = 0; a < 2; ++a)
; #pragma unroll
;             for (int b = 0; b < 2; ++b)
; #pragma unroll
;                 for (int m = 0; m < 4; ++m)
; #pragma unroll
;                     for (int n = 0; n < 2; ++n) acc[a][b][m][n] = (f32x4){0.f, 0.f, 0.f, 0.f};
;         cur = nxt; cA = nA; cB = nB; ++ui;
.LBB0_174:
	s_ashr_i32 s35, s34, 31
	s_lshl_b64 s[46:47], s[34:35], 20
	s_add_u32 s46, s51, s46
	v_mov_b32_e32 v153, 0
	s_addc_u32 s47, s52, s47
	s_andn2_b64 vcc, exec, s[28:29]
	v_mov_b32_e32 v152, v153
	v_pk_mov_b32 v[150:151], v[152:153], v[152:153]
	v_pk_mov_b32 v[148:149], v[152:153], v[152:153]
	v_pk_mov_b32 v[146:147], v[152:153], v[152:153]
	v_pk_mov_b32 v[136:137], v[152:153], v[152:153]
	v_pk_mov_b32 v[134:135], v[152:153], v[152:153]
	v_pk_mov_b32 v[132:133], v[152:153], v[152:153]
	v_pk_mov_b32 v[130:131], v[152:153], v[152:153]
	v_pk_mov_b32 v[120:121], v[152:153], v[152:153]
	v_pk_mov_b32 v[118:119], v[152:153], v[152:153]
	v_pk_mov_b32 v[116:117], v[152:153], v[152:153]
	v_pk_mov_b32 v[114:115], v[152:153], v[152:153]
	v_pk_mov_b32 v[104:105], v[152:153], v[152:153]
	v_pk_mov_b32 v[102:103], v[152:153], v[152:153]
	v_pk_mov_b32 v[100:101], v[152:153], v[152:153]
	v_pk_mov_b32 v[98:99], v[152:153], v[152:153]
	v_pk_mov_b32 v[144:145], v[152:153], v[152:153]
	v_pk_mov_b32 v[142:143], v[152:153], v[152:153]
	v_pk_mov_b32 v[140:141], v[152:153], v[152:153]
	v_pk_mov_b32 v[138:139], v[152:153], v[152:153]
	v_pk_mov_b32 v[128:129], v[152:153], v[152:153]
	v_pk_mov_b32 v[126:127], v[152:153], v[152:153]
	v_pk_mov_b32 v[124:125], v[152:153], v[152:153]
	v_pk_mov_b32 v[122:123], v[152:153], v[152:153]
	v_pk_mov_b32 v[112:113], v[152:153], v[152:153]
	v_pk_mov_b32 v[110:111], v[152:153], v[152:153]
	v_pk_mov_b32 v[108:109], v[152:153], v[152:153]
	v_pk_mov_b32 v[106:107], v[152:153], v[152:153]
	v_pk_mov_b32 v[96:97], v[152:153], v[152:153]
	v_pk_mov_b32 v[94:95], v[152:153], v[152:153]
	v_pk_mov_b32 v[92:93], v[152:153], v[152:153]
	v_pk_mov_b32 v[90:91], v[152:153], v[152:153]
	v_pk_mov_b32 v[80:81], v[152:153], v[152:153]
	v_pk_mov_b32 v[78:79], v[152:153], v[152:153]
	v_pk_mov_b32 v[72:73], v[152:153], v[152:153]
	v_pk_mov_b32 v[70:71], v[152:153], v[152:153]
	v_pk_mov_b32 v[48:49], v[152:153], v[152:153]
	v_pk_mov_b32 v[46:47], v[152:153], v[152:153]
	v_pk_mov_b32 v[44:45], v[152:153], v[152:153]
	v_pk_mov_b32 v[42:43], v[152:153], v[152:153]
	v_pk_mov_b32 v[32:33], v[152:153], v[152:153]
	v_pk_mov_b32 v[30:31], v[152:153], v[152:153]
	v_pk_mov_b32 v[28:29], v[152:153], v[152:153]
	v_pk_mov_b32 v[26:27], v[152:153], v[152:153]
	v_pk_mov_b32 v[16:17], v[152:153], v[152:153]
	v_pk_mov_b32 v[14:15], v[152:153], v[152:153]
	v_pk_mov_b32 v[12:13], v[152:153], v[152:153]
	v_pk_mov_b32 v[10:11], v[152:153], v[152:153]
	v_pk_mov_b32 v[64:65], v[152:153], v[152:153]
	v_pk_mov_b32 v[62:63], v[152:153], v[152:153]
	v_pk_mov_b32 v[56:57], v[152:153], v[152:153]
	v_pk_mov_b32 v[54:55], v[152:153], v[152:153]
	v_pk_mov_b32 v[40:41], v[152:153], v[152:153]
	v_pk_mov_b32 v[38:39], v[152:153], v[152:153]
	v_pk_mov_b32 v[36:37], v[152:153], v[152:153]
	v_pk_mov_b32 v[34:35], v[152:153], v[152:153]
	v_pk_mov_b32 v[24:25], v[152:153], v[152:153]
	v_pk_mov_b32 v[22:23], v[152:153], v[152:153]
	v_pk_mov_b32 v[20:21], v[152:153], v[152:153]
	v_pk_mov_b32 v[18:19], v[152:153], v[152:153]
	v_pk_mov_b32 v[8:9], v[152:153], v[152:153]
	v_pk_mov_b32 v[6:7], v[152:153], v[152:153]
	v_pk_mov_b32 v[4:5], v[152:153], v[152:153]
	v_pk_mov_b32 v[2:3], v[152:153], v[152:153]
	s_cbranch_vccnz .LBB0_178
	s_and_b64 s[42:43], s[42:43], exec
	s_cselect_b32 s11, s47, s13
	s_cselect_b32 s35, s46, s12
	s_add_u32 s12, s12, 0x80080
	s_addc_u32 s13, s13, 0
	s_add_u32 s42, s14, 0x100
	v_mov_b32_e32 v2, 0
	s_addc_u32 s43, s15, 0
	s_mov_b32 s14, 0
	v_mov_b32_e32 v3, v2
	v_pk_mov_b32 v[4:5], v[2:3], v[2:3]
	v_pk_mov_b32 v[6:7], v[2:3], v[2:3]
	v_pk_mov_b32 v[8:9], v[2:3], v[2:3]
	v_pk_mov_b32 v[18:19], v[2:3], v[2:3]
	v_pk_mov_b32 v[20:21], v[2:3], v[2:3]
	v_pk_mov_b32 v[22:23], v[2:3], v[2:3]
	v_pk_mov_b32 v[24:25], v[2:3], v[2:3]
	v_pk_mov_b32 v[34:35], v[2:3], v[2:3]
	v_pk_mov_b32 v[36:37], v[2:3], v[2:3]
	v_pk_mov_b32 v[38:39], v[2:3], v[2:3]
	v_pk_mov_b32 v[40:41], v[2:3], v[2:3]
	v_pk_mov_b32 v[54:55], v[2:3], v[2:3]
	v_pk_mov_b32 v[56:57], v[2:3], v[2:3]
	v_pk_mov_b32 v[62:63], v[2:3], v[2:3]
	v_pk_mov_b32 v[64:65], v[2:3], v[2:3]
	v_pk_mov_b32 v[10:11], v[2:3], v[2:3]
	v_pk_mov_b32 v[12:13], v[2:3], v[2:3]
	v_pk_mov_b32 v[14:15], v[2:3], v[2:3]
	v_pk_mov_b32 v[16:17], v[2:3], v[2:3]
	v_pk_mov_b32 v[26:27], v[2:3], v[2:3]
	v_pk_mov_b32 v[28:29], v[2:3], v[2:3]
	v_pk_mov_b32 v[30:31], v[2:3], v[2:3]
	v_pk_mov_b32 v[32:33], v[2:3], v[2:3]
	v_pk_mov_b32 v[42:43], v[2:3], v[2:3]
	v_pk_mov_b32 v[44:45], v[2:3], v[2:3]
	v_pk_mov_b32 v[46:47], v[2:3], v[2:3]
	v_pk_mov_b32 v[48:49], v[2:3], v[2:3]
	v_pk_mov_b32 v[70:71], v[2:3], v[2:3]
	v_pk_mov_b32 v[72:73], v[2:3], v[2:3]
	v_pk_mov_b32 v[78:79], v[2:3], v[2:3]
	v_pk_mov_b32 v[80:81], v[2:3], v[2:3]
	v_pk_mov_b32 v[90:91], v[2:3], v[2:3]
	v_pk_mov_b32 v[92:93], v[2:3], v[2:3]
	v_pk_mov_b32 v[94:95], v[2:3], v[2:3]
	v_pk_mov_b32 v[96:97], v[2:3], v[2:3]
	v_pk_mov_b32 v[106:107], v[2:3], v[2:3]
	v_pk_mov_b32 v[108:109], v[2:3], v[2:3]
	v_pk_mov_b32 v[110:111], v[2:3], v[2:3]
	v_pk_mov_b32 v[112:113], v[2:3], v[2:3]
	v_pk_mov_b32 v[122:123], v[2:3], v[2:3]
	v_pk_mov_b32 v[124:125], v[2:3], v[2:3]
	v_pk_mov_b32 v[126:127], v[2:3], v[2:3]
	v_pk_mov_b32 v[128:129], v[2:3], v[2:3]
	v_pk_mov_b32 v[138:139], v[2:3], v[2:3]
	v_pk_mov_b32 v[140:141], v[2:3], v[2:3]
	v_pk_mov_b32 v[142:143], v[2:3], v[2:3]
	v_pk_mov_b32 v[144:145], v[2:3], v[2:3]
	v_pk_mov_b32 v[98:99], v[2:3], v[2:3]
	v_pk_mov_b32 v[100:101], v[2:3], v[2:3]
	v_pk_mov_b32 v[102:103], v[2:3], v[2:3]
	v_pk_mov_b32 v[104:105], v[2:3], v[2:3]
	v_pk_mov_b32 v[114:115], v[2:3], v[2:3]
	v_pk_mov_b32 v[116:117], v[2:3], v[2:3]
	v_pk_mov_b32 v[118:119], v[2:3], v[2:3]
	v_pk_mov_b32 v[120:121], v[2:3], v[2:3]
	v_pk_mov_b32 v[130:131], v[2:3], v[2:3]
	v_pk_mov_b32 v[132:133], v[2:3], v[2:3]
	v_pk_mov_b32 v[134:135], v[2:3], v[2:3]
	v_pk_mov_b32 v[136:137], v[2:3], v[2:3]
	v_pk_mov_b32 v[146:147], v[2:3], v[2:3]
	v_pk_mov_b32 v[148:149], v[2:3], v[2:3]
	v_pk_mov_b32 v[150:151], v[2:3], v[2:3]
	v_pk_mov_b32 v[152:153], v[2:3], v[2:3]
	v_add_u32_e32 v171, 0x10000, v185
	v_add_u32_e32 v173, 0x14000, v185
	v_add_u32_e32 v201, 0x18000, v185
	v_add_u32_e32 v227, 0x1c000, v185
	v_add_u32_e32 v59, 0x80000, v162
	v_add_u32_e32 v246, 0x80000, v164
	s_cmp_eq_u64 s[30:31], 0
	s_cbranch_scc0 .Lsp_skip_0
	s_setprio 1
; #define PG8_STAGE(bufoff, gbase, voff) do { _Pragma("unroll") for (int _i = 0; _i < 2; ++_i) \
;         __builtin_amdgcn_global_load_lds((const unsigned*)((const char*)(gbase) + (voff)[_i]), (PG8_LAS unsigned*)(lds + (bufoff) + ldsw + _i * 8192), 16, 0, 0); } while (0)
; #define PG8_LDA(dst, b, h) do { _Pragma("unroll") for (int m = 0; m < 4; ++m) _Pragma("unroll") for (int k = 0; k < 2; ++k) dst[m][k] = *(const PG8_LAS bf16x8*)(lds + PG8_SA(b, h) + aoff + m * 2048 + k * 1024); } while (0)
; #define PG8_LDB(dst, b, h) do { _Pragma("unroll") for (int n = 0; n < 2; ++n) _Pragma("unroll") for (int k = 0; k < 2; ++k) dst[n][k] = *(const PG8_LAS bf16x8*)(lds + PG8_SB(b, h) + boff + n * 2048 + k * 1024); } while (0)
; #define PG8_MMA(ai, bj, At, Bt) do { __builtin_amdgcn_s_setprio(1); _Pragma("unroll") for (int m = 0; m < 4; ++m) _Pragma("unroll") for (int n = 0; n < 2; ++n) _Pragma("unroll") for (int k = 0; k < 2; ++k) \
;         acc[ai][bj][m][n] = __builtin_amdgcn_mfma_f32_16x16x32_bf16(Bt[n][k], At[m][k], acc[ai][bj][m][n], 0, 0, 0); __builtin_amdgcn_s_setprio(0); } while (0)
; #define PG8_WAIT_V(n) asm volatile("s_waitcnt vmcnt(" #n ")" ::: "memory")
; #define PG8_WAIT_L(n) asm volatile("s_waitcnt lgkmcnt(" #n ")" ::: "memory")
; template <class Epi, class Sched, bool ALIGN_EPI = false, bool SP2 = false>
; __device__ __forceinline__ void gemm_phase(PG8_LAS unsigned char* lds, const Gemm g, const Sched& S, const Epi& E, const int wv) {
;     ...
;             const bool last = (t == nt - 2);
;             const char* a1 = cA + (size_t)(t + 1) * kstep;
;             const char* a2 = last ? nA : cA + (size_t)(t + 2) * kstep; const char* b2 = last ? nB : cB + (size_t)(t + 2) * kstep;
;             const char* a3 = a2 + kstep; const char* b3 = b2 + kstep;
;             if (last && has_next) S.a_ready(nxt);
;             if constexpr (SP2) {
;             PG8_LDB(B0, 0, 0); PG8_LDB(B1, 0, 1); PG8_SCHED; PG8_LDA(At, 0, 0); PG8_STAGE(PG8_SA(1, 1), a1 + hstepA, voffA);
;             PG8_WAIT_V(8); PG8_WAIT_L(0); PG8_BAR; PG8_MMA(0, 0, At, B0); PG8_MMA(0, 1, At, B1); PG8_BAR; PG8_SCHED;
;             PG8_LDA(At, 0, 1); PG8_STAGE(PG8_SB(0, 0), b2, voffB); PG8_STAGE(PG8_SB(0, 1), b2 + hstepB, voffB); PG8_STAGE(PG8_SA(0, 0), a2, voffA);
;             PG8_WAIT_V(8); PG8_WAIT_L(0); PG8_BAR; PG8_MMA(1, 0, At, B0); PG8_MMA(1, 1, At, B1); PG8_BAR; PG8_SCHED;
.Lsp_skip_0:
.LBB0_176:
	s_add_i32 s67, s14, 2
	s_add_u32 s68, s12, 0xfff80080
	s_addc_u32 s15, s13, -1
	s_cmp_eq_u32 s61, s14
	s_cselect_b32 s15, s11, s15
	s_cselect_b32 s14, s35, s68
	s_cselect_b32 s69, s45, s43
	s_cselect_b32 s68, s44, s42
	ds_read_b128 v[66:69], v171
	ds_read_b128 v[74:77], v171 offset:1024
	ds_read_b128 v[82:85], v171 offset:2048
	ds_read_b128 v[86:89], v171 offset:3072
	ds_read_b128 v[154:157], v173
	ds_read_b128 v[158:161], v173 offset:1024
	ds_read_b128 v[174:177], v173 offset:2048
	ds_read_b128 v[178:181], v173 offset:3072
	s_add_i32 m0, s54, 0xc000
	ds_read_b128 v[202:205], v200
	ds_read_b128 v[206:209], v200 offset:1024
	ds_read_b128 v[210:213], v200 offset:2048
	ds_read_b128 v[214:217], v200 offset:3072
	ds_read_b128 v[228:231], v200 offset:4096
	ds_read_b128 v[232:235], v200 offset:5120
	ds_read_b128 v[236:239], v200 offset:6144
	ds_read_b128 v[240:243], v200 offset:7168
	global_load_lds_dwordx4 v170, s[12:13]
	s_add_i32 m0, s54, 0xe000
	s_nop 0
	global_load_lds_dwordx4 v172, s[12:13]
	s_waitcnt vmcnt(8) lgkmcnt(0)
	s_barrier
	v_mfma_f32_16x16x32_bf16 v[150:153], v[66:69], v[202:205], v[150:153]
	v_mfma_f32_16x16x32_bf16 v[146:149], v[82:85], v[202:205], v[146:149]
	v_mfma_f32_16x16x32_bf16 v[134:137], v[66:69], v[210:213], v[134:137]
	v_mfma_f32_16x16x32_bf16 v[130:133], v[82:85], v[210:213], v[130:133]
	v_mfma_f32_16x16x32_bf16 v[118:121], v[66:69], v[228:231], v[118:121]
	v_mfma_f32_16x16x32_bf16 v[114:117], v[82:85], v[228:231], v[114:117]
	v_mfma_f32_16x16x32_bf16 v[102:105], v[66:69], v[236:239], v[102:105]
	v_mfma_f32_16x16x32_bf16 v[98:101], v[82:85], v[236:239], v[98:101]
	v_mfma_f32_16x16x32_bf16 v[150:153], v[74:77], v[206:209], v[150:153]
	v_mfma_f32_16x16x32_bf16 v[146:149], v[86:89], v[206:209], v[146:149]
	v_mfma_f32_16x16x32_bf16 v[134:137], v[74:77], v[214:217], v[134:137]
	v_mfma_f32_16x16x32_bf16 v[130:133], v[86:89], v[214:217], v[130:133]
	v_mfma_f32_16x16x32_bf16 v[118:121], v[74:77], v[232:235], v[118:121]
	v_mfma_f32_16x16x32_bf16 v[114:117], v[86:89], v[232:235], v[114:117]
	v_mfma_f32_16x16x32_bf16 v[102:105], v[74:77], v[240:243], v[102:105]
	v_mfma_f32_16x16x32_bf16 v[98:101], v[86:89], v[240:243], v[98:101]
	v_mfma_f32_16x16x32_bf16 v[142:145], v[154:157], v[202:205], v[142:145]
	v_mfma_f32_16x16x32_bf16 v[138:141], v[174:177], v[202:205], v[138:141]
	v_mfma_f32_16x16x32_bf16 v[126:129], v[154:157], v[210:213], v[126:129]
	v_mfma_f32_16x16x32_bf16 v[122:125], v[174:177], v[210:213], v[122:125]
	v_mfma_f32_16x16x32_bf16 v[110:113], v[154:157], v[228:231], v[110:113]
	v_mfma_f32_16x16x32_bf16 v[106:109], v[174:177], v[228:231], v[106:109]
	v_mfma_f32_16x16x32_bf16 v[94:97], v[154:157], v[236:239], v[94:97]
	v_mfma_f32_16x16x32_bf16 v[90:93], v[174:177], v[236:239], v[90:93]
	v_mfma_f32_16x16x32_bf16 v[142:145], v[158:161], v[206:209], v[142:145]
	v_mfma_f32_16x16x32_bf16 v[138:141], v[178:181], v[206:209], v[138:141]
	v_mfma_f32_16x16x32_bf16 v[126:129], v[158:161], v[214:217], v[126:129]
	v_mfma_f32_16x16x32_bf16 v[122:125], v[178:181], v[214:217], v[122:125]
	v_mfma_f32_16x16x32_bf16 v[110:113], v[158:161], v[232:235], v[110:113]
	v_mfma_f32_16x16x32_bf16 v[106:109], v[178:181], v[232:235], v[106:109]
	v_mfma_f32_16x16x32_bf16 v[94:97], v[158:161], v[240:243], v[94:97]
	v_mfma_f32_16x16x32_bf16 v[90:93], v[178:181], v[240:243], v[90:93]
	s_barrier
	s_add_i32 s70, s53, 0x10000
	v_lshl_add_u64 v[218:219], s[68:69], 0, v[0:1]
	s_mov_b32 m0, s70
	ds_read_b128 v[202:205], v200 offset:16384
	ds_read_b128 v[206:209], v200 offset:17408
	ds_read_b128 v[210:213], v200 offset:18432
	ds_read_b128 v[214:217], v200 offset:19456
	ds_read_b128 v[228:231], v200 offset:20480
	ds_read_b128 v[232:235], v200 offset:21504
	ds_read_b128 v[236:239], v200 offset:22528
	ds_read_b128 v[240:243], v200 offset:23552
	global_load_lds_dwordx4 v[218:219], off
	s_add_i32 m0, s70, 0x2000
	v_lshl_add_u64 v[244:245], s[68:69], 0, v[166:167]
	s_add_u32 s68, s68, s24
	s_addc_u32 s69, s69, s25
	s_add_i32 s70, s53, 0x14000
	global_load_lds_dwordx4 v[244:245], off
	s_mov_b32 m0, s70
	global_load_lds_dwordx4 v0, s[68:69]
	s_add_i32 m0, s70, 0x2000
	global_load_lds_dwordx4 v166, s[68:69]
	s_mov_b32 m0, s54
	global_load_lds_dwordx4 v162, s[14:15]
	s_mov_b32 m0, s55
	s_nop 0
	global_load_lds_dwordx4 v164, s[14:15]
	s_waitcnt vmcnt(8) lgkmcnt(0)
	s_barrier
	v_mfma_f32_16x16x32_bf16 v[78:81], v[66:69], v[202:205], v[78:81]
	v_mfma_f32_16x16x32_bf16 v[70:73], v[82:85], v[202:205], v[70:73]
	v_mfma_f32_16x16x32_bf16 v[46:49], v[66:69], v[210:213], v[46:49]
	v_mfma_f32_16x16x32_bf16 v[42:45], v[82:85], v[210:213], v[42:45]
	v_mfma_f32_16x16x32_bf16 v[30:33], v[66:69], v[228:231], v[30:33]
	v_mfma_f32_16x16x32_bf16 v[26:29], v[82:85], v[228:231], v[26:29]
	v_mfma_f32_16x16x32_bf16 v[14:17], v[66:69], v[236:239], v[14:17]
	v_mfma_f32_16x16x32_bf16 v[10:13], v[82:85], v[236:239], v[10:13]
	v_mfma_f32_16x16x32_bf16 v[78:81], v[74:77], v[206:209], v[78:81]
	v_mfma_f32_16x16x32_bf16 v[70:73], v[86:89], v[206:209], v[70:73]
	v_mfma_f32_16x16x32_bf16 v[46:49], v[74:77], v[214:217], v[46:49]
	v_mfma_f32_16x16x32_bf16 v[42:45], v[86:89], v[214:217], v[42:45]
	v_mfma_f32_16x16x32_bf16 v[30:33], v[74:77], v[232:235], v[30:33]
	v_mfma_f32_16x16x32_bf16 v[26:29], v[86:89], v[232:235], v[26:29]
	v_mfma_f32_16x16x32_bf16 v[14:17], v[74:77], v[240:243], v[14:17]
	v_mfma_f32_16x16x32_bf16 v[10:13], v[86:89], v[240:243], v[10:13]
	v_mfma_f32_16x16x32_bf16 v[60:63], v[154:157], v[202:205], v[62:65]
	v_mfma_f32_16x16x32_bf16 v[54:57], v[174:177], v[202:205], v[54:57]
	v_mfma_f32_16x16x32_bf16 v[38:41], v[154:157], v[210:213], v[38:41]
	v_mfma_f32_16x16x32_bf16 v[34:37], v[174:177], v[210:213], v[34:37]
	v_mfma_f32_16x16x32_bf16 v[22:25], v[154:157], v[228:231], v[22:25]
	v_mfma_f32_16x16x32_bf16 v[18:21], v[174:177], v[228:231], v[18:21]
	v_mfma_f32_16x16x32_bf16 v[6:9], v[154:157], v[236:239], v[6:9]
	v_mfma_f32_16x16x32_bf16 v[2:5], v[174:177], v[236:239], v[2:5]
	v_mfma_f32_16x16x32_bf16 v[60:63], v[158:161], v[206:209], v[60:63]
	v_mfma_f32_16x16x32_bf16 v[54:57], v[178:181], v[206:209], v[54:57]
	v_mfma_f32_16x16x32_bf16 v[38:41], v[158:161], v[214:217], v[38:41]
	v_mfma_f32_16x16x32_bf16 v[34:37], v[178:181], v[214:217], v[34:37]
	v_mfma_f32_16x16x32_bf16 v[22:25], v[158:161], v[232:235], v[22:25]
	v_mfma_f32_16x16x32_bf16 v[18:21], v[178:181], v[232:235], v[18:21]
	v_mfma_f32_16x16x32_bf16 v[6:9], v[158:161], v[240:243], v[6:9]
	v_mfma_f32_16x16x32_bf16 v[2:5], v[178:181], v[240:243], v[2:5]
	s_barrier
; #define PG8_STAGE(bufoff, gbase, voff) do { _Pragma("unroll") for (int _i = 0; _i < 2; ++_i) \
;         __builtin_amdgcn_global_load_lds((const unsigned*)((const char*)(gbase) + (voff)[_i]), (PG8_LAS unsigned*)(lds + (bufoff) + ldsw + _i * 8192), 16, 0, 0); } while (0)
; #define PG8_LDA(dst, b, h) do { _Pragma("unroll") for (int m = 0; m < 4; ++m) _Pragma("unroll") for (int k = 0; k < 2; ++k) dst[m][k] = *(const PG8_LAS bf16x8*)(lds + PG8_SA(b, h) + aoff + m * 2048 + k * 1024); } while (0)
; #define PG8_LDB(dst, b, h) do { _Pragma("unroll") for (int n = 0; n < 2; ++n) _Pragma("unroll") for (int k = 0; k < 2; ++k) dst[n][k] = *(const PG8_LAS bf16x8*)(lds + PG8_SB(b, h) + boff + n * 2048 + k * 1024); } while (0)
; #define PG8_MMA(ai, bj, At, Bt) do { __builtin_amdgcn_s_setprio(1); _Pragma("unroll") for (int m = 0; m < 4; ++m) _Pragma("unroll") for (int n = 0; n < 2; ++n) _Pragma("unroll") for (int k = 0; k < 2; ++k) \
;         acc[ai][bj][m][n] = __builtin_amdgcn_mfma_f32_16x16x32_bf16(Bt[n][k], At[m][k], acc[ai][bj][m][n], 0, 0, 0); __builtin_amdgcn_s_setprio(0); } while (0)
; #define PG8_WAIT_V(n) asm volatile("s_waitcnt vmcnt(" #n ")" ::: "memory")
; #define PG8_WAIT_L(n) asm volatile("s_waitcnt lgkmcnt(" #n ")" ::: "memory")
; #define PG8_BAR __builtin_amdgcn_s_barrier()
; #define PG8_SCHED __builtin_amdgcn_sched_barrier(0)
; template <class Epi, class Sched, bool ALIGN_EPI = false, bool SP2 = false>
; __device__ __forceinline__ void gemm_phase(PG8_LAS unsigned char* lds, const Gemm g, const Sched& S, const Epi& E, const int wv) {
;     ...
;             PG8_LDB(B0, 1, 0); PG8_LDB(B1, 1, 1); PG8_SCHED; PG8_LDA(At, 1, 0); PG8_STAGE(PG8_SA(0, 1), a2 + hstepA, voffA);
;             PG8_WAIT_V(8); PG8_WAIT_L(0); PG8_BAR; PG8_MMA(0, 0, At, B0); PG8_MMA(0, 1, At, B1); PG8_BAR; PG8_SCHED;
;             PG8_LDA(At, 1, 1); PG8_STAGE(PG8_SB(1, 0), b3, voffB); PG8_STAGE(PG8_SB(1, 1), b3 + hstepB, voffB); PG8_STAGE(PG8_SA(1, 0), a3, voffA);
;             PG8_WAIT_V(8); PG8_WAIT_L(0); PG8_BAR; PG8_MMA(1, 0, At, B0); PG8_MMA(1, 1, At, B1); PG8_BAR; PG8_SCHED;
	ds_read_b128 v[64:67], v201
	ds_read_b128 v[74:77], v201 offset:1024
	ds_read_b128 v[82:85], v201 offset:2048
	ds_read_b128 v[86:89], v201 offset:3072
	ds_read_b128 v[154:157], v227
	ds_read_b128 v[158:161], v227 offset:1024
	ds_read_b128 v[174:177], v227 offset:2048
	ds_read_b128 v[178:181], v227 offset:3072
	s_mov_b32 m0, s56
	ds_read_b128 v[202:205], v200 offset:32768
	ds_read_b128 v[206:209], v200 offset:33792
	ds_read_b128 v[210:213], v200 offset:34816
	ds_read_b128 v[214:217], v200 offset:35840
	ds_read_b128 v[228:231], v200 offset:36864
	ds_read_b128 v[232:235], v200 offset:37888
	ds_read_b128 v[236:239], v200 offset:38912
	ds_read_b128 v[240:243], v200 offset:39936
	global_load_lds_dwordx4 v59, s[14:15]
	s_mov_b32 m0, s57
	s_nop 0
	global_load_lds_dwordx4 v246, s[14:15]
	s_waitcnt vmcnt(8) lgkmcnt(0)
	s_barrier
	v_mfma_f32_16x16x32_bf16 v[150:153], v[64:67], v[202:205], v[150:153]
	v_mfma_f32_16x16x32_bf16 v[146:149], v[82:85], v[202:205], v[146:149]
	v_mfma_f32_16x16x32_bf16 v[134:137], v[64:67], v[210:213], v[134:137]
	v_mfma_f32_16x16x32_bf16 v[130:133], v[82:85], v[210:213], v[130:133]
	v_mfma_f32_16x16x32_bf16 v[118:121], v[64:67], v[228:231], v[118:121]
	v_mfma_f32_16x16x32_bf16 v[114:117], v[82:85], v[228:231], v[114:117]
	v_mfma_f32_16x16x32_bf16 v[102:105], v[64:67], v[236:239], v[102:105]
	v_mfma_f32_16x16x32_bf16 v[98:101], v[82:85], v[236:239], v[98:101]
	v_mfma_f32_16x16x32_bf16 v[150:153], v[74:77], v[206:209], v[150:153]
	v_mfma_f32_16x16x32_bf16 v[146:149], v[86:89], v[206:209], v[146:149]
	v_mfma_f32_16x16x32_bf16 v[134:137], v[74:77], v[214:217], v[134:137]
	v_mfma_f32_16x16x32_bf16 v[130:133], v[86:89], v[214:217], v[130:133]
	v_mfma_f32_16x16x32_bf16 v[118:121], v[74:77], v[232:235], v[118:121]
	v_mfma_f32_16x16x32_bf16 v[114:117], v[86:89], v[232:235], v[114:117]
	v_mfma_f32_16x16x32_bf16 v[102:105], v[74:77], v[240:243], v[102:105]
	v_mfma_f32_16x16x32_bf16 v[98:101], v[86:89], v[240:243], v[98:101]
	v_mfma_f32_16x16x32_bf16 v[142:145], v[154:157], v[202:205], v[142:145]
	v_mfma_f32_16x16x32_bf16 v[138:141], v[174:177], v[202:205], v[138:141]
	v_mfma_f32_16x16x32_bf16 v[126:129], v[154:157], v[210:213], v[126:129]
	v_mfma_f32_16x16x32_bf16 v[122:125], v[174:177], v[210:213], v[122:125]
	v_mfma_f32_16x16x32_bf16 v[110:113], v[154:157], v[228:231], v[110:113]
	v_mfma_f32_16x16x32_bf16 v[106:109], v[174:177], v[228:231], v[106:109]
	v_mfma_f32_16x16x32_bf16 v[94:97], v[154:157], v[236:239], v[94:97]
	v_mfma_f32_16x16x32_bf16 v[90:93], v[174:177], v[236:239], v[90:93]
	v_mfma_f32_16x16x32_bf16 v[142:145], v[158:161], v[206:209], v[142:145]
	v_mfma_f32_16x16x32_bf16 v[138:141], v[178:181], v[206:209], v[138:141]
	v_mfma_f32_16x16x32_bf16 v[126:129], v[158:161], v[214:217], v[126:129]
	v_mfma_f32_16x16x32_bf16 v[122:125], v[178:181], v[214:217], v[122:125]
	v_mfma_f32_16x16x32_bf16 v[110:113], v[158:161], v[232:235], v[110:113]
	v_mfma_f32_16x16x32_bf16 v[106:109], v[178:181], v[232:235], v[106:109]
	v_mfma_f32_16x16x32_bf16 v[94:97], v[158:161], v[240:243], v[94:97]
	v_mfma_f32_16x16x32_bf16 v[90:93], v[178:181], v[240:243], v[90:93]
	s_barrier
	s_add_i32 m0, s53, 0x17f80
	ds_read_b128 v[202:205], v200 offset:49152
	ds_read_b128 v[206:209], v200 offset:50176
	ds_read_b128 v[210:213], v200 offset:51200
	ds_read_b128 v[214:217], v200 offset:52224
	ds_read_b128 v[228:231], v200 offset:53248
	ds_read_b128 v[232:235], v200 offset:54272
	ds_read_b128 v[236:239], v200 offset:55296
	ds_read_b128 v[240:243], v200 offset:56320
	global_load_lds_dwordx4 v[218:219], off offset:128
	s_add_i32 m0, s53, 0x19f80
	global_load_lds_dwordx4 v[244:245], off offset:128
	s_add_i32 m0, s53, 0x1bf80
	s_nop 0
	global_load_lds_dwordx4 v0, s[68:69] offset:128
	s_add_i32 m0, s53, 0x1df80
	s_nop 0
	global_load_lds_dwordx4 v166, s[68:69] offset:128
	s_add_i32 m0, s58, 0xffffff80
	s_nop 0
	global_load_lds_dwordx4 v162, s[14:15] offset:128
	s_add_i32 m0, s59, 0xffffff80
	s_nop 0
	global_load_lds_dwordx4 v164, s[14:15] offset:128
	s_waitcnt vmcnt(8) lgkmcnt(0)
	s_barrier
	v_mfma_f32_16x16x32_bf16 v[78:81], v[64:67], v[202:205], v[78:81]
	v_mfma_f32_16x16x32_bf16 v[68:71], v[82:85], v[202:205], v[70:73]
	v_mfma_f32_16x16x32_bf16 v[46:49], v[64:67], v[210:213], v[46:49]
	v_mfma_f32_16x16x32_bf16 v[42:45], v[82:85], v[210:213], v[42:45]
	v_mfma_f32_16x16x32_bf16 v[30:33], v[64:67], v[228:231], v[30:33]
	v_mfma_f32_16x16x32_bf16 v[26:29], v[82:85], v[228:231], v[26:29]
	v_mfma_f32_16x16x32_bf16 v[14:17], v[64:67], v[236:239], v[14:17]
	v_mfma_f32_16x16x32_bf16 v[10:13], v[82:85], v[236:239], v[10:13]
	v_mfma_f32_16x16x32_bf16 v[78:81], v[74:77], v[206:209], v[78:81]
	v_mfma_f32_16x16x32_bf16 v[70:73], v[86:89], v[206:209], v[68:71]
	v_mfma_f32_16x16x32_bf16 v[46:49], v[74:77], v[214:217], v[46:49]
	v_mfma_f32_16x16x32_bf16 v[42:45], v[86:89], v[214:217], v[42:45]
	v_mfma_f32_16x16x32_bf16 v[30:33], v[74:77], v[232:235], v[30:33]
	v_mfma_f32_16x16x32_bf16 v[26:29], v[86:89], v[232:235], v[26:29]
	v_mfma_f32_16x16x32_bf16 v[14:17], v[74:77], v[240:243], v[14:17]
	v_mfma_f32_16x16x32_bf16 v[10:13], v[86:89], v[240:243], v[10:13]
	v_mfma_f32_16x16x32_bf16 v[60:63], v[154:157], v[202:205], v[60:63]
	v_mfma_f32_16x16x32_bf16 v[54:57], v[174:177], v[202:205], v[54:57]
	v_mfma_f32_16x16x32_bf16 v[38:41], v[154:157], v[210:213], v[38:41]
	v_mfma_f32_16x16x32_bf16 v[34:37], v[174:177], v[210:213], v[34:37]
	v_mfma_f32_16x16x32_bf16 v[22:25], v[154:157], v[228:231], v[22:25]
	v_mfma_f32_16x16x32_bf16 v[18:21], v[174:177], v[228:231], v[18:21]
	v_mfma_f32_16x16x32_bf16 v[6:9], v[154:157], v[236:239], v[6:9]
	v_mfma_f32_16x16x32_bf16 v[2:5], v[174:177], v[236:239], v[2:5]
	v_mfma_f32_16x16x32_bf16 v[62:65], v[158:161], v[206:209], v[60:63]
	v_mfma_f32_16x16x32_bf16 v[54:57], v[178:181], v[206:209], v[54:57]
	v_mfma_f32_16x16x32_bf16 v[38:41], v[158:161], v[214:217], v[38:41]
	v_mfma_f32_16x16x32_bf16 v[34:37], v[178:181], v[214:217], v[34:37]
	v_mfma_f32_16x16x32_bf16 v[22:25], v[158:161], v[232:235], v[22:25]
	v_mfma_f32_16x16x32_bf16 v[18:21], v[178:181], v[232:235], v[18:21]
	v_mfma_f32_16x16x32_bf16 v[6:9], v[158:161], v[240:243], v[6:9]
	v_mfma_f32_16x16x32_bf16 v[2:5], v[178:181], v[240:243], v[2:5]
	s_barrier
	s_add_u32 s12, s12, 0x100
	s_addc_u32 s13, s13, 0
	s_add_u32 s42, s42, 0x100
	s_addc_u32 s43, s43, 0
	s_cmp_ge_i32 s67, s60
	s_mov_b32 s14, s67
	s_cbranch_scc0 .LBB0_176
	s_setprio 0
	s_movk_i32 s68, 0x4000
	s_movk_i32 s69, 0x6000
	s_mov_b32 s70, 0x18000
	s_mov_b32 s71, 0x3f317217

; template <class Epi, class Sched, bool ALIGN_EPI = false, bool SP2 = false>
; __device__ __forceinline__ void gemm_phase(PG8_LAS unsigned char* lds, const Gemm g, const Sched& S, const Epi& E, const int wv) {
;     ...
; #pragma unroll
;         for (int a = 0; a < 2; ++a)
; #pragma unroll
;             for (int b = 0; b < 2; ++b)
; #pragma unroll
;                 for (int m = 0; m < 4; ++m)
; #pragma unroll
;                     for (int n = 0; n < 2; ++n) acc[a][b][m][n] = (f32x4){0.f, 0.f, 0.f, 0.f};
;         cur = nxt; cA = nA; cB = nB; ++ui;
.LBB0_334:
	v_mov_b32_e32 v141, 0
	s_andn2_b64 vcc, exec, s[34:35]
	v_mov_b32_e32 v140, v141
	v_pk_mov_b32 v[138:139], v[140:141], v[140:141]
	v_pk_mov_b32 v[144:145], v[140:141], v[140:141]
	v_pk_mov_b32 v[142:143], v[140:141], v[140:141]
	v_pk_mov_b32 v[128:129], v[140:141], v[140:141]
	v_pk_mov_b32 v[126:127], v[140:141], v[140:141]
	v_pk_mov_b32 v[124:125], v[140:141], v[140:141]
	v_pk_mov_b32 v[122:123], v[140:141], v[140:141]
	v_pk_mov_b32 v[112:113], v[140:141], v[140:141]
	v_pk_mov_b32 v[110:111], v[140:141], v[140:141]
	v_pk_mov_b32 v[108:109], v[140:141], v[140:141]
	v_pk_mov_b32 v[106:107], v[140:141], v[140:141]
	v_pk_mov_b32 v[96:97], v[140:141], v[140:141]
	v_pk_mov_b32 v[94:95], v[140:141], v[140:141]
	v_pk_mov_b32 v[92:93], v[140:141], v[140:141]
	v_pk_mov_b32 v[90:91], v[140:141], v[140:141]
	v_pk_mov_b32 v[136:137], v[140:141], v[140:141]
	v_pk_mov_b32 v[134:135], v[140:141], v[140:141]
	v_pk_mov_b32 v[132:133], v[140:141], v[140:141]
	v_pk_mov_b32 v[130:131], v[140:141], v[140:141]
	v_pk_mov_b32 v[120:121], v[140:141], v[140:141]
	v_pk_mov_b32 v[118:119], v[140:141], v[140:141]
	v_pk_mov_b32 v[116:117], v[140:141], v[140:141]
	v_pk_mov_b32 v[114:115], v[140:141], v[140:141]
	v_pk_mov_b32 v[104:105], v[140:141], v[140:141]
	v_pk_mov_b32 v[102:103], v[140:141], v[140:141]
	v_pk_mov_b32 v[100:101], v[140:141], v[140:141]
	v_pk_mov_b32 v[98:99], v[140:141], v[140:141]
	v_pk_mov_b32 v[88:89], v[140:141], v[140:141]
	v_pk_mov_b32 v[86:87], v[140:141], v[140:141]
	v_pk_mov_b32 v[84:85], v[140:141], v[140:141]
	v_pk_mov_b32 v[82:83], v[140:141], v[140:141]
	v_pk_mov_b32 v[80:81], v[140:141], v[140:141]
	v_pk_mov_b32 v[78:79], v[140:141], v[140:141]
	v_pk_mov_b32 v[76:77], v[140:141], v[140:141]
	v_pk_mov_b32 v[74:75], v[140:141], v[140:141]
	v_pk_mov_b32 v[64:65], v[140:141], v[140:141]
	v_pk_mov_b32 v[62:63], v[140:141], v[140:141]
	v_pk_mov_b32 v[60:61], v[140:141], v[140:141]
	v_pk_mov_b32 v[58:59], v[140:141], v[140:141]
	s_nop 0
	v_pk_mov_b32 v[40:41], v[140:141], v[140:141]
	v_pk_mov_b32 v[38:39], v[140:141], v[140:141]
	v_pk_mov_b32 v[36:37], v[140:141], v[140:141]
	v_pk_mov_b32 v[34:35], v[140:141], v[140:141]
	v_pk_mov_b32 v[16:17], v[140:141], v[140:141]
	v_pk_mov_b32 v[14:15], v[140:141], v[140:141]
	v_pk_mov_b32 v[12:13], v[140:141], v[140:141]
	v_pk_mov_b32 v[10:11], v[140:141], v[140:141]
	v_pk_mov_b32 v[72:73], v[140:141], v[140:141]
	v_pk_mov_b32 v[70:71], v[140:141], v[140:141]
	v_pk_mov_b32 v[68:69], v[140:141], v[140:141]
	v_pk_mov_b32 v[66:67], v[140:141], v[140:141]
	v_pk_mov_b32 v[56:57], v[140:141], v[140:141]
	v_pk_mov_b32 v[54:55], v[140:141], v[140:141]
	v_pk_mov_b32 v[52:53], v[140:141], v[140:141]
	v_pk_mov_b32 v[50:51], v[140:141], v[140:141]
	v_pk_mov_b32 v[24:25], v[140:141], v[140:141]
	v_pk_mov_b32 v[22:23], v[140:141], v[140:141]
	v_pk_mov_b32 v[20:21], v[140:141], v[140:141]
	v_pk_mov_b32 v[18:19], v[140:141], v[140:141]
	v_pk_mov_b32 v[8:9], v[140:141], v[140:141]
	v_pk_mov_b32 v[6:7], v[140:141], v[140:141]
	v_pk_mov_b32 v[4:5], v[140:141], v[140:141]
	v_pk_mov_b32 v[2:3], v[140:141], v[140:141]
	s_cbranch_vccnz .LBB0_337
	s_add_u32 s12, s40, 0x80080
	s_addc_u32 s13, s41, 0
	s_add_u32 s11, s14, 0x100
	v_mov_b32_e32 v2, 0
	s_addc_u32 s17, s15, 0
	s_mov_b32 s14, 0
	v_mov_b32_e32 v3, v2
	v_pk_mov_b32 v[4:5], v[2:3], v[2:3]
	v_pk_mov_b32 v[6:7], v[2:3], v[2:3]
	v_pk_mov_b32 v[8:9], v[2:3], v[2:3]
	v_pk_mov_b32 v[18:19], v[2:3], v[2:3]
	v_pk_mov_b32 v[20:21], v[2:3], v[2:3]
	v_pk_mov_b32 v[22:23], v[2:3], v[2:3]
	v_pk_mov_b32 v[24:25], v[2:3], v[2:3]
	v_pk_mov_b32 v[50:51], v[2:3], v[2:3]
	v_pk_mov_b32 v[52:53], v[2:3], v[2:3]
	v_pk_mov_b32 v[54:55], v[2:3], v[2:3]
	v_pk_mov_b32 v[56:57], v[2:3], v[2:3]
	v_pk_mov_b32 v[66:67], v[2:3], v[2:3]
	v_pk_mov_b32 v[68:69], v[2:3], v[2:3]
	v_pk_mov_b32 v[70:71], v[2:3], v[2:3]
	v_pk_mov_b32 v[72:73], v[2:3], v[2:3]
	v_pk_mov_b32 v[10:11], v[2:3], v[2:3]
	v_pk_mov_b32 v[12:13], v[2:3], v[2:3]
	v_pk_mov_b32 v[14:15], v[2:3], v[2:3]
	v_pk_mov_b32 v[16:17], v[2:3], v[2:3]
	v_pk_mov_b32 v[34:35], v[2:3], v[2:3]
	v_pk_mov_b32 v[36:37], v[2:3], v[2:3]
	v_pk_mov_b32 v[38:39], v[2:3], v[2:3]
	v_pk_mov_b32 v[40:41], v[2:3], v[2:3]
	v_pk_mov_b32 v[58:59], v[2:3], v[2:3]
	v_pk_mov_b32 v[60:61], v[2:3], v[2:3]
	v_pk_mov_b32 v[62:63], v[2:3], v[2:3]
	v_pk_mov_b32 v[64:65], v[2:3], v[2:3]
	v_pk_mov_b32 v[74:75], v[2:3], v[2:3]
	v_pk_mov_b32 v[76:77], v[2:3], v[2:3]
	v_pk_mov_b32 v[78:79], v[2:3], v[2:3]
	v_pk_mov_b32 v[80:81], v[2:3], v[2:3]
	v_pk_mov_b32 v[82:83], v[2:3], v[2:3]
	v_pk_mov_b32 v[84:85], v[2:3], v[2:3]
	v_pk_mov_b32 v[86:87], v[2:3], v[2:3]
	v_pk_mov_b32 v[88:89], v[2:3], v[2:3]
	v_pk_mov_b32 v[98:99], v[2:3], v[2:3]
	v_pk_mov_b32 v[100:101], v[2:3], v[2:3]
	v_pk_mov_b32 v[102:103], v[2:3], v[2:3]
	v_pk_mov_b32 v[104:105], v[2:3], v[2:3]
	v_pk_mov_b32 v[114:115], v[2:3], v[2:3]
	v_pk_mov_b32 v[116:117], v[2:3], v[2:3]
	v_pk_mov_b32 v[118:119], v[2:3], v[2:3]
	v_pk_mov_b32 v[120:121], v[2:3], v[2:3]
	v_pk_mov_b32 v[130:131], v[2:3], v[2:3]
	v_pk_mov_b32 v[132:133], v[2:3], v[2:3]
	v_pk_mov_b32 v[134:135], v[2:3], v[2:3]
	v_pk_mov_b32 v[136:137], v[2:3], v[2:3]
	v_pk_mov_b32 v[90:91], v[2:3], v[2:3]
	v_pk_mov_b32 v[92:93], v[2:3], v[2:3]
	v_pk_mov_b32 v[94:95], v[2:3], v[2:3]
	v_pk_mov_b32 v[96:97], v[2:3], v[2:3]
	v_pk_mov_b32 v[106:107], v[2:3], v[2:3]
	v_pk_mov_b32 v[108:109], v[2:3], v[2:3]
	v_pk_mov_b32 v[110:111], v[2:3], v[2:3]
	v_pk_mov_b32 v[112:113], v[2:3], v[2:3]
	v_pk_mov_b32 v[122:123], v[2:3], v[2:3]
	v_pk_mov_b32 v[124:125], v[2:3], v[2:3]
	v_pk_mov_b32 v[126:127], v[2:3], v[2:3]
	v_pk_mov_b32 v[128:129], v[2:3], v[2:3]
	v_pk_mov_b32 v[142:143], v[2:3], v[2:3]
	v_pk_mov_b32 v[144:145], v[2:3], v[2:3]
	v_pk_mov_b32 v[138:139], v[2:3], v[2:3]
	v_pk_mov_b32 v[140:141], v[2:3], v[2:3]
	v_add_u32_e32 v171, 0x10000, v197
	v_add_u32_e32 v227, 0x14000, v197
	v_add_u32_e32 v244, 0x18000, v197
	v_add_u32_e32 v245, 0x1c000, v197
	v_add_u32_e32 v246, 0x80000, v166
	v_add_u32_e32 v247, 0x80000, v164
	s_cmp_eq_u64 s[42:43], 0
	s_cbranch_scc0 .Lsp_skip_1
	s_setprio 1
; #define PG8_STAGE(bufoff, gbase, voff) do { _Pragma("unroll") for (int _i = 0; _i < 2; ++_i) \
;         __builtin_amdgcn_global_load_lds((const unsigned*)((const char*)(gbase) + (voff)[_i]), (PG8_LAS unsigned*)(lds + (bufoff) + ldsw + _i * 8192), 16, 0, 0); } while (0)
; #define PG8_LDA(dst, b, h) do { _Pragma("unroll") for (int m = 0; m < 4; ++m) _Pragma("unroll") for (int k = 0; k < 2; ++k) dst[m][k] = *(const PG8_LAS bf16x8*)(lds + PG8_SA(b, h) + aoff + m * 2048 + k * 1024); } while (0)
; #define PG8_LDB(dst, b, h) do { _Pragma("unroll") for (int n = 0; n < 2; ++n) _Pragma("unroll") for (int k = 0; k < 2; ++k) dst[n][k] = *(const PG8_LAS bf16x8*)(lds + PG8_SB(b, h) + boff + n * 2048 + k * 1024); } while (0)
; #define PG8_MMA(ai, bj, At, Bt) do { __builtin_amdgcn_s_setprio(1); _Pragma("unroll") for (int m = 0; m < 4; ++m) _Pragma("unroll") for (int n = 0; n < 2; ++n) _Pragma("unroll") for (int k = 0; k < 2; ++k) \
;         acc[ai][bj][m][n] = __builtin_amdgcn_mfma_f32_16x16x32_bf16(Bt[n][k], At[m][k], acc[ai][bj][m][n], 0, 0, 0); __builtin_amdgcn_s_setprio(0); } while (0)
; #define PG8_WAIT_V(n) asm volatile("s_waitcnt vmcnt(" #n ")" ::: "memory")
; #define PG8_WAIT_L(n) asm volatile("s_waitcnt lgkmcnt(" #n ")" ::: "memory")
; template <class Epi, class Sched, bool ALIGN_EPI = false, bool SP2 = false>
; __device__ __forceinline__ void gemm_phase(PG8_LAS unsigned char* lds, const Gemm g, const Sched& S, const Epi& E, const int wv) {
;     ...
;             const bool last = (t == nt - 2);
;             const char* a1 = cA + (size_t)(t + 1) * kstep;
;             const char* a2 = last ? nA : cA + (size_t)(t + 2) * kstep; const char* b2 = last ? nB : cB + (size_t)(t + 2) * kstep;
;             const char* a3 = a2 + kstep; const char* b3 = b2 + kstep;
;             if (last && has_next) S.a_ready(nxt);
;             if constexpr (SP2) {
;             PG8_LDB(B0, 0, 0); PG8_LDB(B1, 0, 1); PG8_SCHED; PG8_LDA(At, 0, 0); PG8_STAGE(PG8_SA(1, 1), a1 + hstepA, voffA);
;             PG8_WAIT_V(8); PG8_WAIT_L(0); PG8_BAR; PG8_MMA(0, 0, At, B0); PG8_MMA(0, 1, At, B1); PG8_BAR; PG8_SCHED;
;             PG8_LDA(At, 0, 1); PG8_STAGE(PG8_SB(0, 0), b2, voffB); PG8_STAGE(PG8_SB(0, 1), b2 + hstepB, voffB); PG8_STAGE(PG8_SA(0, 0), a2, voffA);
;             PG8_WAIT_V(8); PG8_WAIT_L(0); PG8_BAR; PG8_MMA(1, 0, At, B0); PG8_MMA(1, 1, At, B1); PG8_BAR; PG8_SCHED;
.Lsp_skip_1:
.LBB0_336:
	s_add_i32 s40, s14, 2
	s_add_u32 s41, s12, 0xfff80080
	s_addc_u32 s15, s13, -1
	s_cmp_eq_u32 s62, s14
	s_cselect_b32 s15, s93, s15
	s_cselect_b32 s14, s92, s41
	s_cselect_b32 s45, s25, s17
	s_cselect_b32 s44, s24, s11
	ds_read_b128 v[26:29], v171
	ds_read_b128 v[30:33], v171 offset:1024
	ds_read_b128 v[42:45], v171 offset:2048
	ds_read_b128 v[46:49], v171 offset:3072
	ds_read_b128 v[146:149], v227
	ds_read_b128 v[150:153], v227 offset:1024
	ds_read_b128 v[154:157], v227 offset:2048
	ds_read_b128 v[158:161], v227 offset:3072
	s_add_i32 m0, s55, 0xc000
	ds_read_b128 v[172:175], v199
	ds_read_b128 v[176:179], v199 offset:1024
	ds_read_b128 v[180:183], v199 offset:2048
	ds_read_b128 v[200:203], v199 offset:3072
	ds_read_b128 v[204:207], v199 offset:4096
	ds_read_b128 v[208:211], v199 offset:5120
	ds_read_b128 v[212:215], v199 offset:6144
	ds_read_b128 v[216:219], v199 offset:7168
	global_load_lds_dwordx4 v168, s[12:13]
	s_add_i32 m0, s55, 0xe000
	s_nop 0
	global_load_lds_dwordx4 v170, s[12:13]
	s_waitcnt vmcnt(8) lgkmcnt(0)
	s_barrier
	v_mfma_f32_16x16x32_bf16 v[138:141], v[26:29], v[172:175], v[138:141]
	v_mfma_f32_16x16x32_bf16 v[142:145], v[42:45], v[172:175], v[142:145]
	v_mfma_f32_16x16x32_bf16 v[126:129], v[26:29], v[180:183], v[126:129]
	v_mfma_f32_16x16x32_bf16 v[122:125], v[42:45], v[180:183], v[122:125]
	v_mfma_f32_16x16x32_bf16 v[110:113], v[26:29], v[204:207], v[110:113]
	v_mfma_f32_16x16x32_bf16 v[106:109], v[42:45], v[204:207], v[106:109]
	v_mfma_f32_16x16x32_bf16 v[94:97], v[26:29], v[212:215], v[94:97]
	v_mfma_f32_16x16x32_bf16 v[90:93], v[42:45], v[212:215], v[90:93]
	v_mfma_f32_16x16x32_bf16 v[138:141], v[30:33], v[176:179], v[138:141]
	v_mfma_f32_16x16x32_bf16 v[142:145], v[46:49], v[176:179], v[142:145]
	v_mfma_f32_16x16x32_bf16 v[126:129], v[30:33], v[200:203], v[126:129]
	v_mfma_f32_16x16x32_bf16 v[122:125], v[46:49], v[200:203], v[122:125]
	v_mfma_f32_16x16x32_bf16 v[110:113], v[30:33], v[208:211], v[110:113]
	v_mfma_f32_16x16x32_bf16 v[106:109], v[46:49], v[208:211], v[106:109]
	v_mfma_f32_16x16x32_bf16 v[94:97], v[30:33], v[216:219], v[94:97]
	v_mfma_f32_16x16x32_bf16 v[90:93], v[46:49], v[216:219], v[90:93]
	v_mfma_f32_16x16x32_bf16 v[134:137], v[146:149], v[172:175], v[134:137]
	v_mfma_f32_16x16x32_bf16 v[130:133], v[154:157], v[172:175], v[130:133]
	v_mfma_f32_16x16x32_bf16 v[118:121], v[146:149], v[180:183], v[118:121]
	v_mfma_f32_16x16x32_bf16 v[114:117], v[154:157], v[180:183], v[114:117]
	v_mfma_f32_16x16x32_bf16 v[102:105], v[146:149], v[204:207], v[102:105]
	v_mfma_f32_16x16x32_bf16 v[98:101], v[154:157], v[204:207], v[98:101]
	v_mfma_f32_16x16x32_bf16 v[86:89], v[146:149], v[212:215], v[86:89]
	v_mfma_f32_16x16x32_bf16 v[82:85], v[154:157], v[212:215], v[82:85]
	v_mfma_f32_16x16x32_bf16 v[134:137], v[150:153], v[176:179], v[134:137]
	v_mfma_f32_16x16x32_bf16 v[130:133], v[158:161], v[176:179], v[130:133]
	v_mfma_f32_16x16x32_bf16 v[118:121], v[150:153], v[200:203], v[118:121]
	v_mfma_f32_16x16x32_bf16 v[114:117], v[158:161], v[200:203], v[114:117]
	v_mfma_f32_16x16x32_bf16 v[102:105], v[150:153], v[208:211], v[102:105]
	v_mfma_f32_16x16x32_bf16 v[98:101], v[158:161], v[208:211], v[98:101]
	v_mfma_f32_16x16x32_bf16 v[86:89], v[150:153], v[216:219], v[86:89]
	v_mfma_f32_16x16x32_bf16 v[82:85], v[158:161], v[216:219], v[82:85]
	s_barrier
	s_add_i32 s65, s54, 0x10000
	v_lshl_add_u64 v[184:185], s[44:45], 0, v[0:1]
	s_mov_b32 m0, s65
	ds_read_b128 v[172:175], v199 offset:16384
	ds_read_b128 v[176:179], v199 offset:17408
	ds_read_b128 v[180:183], v199 offset:18432
	ds_read_b128 v[200:203], v199 offset:19456
	ds_read_b128 v[204:207], v199 offset:20480
	ds_read_b128 v[208:211], v199 offset:21504
	ds_read_b128 v[212:215], v199 offset:22528
	ds_read_b128 v[216:219], v199 offset:23552
	global_load_lds_dwordx4 v[184:185], off
	s_add_i32 m0, s65, 0x2000
	v_lshl_add_u64 v[194:195], s[44:45], 0, v[162:163]
	s_add_u32 s44, s44, s28
	s_addc_u32 s45, s45, s29
	s_add_i32 s41, s54, 0x14000
	global_load_lds_dwordx4 v[194:195], off
	s_mov_b32 m0, s41
	global_load_lds_dwordx4 v0, s[44:45]
	s_add_i32 m0, s41, 0x2000
	global_load_lds_dwordx4 v162, s[44:45]
	s_mov_b32 m0, s55
	global_load_lds_dwordx4 v166, s[14:15]
	s_mov_b32 m0, s56
	s_nop 0
	global_load_lds_dwordx4 v164, s[14:15]
	s_waitcnt vmcnt(8) lgkmcnt(0)
	s_barrier
	v_mfma_f32_16x16x32_bf16 v[78:81], v[26:29], v[172:175], v[78:81]
	v_mfma_f32_16x16x32_bf16 v[74:77], v[42:45], v[172:175], v[74:77]
	v_mfma_f32_16x16x32_bf16 v[62:65], v[26:29], v[180:183], v[62:65]
	v_mfma_f32_16x16x32_bf16 v[58:61], v[42:45], v[180:183], v[58:61]
	v_mfma_f32_16x16x32_bf16 v[38:41], v[26:29], v[204:207], v[38:41]
	v_mfma_f32_16x16x32_bf16 v[34:37], v[42:45], v[204:207], v[34:37]
	v_mfma_f32_16x16x32_bf16 v[14:17], v[26:29], v[212:215], v[14:17]
	v_mfma_f32_16x16x32_bf16 v[10:13], v[42:45], v[212:215], v[10:13]
	v_mfma_f32_16x16x32_bf16 v[78:81], v[30:33], v[176:179], v[78:81]
	v_mfma_f32_16x16x32_bf16 v[74:77], v[46:49], v[176:179], v[74:77]
	v_mfma_f32_16x16x32_bf16 v[62:65], v[30:33], v[200:203], v[62:65]
	v_mfma_f32_16x16x32_bf16 v[58:61], v[46:49], v[200:203], v[58:61]
	v_mfma_f32_16x16x32_bf16 v[38:41], v[30:33], v[208:211], v[38:41]
	v_mfma_f32_16x16x32_bf16 v[34:37], v[46:49], v[208:211], v[34:37]
	v_mfma_f32_16x16x32_bf16 v[14:17], v[30:33], v[216:219], v[14:17]
	v_mfma_f32_16x16x32_bf16 v[10:13], v[46:49], v[216:219], v[10:13]
	v_mfma_f32_16x16x32_bf16 v[22:25], v[146:149], v[204:207], v[22:25]
	v_mfma_f32_16x16x32_bf16 v[18:21], v[154:157], v[204:207], v[18:21]
	v_mfma_f32_16x16x32_bf16 v[6:9], v[146:149], v[212:215], v[6:9]
	v_mfma_f32_16x16x32_bf16 v[2:5], v[154:157], v[212:215], v[2:5]
	v_mfma_f32_16x16x32_bf16 v[26:29], v[146:149], v[172:175], v[70:73]
	v_mfma_f32_16x16x32_bf16 v[30:33], v[154:157], v[172:175], v[66:69]
	v_mfma_f32_16x16x32_bf16 v[42:45], v[146:149], v[180:183], v[54:57]
	v_mfma_f32_16x16x32_bf16 v[46:49], v[154:157], v[180:183], v[50:53]
	v_mfma_f32_16x16x32_bf16 v[22:25], v[150:153], v[208:211], v[22:25]
	v_mfma_f32_16x16x32_bf16 v[18:21], v[158:161], v[208:211], v[18:21]
	v_mfma_f32_16x16x32_bf16 v[6:9], v[150:153], v[216:219], v[6:9]
	v_mfma_f32_16x16x32_bf16 v[2:5], v[158:161], v[216:219], v[2:5]
	v_mfma_f32_16x16x32_bf16 v[26:29], v[150:153], v[176:179], v[26:29]
	v_mfma_f32_16x16x32_bf16 v[30:33], v[158:161], v[176:179], v[30:33]
	v_mfma_f32_16x16x32_bf16 v[42:45], v[150:153], v[200:203], v[42:45]
	v_mfma_f32_16x16x32_bf16 v[46:49], v[158:161], v[200:203], v[46:49]
	s_barrier
; #define PG8_STAGE(bufoff, gbase, voff) do { _Pragma("unroll") for (int _i = 0; _i < 2; ++_i) \
;         __builtin_amdgcn_global_load_lds((const unsigned*)((const char*)(gbase) + (voff)[_i]), (PG8_LAS unsigned*)(lds + (bufoff) + ldsw + _i * 8192), 16, 0, 0); } while (0)
; #define PG8_LDA(dst, b, h) do { _Pragma("unroll") for (int m = 0; m < 4; ++m) _Pragma("unroll") for (int k = 0; k < 2; ++k) dst[m][k] = *(const PG8_LAS bf16x8*)(lds + PG8_SA(b, h) + aoff + m * 2048 + k * 1024); } while (0)
; #define PG8_LDB(dst, b, h) do { _Pragma("unroll") for (int n = 0; n < 2; ++n) _Pragma("unroll") for (int k = 0; k < 2; ++k) dst[n][k] = *(const PG8_LAS bf16x8*)(lds + PG8_SB(b, h) + boff + n * 2048 + k * 1024); } while (0)
; #define PG8_MMA(ai, bj, At, Bt) do { __builtin_amdgcn_s_setprio(1); _Pragma("unroll") for (int m = 0; m < 4; ++m) _Pragma("unroll") for (int n = 0; n < 2; ++n) _Pragma("unroll") for (int k = 0; k < 2; ++k) \
;         acc[ai][bj][m][n] = __builtin_amdgcn_mfma_f32_16x16x32_bf16(Bt[n][k], At[m][k], acc[ai][bj][m][n], 0, 0, 0); __builtin_amdgcn_s_setprio(0); } while (0)
; #define PG8_WAIT_V(n) asm volatile("s_waitcnt vmcnt(" #n ")" ::: "memory")
; #define PG8_WAIT_L(n) asm volatile("s_waitcnt lgkmcnt(" #n ")" ::: "memory")
; #define PG8_BAR __builtin_amdgcn_s_barrier()
; #define PG8_SCHED __builtin_amdgcn_sched_barrier(0)
; template <class Epi, class Sched, bool ALIGN_EPI = false, bool SP2 = false>
; __device__ __forceinline__ void gemm_phase(PG8_LAS unsigned char* lds, const Gemm g, const Sched& S, const Epi& E, const int wv) {
;     ...
;             PG8_LDB(B0, 1, 0); PG8_LDB(B1, 1, 1); PG8_SCHED; PG8_LDA(At, 1, 0); PG8_STAGE(PG8_SA(0, 1), a2 + hstepA, voffA);
;             PG8_WAIT_V(8); PG8_WAIT_L(0); PG8_BAR; PG8_MMA(0, 0, At, B0); PG8_MMA(0, 1, At, B1); PG8_BAR; PG8_SCHED;
;             PG8_LDA(At, 1, 1); PG8_STAGE(PG8_SB(1, 0), b3, voffB); PG8_STAGE(PG8_SB(1, 1), b3 + hstepB, voffB); PG8_STAGE(PG8_SA(1, 0), a3, voffA);
;             PG8_WAIT_V(8); PG8_WAIT_L(0); PG8_BAR; PG8_MMA(1, 0, At, B0); PG8_MMA(1, 1, At, B1); PG8_BAR; PG8_SCHED;
	ds_read_b128 v[50:53], v244
	ds_read_b128 v[54:57], v244 offset:1024
	ds_read_b128 v[66:69], v244 offset:2048
	ds_read_b128 v[70:73], v244 offset:3072
	ds_read_b128 v[146:149], v245
	ds_read_b128 v[150:153], v245 offset:1024
	ds_read_b128 v[154:157], v245 offset:2048
	ds_read_b128 v[158:161], v245 offset:3072
	s_mov_b32 m0, s57
	ds_read_b128 v[172:175], v199 offset:32768
	ds_read_b128 v[176:179], v199 offset:33792
	ds_read_b128 v[180:183], v199 offset:34816
	ds_read_b128 v[200:203], v199 offset:35840
	ds_read_b128 v[204:207], v199 offset:36864
	ds_read_b128 v[208:211], v199 offset:37888
	ds_read_b128 v[212:215], v199 offset:38912
	ds_read_b128 v[216:219], v199 offset:39936
	global_load_lds_dwordx4 v246, s[14:15]
	s_mov_b32 m0, s58
	s_nop 0
	global_load_lds_dwordx4 v247, s[14:15]
	s_waitcnt vmcnt(8) lgkmcnt(0)
	s_barrier
	v_mfma_f32_16x16x32_bf16 v[138:141], v[50:53], v[172:175], v[138:141]
	v_mfma_f32_16x16x32_bf16 v[142:145], v[66:69], v[172:175], v[142:145]
	v_mfma_f32_16x16x32_bf16 v[126:129], v[50:53], v[180:183], v[126:129]
	v_mfma_f32_16x16x32_bf16 v[122:125], v[66:69], v[180:183], v[122:125]
	v_mfma_f32_16x16x32_bf16 v[110:113], v[50:53], v[204:207], v[110:113]
	v_mfma_f32_16x16x32_bf16 v[106:109], v[66:69], v[204:207], v[106:109]
	v_mfma_f32_16x16x32_bf16 v[94:97], v[50:53], v[212:215], v[94:97]
	v_mfma_f32_16x16x32_bf16 v[90:93], v[66:69], v[212:215], v[90:93]
	v_mfma_f32_16x16x32_bf16 v[138:141], v[54:57], v[176:179], v[138:141]
	v_mfma_f32_16x16x32_bf16 v[142:145], v[70:73], v[176:179], v[142:145]
	v_mfma_f32_16x16x32_bf16 v[126:129], v[54:57], v[200:203], v[126:129]
	v_mfma_f32_16x16x32_bf16 v[122:125], v[70:73], v[200:203], v[122:125]
	v_mfma_f32_16x16x32_bf16 v[110:113], v[54:57], v[208:211], v[110:113]
	v_mfma_f32_16x16x32_bf16 v[106:109], v[70:73], v[208:211], v[106:109]
	v_mfma_f32_16x16x32_bf16 v[94:97], v[54:57], v[216:219], v[94:97]
	v_mfma_f32_16x16x32_bf16 v[90:93], v[70:73], v[216:219], v[90:93]
	v_mfma_f32_16x16x32_bf16 v[134:137], v[146:149], v[172:175], v[134:137]
	v_mfma_f32_16x16x32_bf16 v[130:133], v[154:157], v[172:175], v[130:133]
	v_mfma_f32_16x16x32_bf16 v[118:121], v[146:149], v[180:183], v[118:121]
	v_mfma_f32_16x16x32_bf16 v[114:117], v[154:157], v[180:183], v[114:117]
	v_mfma_f32_16x16x32_bf16 v[102:105], v[146:149], v[204:207], v[102:105]
	v_mfma_f32_16x16x32_bf16 v[98:101], v[154:157], v[204:207], v[98:101]
	v_mfma_f32_16x16x32_bf16 v[86:89], v[146:149], v[212:215], v[86:89]
	v_mfma_f32_16x16x32_bf16 v[82:85], v[154:157], v[212:215], v[82:85]
	v_mfma_f32_16x16x32_bf16 v[134:137], v[150:153], v[176:179], v[134:137]
	v_mfma_f32_16x16x32_bf16 v[130:133], v[158:161], v[176:179], v[130:133]
	v_mfma_f32_16x16x32_bf16 v[118:121], v[150:153], v[200:203], v[118:121]
	v_mfma_f32_16x16x32_bf16 v[114:117], v[158:161], v[200:203], v[114:117]
	v_mfma_f32_16x16x32_bf16 v[102:105], v[150:153], v[208:211], v[102:105]
	v_mfma_f32_16x16x32_bf16 v[98:101], v[158:161], v[208:211], v[98:101]
	v_mfma_f32_16x16x32_bf16 v[86:89], v[150:153], v[216:219], v[86:89]
	v_mfma_f32_16x16x32_bf16 v[82:85], v[158:161], v[216:219], v[82:85]
	s_barrier
	s_add_i32 m0, s54, 0x17f80
	ds_read_b128 v[172:175], v199 offset:49152
	ds_read_b128 v[176:179], v199 offset:50176
	ds_read_b128 v[180:183], v199 offset:51200
	ds_read_b128 v[200:203], v199 offset:52224
	ds_read_b128 v[204:207], v199 offset:53248
	ds_read_b128 v[208:211], v199 offset:54272
	ds_read_b128 v[212:215], v199 offset:55296
	ds_read_b128 v[216:219], v199 offset:56320
	global_load_lds_dwordx4 v[184:185], off offset:128
	s_add_i32 m0, s54, 0x19f80
	global_load_lds_dwordx4 v[194:195], off offset:128
	s_add_i32 m0, s54, 0x1bf80
	s_nop 0
	global_load_lds_dwordx4 v0, s[44:45] offset:128
	s_add_i32 m0, s54, 0x1df80
	s_nop 0
	global_load_lds_dwordx4 v162, s[44:45] offset:128
	s_add_i32 m0, s60, 0xffffff80
	s_nop 0
	global_load_lds_dwordx4 v166, s[14:15] offset:128
	s_add_i32 m0, s61, 0xffffff80
	s_nop 0
	global_load_lds_dwordx4 v164, s[14:15] offset:128
	s_waitcnt vmcnt(8) lgkmcnt(0)
	s_barrier
	v_mfma_f32_16x16x32_bf16 v[78:81], v[50:53], v[172:175], v[78:81]
	v_mfma_f32_16x16x32_bf16 v[74:77], v[66:69], v[172:175], v[74:77]
	v_mfma_f32_16x16x32_bf16 v[62:65], v[50:53], v[180:183], v[62:65]
	v_mfma_f32_16x16x32_bf16 v[58:61], v[66:69], v[180:183], v[58:61]
	v_mfma_f32_16x16x32_bf16 v[38:41], v[50:53], v[204:207], v[38:41]
	v_mfma_f32_16x16x32_bf16 v[34:37], v[66:69], v[204:207], v[34:37]
	v_mfma_f32_16x16x32_bf16 v[14:17], v[50:53], v[212:215], v[14:17]
	v_mfma_f32_16x16x32_bf16 v[10:13], v[66:69], v[212:215], v[10:13]
	v_mfma_f32_16x16x32_bf16 v[78:81], v[54:57], v[176:179], v[78:81]
	v_mfma_f32_16x16x32_bf16 v[74:77], v[70:73], v[176:179], v[74:77]
	v_mfma_f32_16x16x32_bf16 v[62:65], v[54:57], v[200:203], v[62:65]
	v_mfma_f32_16x16x32_bf16 v[58:61], v[70:73], v[200:203], v[58:61]
	v_mfma_f32_16x16x32_bf16 v[38:41], v[54:57], v[208:211], v[38:41]
	v_mfma_f32_16x16x32_bf16 v[34:37], v[70:73], v[208:211], v[34:37]
	v_mfma_f32_16x16x32_bf16 v[14:17], v[54:57], v[216:219], v[14:17]
	v_mfma_f32_16x16x32_bf16 v[10:13], v[70:73], v[216:219], v[10:13]
	v_mfma_f32_16x16x32_bf16 v[26:29], v[146:149], v[172:175], v[26:29]
	v_mfma_f32_16x16x32_bf16 v[70:73], v[150:153], v[176:179], v[26:29]
	v_mfma_f32_16x16x32_bf16 v[26:29], v[154:157], v[172:175], v[30:33]
	v_mfma_f32_16x16x32_bf16 v[66:69], v[158:161], v[176:179], v[26:29]
	v_mfma_f32_16x16x32_bf16 v[26:29], v[146:149], v[180:183], v[42:45]
	v_mfma_f32_16x16x32_bf16 v[54:57], v[150:153], v[200:203], v[26:29]
	v_mfma_f32_16x16x32_bf16 v[26:29], v[154:157], v[180:183], v[46:49]
	v_mfma_f32_16x16x32_bf16 v[22:25], v[146:149], v[204:207], v[22:25]
	v_mfma_f32_16x16x32_bf16 v[18:21], v[154:157], v[204:207], v[18:21]
	v_mfma_f32_16x16x32_bf16 v[6:9], v[146:149], v[212:215], v[6:9]
	v_mfma_f32_16x16x32_bf16 v[2:5], v[154:157], v[212:215], v[2:5]
	v_mfma_f32_16x16x32_bf16 v[50:53], v[158:161], v[200:203], v[26:29]
	v_mfma_f32_16x16x32_bf16 v[22:25], v[150:153], v[208:211], v[22:25]
	v_mfma_f32_16x16x32_bf16 v[18:21], v[158:161], v[208:211], v[18:21]
	v_mfma_f32_16x16x32_bf16 v[6:9], v[150:153], v[216:219], v[6:9]
	v_mfma_f32_16x16x32_bf16 v[2:5], v[158:161], v[216:219], v[2:5]
	s_barrier
	s_add_u32 s12, s12, 0x100
	s_addc_u32 s13, s13, 0
	s_add_u32 s11, s11, 0x100
	s_addc_u32 s17, s17, 0
	s_cmp_ge_i32 s40, s59
	s_mov_b32 s14, s40
	s_cbranch_scc0 .LBB0_336
	s_setprio 0

; #define PG8_STAGE(bufoff, gbase, voff) do { _Pragma("unroll") for (int _i = 0; _i < 2; ++_i) \
;         __builtin_amdgcn_global_load_lds((const unsigned*)((const char*)(gbase) + (voff)[_i]), (PG8_LAS unsigned*)(lds + (bufoff) + ldsw + _i * 8192), 16, 0, 0); } while (0)
; #define PG8_LDA(dst, b, h) do { _Pragma("unroll") for (int m = 0; m < 4; ++m) _Pragma("unroll") for (int k = 0; k < 2; ++k) dst[m][k] = *(const PG8_LAS bf16x8*)(lds + PG8_SA(b, h) + aoff + m * 2048 + k * 1024); } while (0)
; #define PG8_LDB(dst, b, h) do { _Pragma("unroll") for (int n = 0; n < 2; ++n) _Pragma("unroll") for (int k = 0; k < 2; ++k) dst[n][k] = *(const PG8_LAS bf16x8*)(lds + PG8_SB(b, h) + boff + n * 2048 + k * 1024); } while (0)
; #define PG8_MMA(ai, bj, At, Bt) do { __builtin_amdgcn_s_setprio(1); _Pragma("unroll") for (int m = 0; m < 4; ++m) _Pragma("unroll") for (int n = 0; n < 2; ++n) _Pragma("unroll") for (int k = 0; k < 2; ++k) \
;         acc[ai][bj][m][n] = __builtin_amdgcn_mfma_f32_16x16x32_bf16(Bt[n][k], At[m][k], acc[ai][bj][m][n], 0, 0, 0); __builtin_amdgcn_s_setprio(0); } while (0)
; #define PG8_WAIT_V(n) asm volatile("s_waitcnt vmcnt(" #n ")" ::: "memory")
; template <class Epi, class Sched, bool ALIGN_EPI = false, bool SP2 = false>
; __device__ __forceinline__ void gemm_phase(PG8_LAS unsigned char* lds, const Gemm g, const Sched& S, const Epi& E, const int wv) {
;     ...
;             const bool last = (t == nt - 2);
;             const char* a1 = cA + (size_t)(t + 1) * kstep;
;             const char* a2 = last ? nA : cA + (size_t)(t + 2) * kstep; const char* b2 = last ? nB : cB + (size_t)(t + 2) * kstep;
;             const char* a3 = a2 + kstep; const char* b3 = b2 + kstep;
;             if (last && has_next) S.a_ready(nxt);
;             if constexpr (SP2) {
;             PG8_LDB(B0, 0, 0); PG8_LDB(B1, 0, 1); PG8_SCHED; PG8_LDA(At, 0, 0); PG8_STAGE(PG8_SA(1, 1), a1 + hstepA, voffA);
;             PG8_WAIT_V(8); PG8_WAIT_L(0); PG8_BAR; PG8_MMA(0, 0, At, B0); PG8_MMA(0, 1, At, B1); PG8_BAR; PG8_SCHED;
;     ...
; #pragma unroll
;         for (int a = 0; a < 2; ++a)
; #pragma unroll
;             for (int b = 0; b < 2; ++b)
; #pragma unroll
;                 for (int m = 0; m < 4; ++m)
; #pragma unroll
;                     for (int n = 0; n < 2; ++n) acc[a][b][m][n] = (f32x4){0.f, 0.f, 0.f, 0.f};
;         cur = nxt; cA = nA; cB = nB; ++ui;
.LBB0_698:
	s_and_b64 s[44:45], s[44:45], exec
	s_cselect_b32 s31, s15, s55
	s_cselect_b32 s71, s14, s54
	s_add_u32 s44, s54, 0x80080
	s_addc_u32 s45, s55, 0
	s_add_u32 s56, s56, 0x100
	v_mov_b32_e32 v2, 0
	s_addc_u32 s57, s57, 0
	s_mov_b32 s54, 0
	v_mov_b32_e32 v3, v2
	v_pk_mov_b32 v[4:5], v[2:3], v[2:3]
	v_pk_mov_b32 v[6:7], v[2:3], v[2:3]
	v_pk_mov_b32 v[8:9], v[2:3], v[2:3]
	v_pk_mov_b32 v[18:19], v[2:3], v[2:3]
	v_pk_mov_b32 v[20:21], v[2:3], v[2:3]
	v_pk_mov_b32 v[22:23], v[2:3], v[2:3]
	v_pk_mov_b32 v[24:25], v[2:3], v[2:3]
	v_pk_mov_b32 v[34:35], v[2:3], v[2:3]
	v_pk_mov_b32 v[36:37], v[2:3], v[2:3]
	v_pk_mov_b32 v[38:39], v[2:3], v[2:3]
	v_pk_mov_b32 v[40:41], v[2:3], v[2:3]
	v_pk_mov_b32 v[50:51], v[2:3], v[2:3]
	v_pk_mov_b32 v[52:53], v[2:3], v[2:3]
	v_pk_mov_b32 v[54:55], v[2:3], v[2:3]
	v_pk_mov_b32 v[56:57], v[2:3], v[2:3]
	v_pk_mov_b32 v[10:11], v[2:3], v[2:3]
	v_pk_mov_b32 v[12:13], v[2:3], v[2:3]
	v_pk_mov_b32 v[14:15], v[2:3], v[2:3]
	v_pk_mov_b32 v[16:17], v[2:3], v[2:3]
	v_pk_mov_b32 v[26:27], v[2:3], v[2:3]
	v_pk_mov_b32 v[28:29], v[2:3], v[2:3]
	v_pk_mov_b32 v[30:31], v[2:3], v[2:3]
	v_pk_mov_b32 v[32:33], v[2:3], v[2:3]
	v_pk_mov_b32 v[42:43], v[2:3], v[2:3]
	v_pk_mov_b32 v[44:45], v[2:3], v[2:3]
	v_pk_mov_b32 v[46:47], v[2:3], v[2:3]
	v_pk_mov_b32 v[48:49], v[2:3], v[2:3]
	v_pk_mov_b32 v[58:59], v[2:3], v[2:3]
	v_pk_mov_b32 v[60:61], v[2:3], v[2:3]
	v_pk_mov_b32 v[62:63], v[2:3], v[2:3]
	v_pk_mov_b32 v[64:65], v[2:3], v[2:3]
	v_pk_mov_b32 v[66:67], v[2:3], v[2:3]
	v_pk_mov_b32 v[68:69], v[2:3], v[2:3]
	v_pk_mov_b32 v[70:71], v[2:3], v[2:3]
	v_pk_mov_b32 v[72:73], v[2:3], v[2:3]
	v_pk_mov_b32 v[82:83], v[2:3], v[2:3]
	v_pk_mov_b32 v[84:85], v[2:3], v[2:3]
	v_pk_mov_b32 v[86:87], v[2:3], v[2:3]
	v_pk_mov_b32 v[88:89], v[2:3], v[2:3]
	v_pk_mov_b32 v[98:99], v[2:3], v[2:3]
	v_pk_mov_b32 v[100:101], v[2:3], v[2:3]
	v_pk_mov_b32 v[102:103], v[2:3], v[2:3]
	v_pk_mov_b32 v[104:105], v[2:3], v[2:3]
	v_pk_mov_b32 v[118:119], v[2:3], v[2:3]
	v_pk_mov_b32 v[120:121], v[2:3], v[2:3]
	v_pk_mov_b32 v[122:123], v[2:3], v[2:3]
	v_pk_mov_b32 v[124:125], v[2:3], v[2:3]
	v_pk_mov_b32 v[74:75], v[2:3], v[2:3]
	v_pk_mov_b32 v[76:77], v[2:3], v[2:3]
	v_pk_mov_b32 v[78:79], v[2:3], v[2:3]
	v_pk_mov_b32 v[80:81], v[2:3], v[2:3]
	v_pk_mov_b32 v[90:91], v[2:3], v[2:3]
	v_pk_mov_b32 v[92:93], v[2:3], v[2:3]
	v_pk_mov_b32 v[94:95], v[2:3], v[2:3]
	v_pk_mov_b32 v[96:97], v[2:3], v[2:3]
	v_pk_mov_b32 v[106:107], v[2:3], v[2:3]
	v_pk_mov_b32 v[108:109], v[2:3], v[2:3]
	v_pk_mov_b32 v[110:111], v[2:3], v[2:3]
	v_pk_mov_b32 v[112:113], v[2:3], v[2:3]
	v_pk_mov_b32 v[130:131], v[2:3], v[2:3]
	v_pk_mov_b32 v[132:133], v[2:3], v[2:3]
	v_pk_mov_b32 v[134:135], v[2:3], v[2:3]
	v_pk_mov_b32 v[136:137], v[2:3], v[2:3]
	v_add_u32_e32 v190, 0x10000, v230
	v_add_u32_e32 v191, 0x14000, v230
	v_add_u32_e32 v192, 0x18000, v230
	v_add_u32_e32 v193, 0x1c000, v230
	v_add_u32_e32 v115, 0x80000, v194
	v_add_u32_e32 v201, 0x80000, v196
	s_cmp_eq_u64 s[48:49], 0
	s_cbranch_scc0 .Lsp_skip_2
	s_setprio 1
.Lsp_skip_2:
.LBB0_699:
	s_add_i32 s72, s54, 2
	s_add_u32 s73, s44, 0xfff80080
	s_addc_u32 s55, s45, -1
	s_cmp_eq_u32 s66, s54
	s_cselect_b32 s55, s31, s55
	s_cselect_b32 s54, s71, s73
	s_cselect_b32 s75, s13, s57
	s_cselect_b32 s74, s12, s56
	ds_read_b128 v[126:129], v190
	ds_read_b128 v[138:141], v190 offset:1024
	ds_read_b128 v[142:145], v190 offset:2048
	ds_read_b128 v[146:149], v190 offset:3072
	ds_read_b128 v[150:153], v191
	ds_read_b128 v[154:157], v191 offset:1024
	ds_read_b128 v[158:161], v191 offset:2048
	ds_read_b128 v[162:165], v191 offset:3072
	s_add_i32 m0, s59, 0xc000
	ds_read_b128 v[166:169], v235
	ds_read_b128 v[170:173], v235 offset:1024
	ds_read_b128 v[174:177], v235 offset:2048
	ds_read_b128 v[178:181], v235 offset:3072
	ds_read_b128 v[182:185], v235 offset:4096
	ds_read_b128 v[204:207], v235 offset:5120
	ds_read_b128 v[208:211], v235 offset:6144
	ds_read_b128 v[212:215], v235 offset:7168
	global_load_lds_dwordx4 v200, s[44:45]
	s_add_i32 m0, s59, 0xe000
	s_nop 0
	global_load_lds_dwordx4 v202, s[44:45]
	s_waitcnt vmcnt(8) lgkmcnt(0)
	s_barrier
	v_mfma_f32_16x16x32_bf16 v[134:137], v[126:129], v[166:169], v[134:137]
	v_mfma_f32_16x16x32_bf16 v[130:133], v[142:145], v[166:169], v[130:133]
	v_mfma_f32_16x16x32_bf16 v[110:113], v[126:129], v[174:177], v[110:113]
	v_mfma_f32_16x16x32_bf16 v[106:109], v[142:145], v[174:177], v[106:109]
	v_mfma_f32_16x16x32_bf16 v[94:97], v[126:129], v[182:185], v[94:97]
	v_mfma_f32_16x16x32_bf16 v[90:93], v[142:145], v[182:185], v[90:93]
	v_mfma_f32_16x16x32_bf16 v[78:81], v[126:129], v[208:211], v[78:81]
	v_mfma_f32_16x16x32_bf16 v[74:77], v[142:145], v[208:211], v[74:77]
	v_mfma_f32_16x16x32_bf16 v[134:137], v[138:141], v[170:173], v[134:137]
	v_mfma_f32_16x16x32_bf16 v[130:133], v[146:149], v[170:173], v[130:133]
	v_mfma_f32_16x16x32_bf16 v[110:113], v[138:141], v[178:181], v[110:113]
	v_mfma_f32_16x16x32_bf16 v[106:109], v[146:149], v[178:181], v[106:109]
	v_mfma_f32_16x16x32_bf16 v[94:97], v[138:141], v[204:207], v[94:97]
	v_mfma_f32_16x16x32_bf16 v[90:93], v[146:149], v[204:207], v[90:93]
	v_mfma_f32_16x16x32_bf16 v[78:81], v[138:141], v[212:215], v[78:81]
	v_mfma_f32_16x16x32_bf16 v[74:77], v[146:149], v[212:215], v[74:77]
	v_mfma_f32_16x16x32_bf16 v[122:125], v[150:153], v[166:169], v[122:125]
	v_mfma_f32_16x16x32_bf16 v[116:119], v[158:161], v[166:169], v[118:121]
	v_mfma_f32_16x16x32_bf16 v[102:105], v[150:153], v[174:177], v[102:105]
	v_mfma_f32_16x16x32_bf16 v[98:101], v[158:161], v[174:177], v[98:101]
	v_mfma_f32_16x16x32_bf16 v[86:89], v[150:153], v[182:185], v[86:89]
	v_mfma_f32_16x16x32_bf16 v[82:85], v[158:161], v[182:185], v[82:85]
	v_mfma_f32_16x16x32_bf16 v[70:73], v[150:153], v[208:211], v[70:73]
	v_mfma_f32_16x16x32_bf16 v[66:69], v[158:161], v[208:211], v[66:69]
	v_mfma_f32_16x16x32_bf16 v[122:125], v[154:157], v[170:173], v[122:125]
	v_mfma_f32_16x16x32_bf16 v[116:119], v[162:165], v[170:173], v[116:119]
	v_mfma_f32_16x16x32_bf16 v[102:105], v[154:157], v[178:181], v[102:105]
	v_mfma_f32_16x16x32_bf16 v[98:101], v[162:165], v[178:181], v[98:101]
	v_mfma_f32_16x16x32_bf16 v[86:89], v[154:157], v[204:207], v[86:89]
	v_mfma_f32_16x16x32_bf16 v[82:85], v[162:165], v[204:207], v[82:85]
	v_mfma_f32_16x16x32_bf16 v[70:73], v[154:157], v[212:215], v[70:73]
	v_mfma_f32_16x16x32_bf16 v[66:69], v[162:165], v[212:215], v[66:69]
	s_barrier
; #define PG8_STAGE(bufoff, gbase, voff) do { _Pragma("unroll") for (int _i = 0; _i < 2; ++_i) \
;         __builtin_amdgcn_global_load_lds((const unsigned*)((const char*)(gbase) + (voff)[_i]), (PG8_LAS unsigned*)(lds + (bufoff) + ldsw + _i * 8192), 16, 0, 0); } while (0)
; #define PG8_LDA(dst, b, h) do { _Pragma("unroll") for (int m = 0; m < 4; ++m) _Pragma("unroll") for (int k = 0; k < 2; ++k) dst[m][k] = *(const PG8_LAS bf16x8*)(lds + PG8_SA(b, h) + aoff + m * 2048 + k * 1024); } while (0)
; #define PG8_LDB(dst, b, h) do { _Pragma("unroll") for (int n = 0; n < 2; ++n) _Pragma("unroll") for (int k = 0; k < 2; ++k) dst[n][k] = *(const PG8_LAS bf16x8*)(lds + PG8_SB(b, h) + boff + n * 2048 + k * 1024); } while (0)
; #define PG8_MMA(ai, bj, At, Bt) do { __builtin_amdgcn_s_setprio(1); _Pragma("unroll") for (int m = 0; m < 4; ++m) _Pragma("unroll") for (int n = 0; n < 2; ++n) _Pragma("unroll") for (int k = 0; k < 2; ++k) \
;         acc[ai][bj][m][n] = __builtin_amdgcn_mfma_f32_16x16x32_bf16(Bt[n][k], At[m][k], acc[ai][bj][m][n], 0, 0, 0); __builtin_amdgcn_s_setprio(0); } while (0)
; #define PG8_WAIT_V(n) asm volatile("s_waitcnt vmcnt(" #n ")" ::: "memory")
; #define PG8_WAIT_L(n) asm volatile("s_waitcnt lgkmcnt(" #n ")" ::: "memory")
; #define PG8_BAR __builtin_amdgcn_s_barrier()
; #define PG8_SCHED __builtin_amdgcn_sched_barrier(0)
; template <class Epi, class Sched, bool ALIGN_EPI = false, bool SP2 = false>
; __device__ __forceinline__ void gemm_phase(PG8_LAS unsigned char* lds, const Gemm g, const Sched& S, const Epi& E, const int wv) {
;     ...
;             PG8_LDA(At, 0, 1); PG8_STAGE(PG8_SB(0, 0), b2, voffB); PG8_STAGE(PG8_SB(0, 1), b2 + hstepB, voffB); PG8_STAGE(PG8_SA(0, 0), a2, voffA);
;             PG8_WAIT_V(8); PG8_WAIT_L(0); PG8_BAR; PG8_MMA(1, 0, At, B0); PG8_MMA(1, 1, At, B1); PG8_BAR; PG8_SCHED;
;             PG8_LDB(B0, 1, 0); PG8_LDB(B1, 1, 1); PG8_SCHED; PG8_LDA(At, 1, 0); PG8_STAGE(PG8_SA(0, 1), a2 + hstepA, voffA);
;             PG8_WAIT_V(8); PG8_WAIT_L(0); PG8_BAR; PG8_MMA(0, 0, At, B0); PG8_MMA(0, 1, At, B1); PG8_BAR; PG8_SCHED;
	s_add_i32 s76, s53, 0x10000
	v_lshl_add_u64 v[216:217], s[74:75], 0, v[0:1]
	s_mov_b32 m0, s76
	ds_read_b128 v[166:169], v235 offset:16384
	ds_read_b128 v[170:173], v235 offset:17408
	ds_read_b128 v[174:177], v235 offset:18432
	ds_read_b128 v[178:181], v235 offset:19456
	ds_read_b128 v[182:185], v235 offset:20480
	ds_read_b128 v[204:207], v235 offset:21504
	ds_read_b128 v[208:211], v235 offset:22528
	ds_read_b128 v[212:215], v235 offset:23552
	global_load_lds_dwordx4 v[216:217], off
	s_add_i32 m0, s76, 0x2000
	v_lshl_add_u64 v[218:219], s[74:75], 0, v[198:199]
	s_add_u32 s74, s74, s34
	s_addc_u32 s75, s75, s35
	s_add_i32 s73, s53, 0x14000
	global_load_lds_dwordx4 v[218:219], off
	s_mov_b32 m0, s73
	global_load_lds_dwordx4 v0, s[74:75]
	s_add_i32 m0, s73, 0x2000
	global_load_lds_dwordx4 v198, s[74:75]
	s_mov_b32 m0, s59
	global_load_lds_dwordx4 v194, s[54:55]
	s_mov_b32 m0, s60
	s_nop 0
	global_load_lds_dwordx4 v196, s[54:55]
	s_waitcnt vmcnt(8) lgkmcnt(0)
	s_barrier
	v_mfma_f32_16x16x32_bf16 v[62:65], v[126:129], v[166:169], v[62:65]
	v_mfma_f32_16x16x32_bf16 v[58:61], v[142:145], v[166:169], v[58:61]
	v_mfma_f32_16x16x32_bf16 v[46:49], v[126:129], v[174:177], v[46:49]
	v_mfma_f32_16x16x32_bf16 v[42:45], v[142:145], v[174:177], v[42:45]
	v_mfma_f32_16x16x32_bf16 v[30:33], v[126:129], v[182:185], v[30:33]
	v_mfma_f32_16x16x32_bf16 v[26:29], v[142:145], v[182:185], v[26:29]
	v_mfma_f32_16x16x32_bf16 v[14:17], v[126:129], v[208:211], v[14:17]
	v_mfma_f32_16x16x32_bf16 v[10:13], v[142:145], v[208:211], v[10:13]
	v_mfma_f32_16x16x32_bf16 v[62:65], v[138:141], v[170:173], v[62:65]
	v_mfma_f32_16x16x32_bf16 v[58:61], v[146:149], v[170:173], v[58:61]
	v_mfma_f32_16x16x32_bf16 v[46:49], v[138:141], v[178:181], v[46:49]
	v_mfma_f32_16x16x32_bf16 v[42:45], v[146:149], v[178:181], v[42:45]
	v_mfma_f32_16x16x32_bf16 v[30:33], v[138:141], v[204:207], v[30:33]
	v_mfma_f32_16x16x32_bf16 v[26:29], v[146:149], v[204:207], v[26:29]
	v_mfma_f32_16x16x32_bf16 v[14:17], v[138:141], v[212:215], v[14:17]
	v_mfma_f32_16x16x32_bf16 v[10:13], v[146:149], v[212:215], v[10:13]
	v_mfma_f32_16x16x32_bf16 v[54:57], v[150:153], v[166:169], v[54:57]
	v_mfma_f32_16x16x32_bf16 v[50:53], v[158:161], v[166:169], v[50:53]
	v_mfma_f32_16x16x32_bf16 v[38:41], v[150:153], v[174:177], v[38:41]
	v_mfma_f32_16x16x32_bf16 v[34:37], v[158:161], v[174:177], v[34:37]
	v_mfma_f32_16x16x32_bf16 v[22:25], v[150:153], v[182:185], v[22:25]
	v_mfma_f32_16x16x32_bf16 v[18:21], v[158:161], v[182:185], v[18:21]
	v_mfma_f32_16x16x32_bf16 v[6:9], v[150:153], v[208:211], v[6:9]
	v_mfma_f32_16x16x32_bf16 v[2:5], v[158:161], v[208:211], v[2:5]
	v_mfma_f32_16x16x32_bf16 v[54:57], v[154:157], v[170:173], v[54:57]
	v_mfma_f32_16x16x32_bf16 v[50:53], v[162:165], v[170:173], v[50:53]
	v_mfma_f32_16x16x32_bf16 v[38:41], v[154:157], v[178:181], v[38:41]
	v_mfma_f32_16x16x32_bf16 v[34:37], v[162:165], v[178:181], v[34:37]
	v_mfma_f32_16x16x32_bf16 v[22:25], v[154:157], v[204:207], v[22:25]
	v_mfma_f32_16x16x32_bf16 v[18:21], v[162:165], v[204:207], v[18:21]
	v_mfma_f32_16x16x32_bf16 v[6:9], v[154:157], v[212:215], v[6:9]
	v_mfma_f32_16x16x32_bf16 v[2:5], v[162:165], v[212:215], v[2:5]
	s_barrier
	ds_read_b128 v[126:129], v192
	ds_read_b128 v[138:141], v192 offset:1024
	ds_read_b128 v[142:145], v192 offset:2048
	ds_read_b128 v[146:149], v192 offset:3072
	ds_read_b128 v[150:153], v193
	ds_read_b128 v[154:157], v193 offset:1024
	ds_read_b128 v[158:161], v193 offset:2048
	ds_read_b128 v[162:165], v193 offset:3072
	s_mov_b32 m0, s61
	ds_read_b128 v[166:169], v235 offset:32768
	ds_read_b128 v[170:173], v235 offset:33792
	ds_read_b128 v[174:177], v235 offset:34816
	ds_read_b128 v[178:181], v235 offset:35840
	ds_read_b128 v[182:185], v235 offset:36864
	ds_read_b128 v[204:207], v235 offset:37888
	ds_read_b128 v[208:211], v235 offset:38912
	ds_read_b128 v[212:215], v235 offset:39936
	global_load_lds_dwordx4 v115, s[54:55]
	s_mov_b32 m0, s62
	s_nop 0
	global_load_lds_dwordx4 v201, s[54:55]
	s_waitcnt vmcnt(8) lgkmcnt(0)
	s_barrier
; #define PG8_STAGE(bufoff, gbase, voff) do { _Pragma("unroll") for (int _i = 0; _i < 2; ++_i) \
;         __builtin_amdgcn_global_load_lds((const unsigned*)((const char*)(gbase) + (voff)[_i]), (PG8_LAS unsigned*)(lds + (bufoff) + ldsw + _i * 8192), 16, 0, 0); } while (0)
; #define PG8_LDA(dst, b, h) do { _Pragma("unroll") for (int m = 0; m < 4; ++m) _Pragma("unroll") for (int k = 0; k < 2; ++k) dst[m][k] = *(const PG8_LAS bf16x8*)(lds + PG8_SA(b, h) + aoff + m * 2048 + k * 1024); } while (0)
; #define PG8_MMA(ai, bj, At, Bt) do { __builtin_amdgcn_s_setprio(1); _Pragma("unroll") for (int m = 0; m < 4; ++m) _Pragma("unroll") for (int n = 0; n < 2; ++n) _Pragma("unroll") for (int k = 0; k < 2; ++k) \
;         acc[ai][bj][m][n] = __builtin_amdgcn_mfma_f32_16x16x32_bf16(Bt[n][k], At[m][k], acc[ai][bj][m][n], 0, 0, 0); __builtin_amdgcn_s_setprio(0); } while (0)
; #define PG8_WAIT_V(n) asm volatile("s_waitcnt vmcnt(" #n ")" ::: "memory")
; #define PG8_WAIT_L(n) asm volatile("s_waitcnt lgkmcnt(" #n ")" ::: "memory")
; #define PG8_BAR __builtin_amdgcn_s_barrier()
; #define PG8_SCHED __builtin_amdgcn_sched_barrier(0)
; template <class Epi, class Sched, bool ALIGN_EPI = false, bool SP2 = false>
; __device__ __forceinline__ void gemm_phase(PG8_LAS unsigned char* lds, const Gemm g, const Sched& S, const Epi& E, const int wv) {
;     ...
;             PG8_WAIT_V(8); PG8_WAIT_L(0); PG8_BAR; PG8_MMA(0, 0, At, B0); PG8_MMA(0, 1, At, B1); PG8_BAR; PG8_SCHED;
;             PG8_LDA(At, 1, 1); PG8_STAGE(PG8_SB(1, 0), b3, voffB); PG8_STAGE(PG8_SB(1, 1), b3 + hstepB, voffB); PG8_STAGE(PG8_SA(1, 0), a3, voffA);
;             PG8_WAIT_V(8); PG8_WAIT_L(0); PG8_BAR; PG8_MMA(1, 0, At, B0); PG8_MMA(1, 1, At, B1); PG8_BAR; PG8_SCHED;
	v_mfma_f32_16x16x32_bf16 v[134:137], v[126:129], v[166:169], v[134:137]
	v_mfma_f32_16x16x32_bf16 v[130:133], v[142:145], v[166:169], v[130:133]
	v_mfma_f32_16x16x32_bf16 v[110:113], v[126:129], v[174:177], v[110:113]
	v_mfma_f32_16x16x32_bf16 v[106:109], v[142:145], v[174:177], v[106:109]
	v_mfma_f32_16x16x32_bf16 v[94:97], v[126:129], v[182:185], v[94:97]
	v_mfma_f32_16x16x32_bf16 v[90:93], v[142:145], v[182:185], v[90:93]
	v_mfma_f32_16x16x32_bf16 v[78:81], v[126:129], v[208:211], v[78:81]
	v_mfma_f32_16x16x32_bf16 v[74:77], v[142:145], v[208:211], v[74:77]
	v_mfma_f32_16x16x32_bf16 v[134:137], v[138:141], v[170:173], v[134:137]
	v_mfma_f32_16x16x32_bf16 v[130:133], v[146:149], v[170:173], v[130:133]
	v_mfma_f32_16x16x32_bf16 v[110:113], v[138:141], v[178:181], v[110:113]
	v_mfma_f32_16x16x32_bf16 v[106:109], v[146:149], v[178:181], v[106:109]
	v_mfma_f32_16x16x32_bf16 v[94:97], v[138:141], v[204:207], v[94:97]
	v_mfma_f32_16x16x32_bf16 v[90:93], v[146:149], v[204:207], v[90:93]
	v_mfma_f32_16x16x32_bf16 v[78:81], v[138:141], v[212:215], v[78:81]
	v_mfma_f32_16x16x32_bf16 v[74:77], v[146:149], v[212:215], v[74:77]
	v_mfma_f32_16x16x32_bf16 v[120:123], v[150:153], v[166:169], v[122:125]
	v_mfma_f32_16x16x32_bf16 v[116:119], v[158:161], v[166:169], v[116:119]
	v_mfma_f32_16x16x32_bf16 v[102:105], v[150:153], v[174:177], v[102:105]
	v_mfma_f32_16x16x32_bf16 v[98:101], v[158:161], v[174:177], v[98:101]
	v_mfma_f32_16x16x32_bf16 v[86:89], v[150:153], v[182:185], v[86:89]
	v_mfma_f32_16x16x32_bf16 v[82:85], v[158:161], v[182:185], v[82:85]
	v_mfma_f32_16x16x32_bf16 v[70:73], v[150:153], v[208:211], v[70:73]
	v_mfma_f32_16x16x32_bf16 v[66:69], v[158:161], v[208:211], v[66:69]
	v_mfma_f32_16x16x32_bf16 v[122:125], v[154:157], v[170:173], v[120:123]
	v_mfma_f32_16x16x32_bf16 v[118:121], v[162:165], v[170:173], v[116:119]
	v_mfma_f32_16x16x32_bf16 v[102:105], v[154:157], v[178:181], v[102:105]
	v_mfma_f32_16x16x32_bf16 v[98:101], v[162:165], v[178:181], v[98:101]
	v_mfma_f32_16x16x32_bf16 v[86:89], v[154:157], v[204:207], v[86:89]
	v_mfma_f32_16x16x32_bf16 v[82:85], v[162:165], v[204:207], v[82:85]
	v_mfma_f32_16x16x32_bf16 v[70:73], v[154:157], v[212:215], v[70:73]
	v_mfma_f32_16x16x32_bf16 v[66:69], v[162:165], v[212:215], v[66:69]
	s_barrier
	s_add_i32 m0, s53, 0x17f80
	ds_read_b128 v[166:169], v235 offset:49152
	ds_read_b128 v[170:173], v235 offset:50176
	ds_read_b128 v[174:177], v235 offset:51200
	ds_read_b128 v[178:181], v235 offset:52224
	ds_read_b128 v[182:185], v235 offset:53248
	ds_read_b128 v[204:207], v235 offset:54272
	ds_read_b128 v[208:211], v235 offset:55296
	ds_read_b128 v[212:215], v235 offset:56320
	global_load_lds_dwordx4 v[216:217], off offset:128
	s_add_i32 m0, s53, 0x19f80
	global_load_lds_dwordx4 v[218:219], off offset:128
	s_add_i32 m0, s53, 0x1bf80
	s_nop 0
	global_load_lds_dwordx4 v0, s[74:75] offset:128
	s_add_i32 m0, s53, 0x1df80
	s_nop 0
	global_load_lds_dwordx4 v198, s[74:75] offset:128
	s_add_i32 m0, s64, 0xffffff80
	s_nop 0
	global_load_lds_dwordx4 v194, s[54:55] offset:128
	s_add_i32 m0, s65, 0xffffff80
	s_nop 0
	global_load_lds_dwordx4 v196, s[54:55] offset:128
	s_waitcnt vmcnt(8) lgkmcnt(0)
	s_barrier
	v_mfma_f32_16x16x32_bf16 v[62:65], v[126:129], v[166:169], v[62:65]
	v_mfma_f32_16x16x32_bf16 v[58:61], v[142:145], v[166:169], v[58:61]
	v_mfma_f32_16x16x32_bf16 v[46:49], v[126:129], v[174:177], v[46:49]
	v_mfma_f32_16x16x32_bf16 v[42:45], v[142:145], v[174:177], v[42:45]
	v_mfma_f32_16x16x32_bf16 v[30:33], v[126:129], v[182:185], v[30:33]
	v_mfma_f32_16x16x32_bf16 v[26:29], v[142:145], v[182:185], v[26:29]
	v_mfma_f32_16x16x32_bf16 v[14:17], v[126:129], v[208:211], v[14:17]
	v_mfma_f32_16x16x32_bf16 v[10:13], v[142:145], v[208:211], v[10:13]
	v_mfma_f32_16x16x32_bf16 v[62:65], v[138:141], v[170:173], v[62:65]
	v_mfma_f32_16x16x32_bf16 v[58:61], v[146:149], v[170:173], v[58:61]
	v_mfma_f32_16x16x32_bf16 v[46:49], v[138:141], v[178:181], v[46:49]
	v_mfma_f32_16x16x32_bf16 v[42:45], v[146:149], v[178:181], v[42:45]
	v_mfma_f32_16x16x32_bf16 v[30:33], v[138:141], v[204:207], v[30:33]
	v_mfma_f32_16x16x32_bf16 v[26:29], v[146:149], v[204:207], v[26:29]
	v_mfma_f32_16x16x32_bf16 v[14:17], v[138:141], v[212:215], v[14:17]
	v_mfma_f32_16x16x32_bf16 v[10:13], v[146:149], v[212:215], v[10:13]
	v_mfma_f32_16x16x32_bf16 v[54:57], v[150:153], v[166:169], v[54:57]
	v_mfma_f32_16x16x32_bf16 v[50:53], v[158:161], v[166:169], v[50:53]
	v_mfma_f32_16x16x32_bf16 v[38:41], v[150:153], v[174:177], v[38:41]
	v_mfma_f32_16x16x32_bf16 v[34:37], v[158:161], v[174:177], v[34:37]
	v_mfma_f32_16x16x32_bf16 v[22:25], v[150:153], v[182:185], v[22:25]
	v_mfma_f32_16x16x32_bf16 v[18:21], v[158:161], v[182:185], v[18:21]
	v_mfma_f32_16x16x32_bf16 v[6:9], v[150:153], v[208:211], v[6:9]
	v_mfma_f32_16x16x32_bf16 v[2:5], v[158:161], v[208:211], v[2:5]
	v_mfma_f32_16x16x32_bf16 v[54:57], v[154:157], v[170:173], v[54:57]
	v_mfma_f32_16x16x32_bf16 v[50:53], v[162:165], v[170:173], v[50:53]
	v_mfma_f32_16x16x32_bf16 v[38:41], v[154:157], v[178:181], v[38:41]
	v_mfma_f32_16x16x32_bf16 v[34:37], v[162:165], v[178:181], v[34:37]
	v_mfma_f32_16x16x32_bf16 v[22:25], v[154:157], v[204:207], v[22:25]
	v_mfma_f32_16x16x32_bf16 v[18:21], v[162:165], v[204:207], v[18:21]
	v_mfma_f32_16x16x32_bf16 v[6:9], v[154:157], v[212:215], v[6:9]
	v_mfma_f32_16x16x32_bf16 v[2:5], v[162:165], v[212:215], v[2:5]
	s_barrier
	s_add_u32 s44, s44, 0x100
	s_addc_u32 s45, s45, 0
	s_add_u32 s56, s56, 0x100
	s_addc_u32 s57, s57, 0
	s_cmp_ge_i32 s72, s63
	s_mov_b32 s54, s72
	s_cbranch_scc0 .LBB0_699
	s_setprio 0
	s_movk_i32 s75, 0x2000
	s_mov_b32 s72, 0x10000
	s_mov_b32 s73, 0x12000
	s_mov_b32 s74, 0x14000
	s_mov_b32 s71, 0x3f317217
	s_and_b64 vcc, exec, s[48:49]
	s_cbranch_vccz .LBB0_673

; #define PG8_STAGE(bufoff, gbase, voff) do { _Pragma("unroll") for (int _i = 0; _i < 2; ++_i) \
;         __builtin_amdgcn_global_load_lds((const unsigned*)((const char*)(gbase) + (voff)[_i]), (PG8_LAS unsigned*)(lds + (bufoff) + ldsw + _i * 8192), 16, 0, 0); } while (0)
; #define PG8_LDA(dst, b, h) do { _Pragma("unroll") for (int m = 0; m < 4; ++m) _Pragma("unroll") for (int k = 0; k < 2; ++k) dst[m][k] = *(const PG8_LAS bf16x8*)(lds + PG8_SA(b, h) + aoff + m * 2048 + k * 1024); } while (0)
; #define PG8_LDB(dst, b, h) do { _Pragma("unroll") for (int n = 0; n < 2; ++n) _Pragma("unroll") for (int k = 0; k < 2; ++k) dst[n][k] = *(const PG8_LAS bf16x8*)(lds + PG8_SB(b, h) + boff + n * 2048 + k * 1024); } while (0)
; #define PG8_MMA(ai, bj, At, Bt) do { __builtin_amdgcn_s_setprio(1); _Pragma("unroll") for (int m = 0; m < 4; ++m) _Pragma("unroll") for (int n = 0; n < 2; ++n) _Pragma("unroll") for (int k = 0; k < 2; ++k) \
;         acc[ai][bj][m][n] = __builtin_amdgcn_mfma_f32_16x16x32_bf16(Bt[n][k], At[m][k], acc[ai][bj][m][n], 0, 0, 0); __builtin_amdgcn_s_setprio(0); } while (0)
; #define PG8_WAIT_V(n) asm volatile("s_waitcnt vmcnt(" #n ")" ::: "memory")
; template <class Epi, class Sched, bool ALIGN_EPI = false, bool SP2 = false>
; __device__ __forceinline__ void gemm_phase(PG8_LAS unsigned char* lds, const Gemm g, const Sched& S, const Epi& E, const int wv) {
;     ...
;             const bool last = (t == nt - 2);
;             const char* a1 = cA + (size_t)(t + 1) * kstep;
;             const char* a2 = last ? nA : cA + (size_t)(t + 2) * kstep; const char* b2 = last ? nB : cB + (size_t)(t + 2) * kstep;
;             const char* a3 = a2 + kstep; const char* b3 = b2 + kstep;
;             if (last && has_next) S.a_ready(nxt);
;             if constexpr (SP2) {
;             PG8_LDB(B0, 0, 0); PG8_LDB(B1, 0, 1); PG8_SCHED; PG8_LDA(At, 0, 0); PG8_STAGE(PG8_SA(1, 1), a1 + hstepA, voffA);
;             PG8_WAIT_V(8); PG8_WAIT_L(0); PG8_BAR; PG8_MMA(0, 0, At, B0); PG8_MMA(0, 1, At, B1); PG8_BAR; PG8_SCHED;
;     ...
; #pragma unroll
;         for (int a = 0; a < 2; ++a)
; #pragma unroll
;             for (int b = 0; b < 2; ++b)
; #pragma unroll
;                 for (int m = 0; m < 4; ++m)
; #pragma unroll
;                     for (int n = 0; n < 2; ++n) acc[a][b][m][n] = (f32x4){0.f, 0.f, 0.f, 0.f};
;         cur = nxt; cA = nA; cB = nB; ++ui;
.LBB0_808:
	s_and_b64 s[14:15], s[46:47], exec
	s_cselect_b32 s11, s91, s49
	s_cselect_b32 s13, s90, s48
	s_add_u32 s35, s52, 0x100
	v_mov_b32_e32 v18, 0
	s_addc_u32 s51, s53, 0
	s_mov_b32 s46, 0
	v_mov_b32_e32 v19, v18
	v_pk_mov_b32 v[20:21], v[18:19], v[18:19]
	v_pk_mov_b32 v[90:91], v[18:19], v[18:19]
	v_pk_mov_b32 v[92:93], v[18:19], v[18:19]
	v_pk_mov_b32 v[22:23], v[18:19], v[18:19]
	v_pk_mov_b32 v[24:25], v[18:19], v[18:19]
	v_pk_mov_b32 v[94:95], v[18:19], v[18:19]
	v_pk_mov_b32 v[96:97], v[18:19], v[18:19]
	v_pk_mov_b32 v[2:3], v[18:19], v[18:19]
	v_pk_mov_b32 v[4:5], v[18:19], v[18:19]
	v_pk_mov_b32 v[66:67], v[18:19], v[18:19]
	v_pk_mov_b32 v[68:69], v[18:19], v[18:19]
	v_pk_mov_b32 v[10:11], v[18:19], v[18:19]
	v_pk_mov_b32 v[12:13], v[18:19], v[18:19]
	v_pk_mov_b32 v[82:83], v[18:19], v[18:19]
	v_pk_mov_b32 v[84:85], v[18:19], v[18:19]
	v_pk_mov_b32 v[26:27], v[18:19], v[18:19]
	v_pk_mov_b32 v[28:29], v[18:19], v[18:19]
	v_pk_mov_b32 v[98:99], v[18:19], v[18:19]
	v_pk_mov_b32 v[100:101], v[18:19], v[18:19]
	v_pk_mov_b32 v[30:31], v[18:19], v[18:19]
	v_pk_mov_b32 v[32:33], v[18:19], v[18:19]
	v_pk_mov_b32 v[102:103], v[18:19], v[18:19]
	v_pk_mov_b32 v[104:105], v[18:19], v[18:19]
	v_pk_mov_b32 v[6:7], v[18:19], v[18:19]
	v_pk_mov_b32 v[8:9], v[18:19], v[18:19]
	v_pk_mov_b32 v[70:71], v[18:19], v[18:19]
	v_pk_mov_b32 v[72:73], v[18:19], v[18:19]
	v_pk_mov_b32 v[14:15], v[18:19], v[18:19]
	v_pk_mov_b32 v[16:17], v[18:19], v[18:19]
	v_pk_mov_b32 v[86:87], v[18:19], v[18:19]
	v_pk_mov_b32 v[88:89], v[18:19], v[18:19]
	v_pk_mov_b32 v[50:51], v[18:19], v[18:19]
	v_pk_mov_b32 v[52:53], v[18:19], v[18:19]
	v_pk_mov_b32 v[122:123], v[18:19], v[18:19]
	v_pk_mov_b32 v[124:125], v[18:19], v[18:19]
	v_pk_mov_b32 v[54:55], v[18:19], v[18:19]
	v_pk_mov_b32 v[56:57], v[18:19], v[18:19]
	v_pk_mov_b32 v[126:127], v[18:19], v[18:19]
	v_pk_mov_b32 v[128:129], v[18:19], v[18:19]
	v_pk_mov_b32 v[34:35], v[18:19], v[18:19]
	v_pk_mov_b32 v[36:37], v[18:19], v[18:19]
	v_pk_mov_b32 v[106:107], v[18:19], v[18:19]
	v_pk_mov_b32 v[108:109], v[18:19], v[18:19]
	v_pk_mov_b32 v[42:43], v[18:19], v[18:19]
	v_pk_mov_b32 v[44:45], v[18:19], v[18:19]
	v_pk_mov_b32 v[114:115], v[18:19], v[18:19]
	v_pk_mov_b32 v[116:117], v[18:19], v[18:19]
	v_pk_mov_b32 v[58:59], v[18:19], v[18:19]
	v_pk_mov_b32 v[60:61], v[18:19], v[18:19]
	v_pk_mov_b32 v[130:131], v[18:19], v[18:19]
	v_pk_mov_b32 v[132:133], v[18:19], v[18:19]
	v_pk_mov_b32 v[62:63], v[18:19], v[18:19]
	v_pk_mov_b32 v[64:65], v[18:19], v[18:19]
	v_pk_mov_b32 v[134:135], v[18:19], v[18:19]
	v_pk_mov_b32 v[136:137], v[18:19], v[18:19]
	v_pk_mov_b32 v[38:39], v[18:19], v[18:19]
	v_pk_mov_b32 v[40:41], v[18:19], v[18:19]
	v_pk_mov_b32 v[110:111], v[18:19], v[18:19]
	v_pk_mov_b32 v[112:113], v[18:19], v[18:19]
	v_pk_mov_b32 v[46:47], v[18:19], v[18:19]
	v_pk_mov_b32 v[48:49], v[18:19], v[18:19]
	v_pk_mov_b32 v[118:119], v[18:19], v[18:19]
	v_pk_mov_b32 v[120:121], v[18:19], v[18:19]
	v_add_u32_e32 v192, 0x10000, v208
	v_add_u32_e32 v193, 0x14000, v208
	v_add_u32_e32 v213, 0x18000, v208
	v_add_u32_e32 v227, 0x1c000, v208
	v_add_u32_e32 v218, 0x80000, v170
	v_add_u32_e32 v219, 0x80000, v172
	s_cmp_eq_u64 s[30:31], 0
	s_cbranch_scc0 .Lsp_skip_3
	s_setprio 1
.Lsp_skip_3:
.LBB0_809:
	s_add_i32 s52, s46, 2
	s_add_u32 s14, s48, 0x100
	s_addc_u32 s15, s49, 0
	s_cmp_eq_u32 s71, s46
	s_cselect_b32 s47, s11, s15
	s_cselect_b32 s46, s13, s14
	s_cselect_b32 s77, s87, s51
	s_cselect_b32 s76, s86, s35
	ds_read_b128 v[138:141], v192
	ds_read_b128 v[142:145], v192 offset:1024
	ds_read_b128 v[146:149], v192 offset:2048
	ds_read_b128 v[150:153], v192 offset:3072
	ds_read_b128 v[154:157], v193
	ds_read_b128 v[158:161], v193 offset:1024
	ds_read_b128 v[162:165], v193 offset:2048
	ds_read_b128 v[166:169], v193 offset:3072
	s_add_i32 m0, s63, 0xc000
	ds_read_b128 v[194:197], v211
	ds_read_b128 v[198:201], v211 offset:1024
	ds_read_b128 v[202:205], v211 offset:2048
	ds_read_b128 v[214:217], v211 offset:3072
	ds_read_b128 v[228:231], v211 offset:4096
	ds_read_b128 v[232:235], v211 offset:5120
	ds_read_b128 v[236:239], v211 offset:6144
	ds_read_b128 v[240:243], v211 offset:7168
	global_load_lds_dwordx4 v182, s[48:49]
	v_lshl_add_u64 v[190:191], s[48:49], 0, v[184:185]
	s_add_i32 m0, s63, 0xe000
	s_nop 0
	global_load_lds_dwordx4 v[190:191], off
	s_waitcnt vmcnt(8) lgkmcnt(0)
	s_barrier
	v_mfma_f32_16x16x32_bf16 v[118:121], v[138:141], v[194:197], v[118:121]
	v_mfma_f32_16x16x32_bf16 v[46:49], v[146:149], v[194:197], v[46:49]
	v_mfma_f32_16x16x32_bf16 v[110:113], v[138:141], v[202:205], v[110:113]
	v_mfma_f32_16x16x32_bf16 v[38:41], v[146:149], v[202:205], v[38:41]
	v_mfma_f32_16x16x32_bf16 v[134:137], v[138:141], v[228:231], v[134:137]
	v_mfma_f32_16x16x32_bf16 v[62:65], v[146:149], v[228:231], v[62:65]
	v_mfma_f32_16x16x32_bf16 v[130:133], v[138:141], v[236:239], v[130:133]
	v_mfma_f32_16x16x32_bf16 v[58:61], v[146:149], v[236:239], v[58:61]
	v_mfma_f32_16x16x32_bf16 v[118:121], v[142:145], v[198:201], v[118:121]
	v_mfma_f32_16x16x32_bf16 v[46:49], v[150:153], v[198:201], v[46:49]
	v_mfma_f32_16x16x32_bf16 v[110:113], v[142:145], v[214:217], v[110:113]
	v_mfma_f32_16x16x32_bf16 v[38:41], v[150:153], v[214:217], v[38:41]
	v_mfma_f32_16x16x32_bf16 v[134:137], v[142:145], v[232:235], v[134:137]
	v_mfma_f32_16x16x32_bf16 v[62:65], v[150:153], v[232:235], v[62:65]
	v_mfma_f32_16x16x32_bf16 v[130:133], v[142:145], v[240:243], v[130:133]
	v_mfma_f32_16x16x32_bf16 v[58:61], v[150:153], v[240:243], v[58:61]
	v_mfma_f32_16x16x32_bf16 v[114:117], v[154:157], v[194:197], v[114:117]
	v_mfma_f32_16x16x32_bf16 v[42:45], v[162:165], v[194:197], v[42:45]
	v_mfma_f32_16x16x32_bf16 v[106:109], v[154:157], v[202:205], v[106:109]
	v_mfma_f32_16x16x32_bf16 v[34:37], v[162:165], v[202:205], v[34:37]
	v_mfma_f32_16x16x32_bf16 v[126:129], v[154:157], v[228:231], v[126:129]
	v_mfma_f32_16x16x32_bf16 v[54:57], v[162:165], v[228:231], v[54:57]
	v_mfma_f32_16x16x32_bf16 v[122:125], v[154:157], v[236:239], v[122:125]
	v_mfma_f32_16x16x32_bf16 v[50:53], v[162:165], v[236:239], v[50:53]
	v_mfma_f32_16x16x32_bf16 v[114:117], v[158:161], v[198:201], v[114:117]
	v_mfma_f32_16x16x32_bf16 v[42:45], v[166:169], v[198:201], v[42:45]
	v_mfma_f32_16x16x32_bf16 v[106:109], v[158:161], v[214:217], v[106:109]
	v_mfma_f32_16x16x32_bf16 v[34:37], v[166:169], v[214:217], v[34:37]
	v_mfma_f32_16x16x32_bf16 v[126:129], v[158:161], v[232:235], v[126:129]
	v_mfma_f32_16x16x32_bf16 v[54:57], v[166:169], v[232:235], v[54:57]
	v_mfma_f32_16x16x32_bf16 v[122:125], v[158:161], v[240:243], v[122:125]
	v_mfma_f32_16x16x32_bf16 v[50:53], v[166:169], v[240:243], v[50:53]
	s_barrier
; #define PG8_STAGE(bufoff, gbase, voff) do { _Pragma("unroll") for (int _i = 0; _i < 2; ++_i) \
;         __builtin_amdgcn_global_load_lds((const unsigned*)((const char*)(gbase) + (voff)[_i]), (PG8_LAS unsigned*)(lds + (bufoff) + ldsw + _i * 8192), 16, 0, 0); } while (0)
; #define PG8_LDA(dst, b, h) do { _Pragma("unroll") for (int m = 0; m < 4; ++m) _Pragma("unroll") for (int k = 0; k < 2; ++k) dst[m][k] = *(const PG8_LAS bf16x8*)(lds + PG8_SA(b, h) + aoff + m * 2048 + k * 1024); } while (0)
; #define PG8_LDB(dst, b, h) do { _Pragma("unroll") for (int n = 0; n < 2; ++n) _Pragma("unroll") for (int k = 0; k < 2; ++k) dst[n][k] = *(const PG8_LAS bf16x8*)(lds + PG8_SB(b, h) + boff + n * 2048 + k * 1024); } while (0)
; #define PG8_MMA(ai, bj, At, Bt) do { __builtin_amdgcn_s_setprio(1); _Pragma("unroll") for (int m = 0; m < 4; ++m) _Pragma("unroll") for (int n = 0; n < 2; ++n) _Pragma("unroll") for (int k = 0; k < 2; ++k) \
;         acc[ai][bj][m][n] = __builtin_amdgcn_mfma_f32_16x16x32_bf16(Bt[n][k], At[m][k], acc[ai][bj][m][n], 0, 0, 0); __builtin_amdgcn_s_setprio(0); } while (0)
; #define PG8_WAIT_V(n) asm volatile("s_waitcnt vmcnt(" #n ")" ::: "memory")
; #define PG8_WAIT_L(n) asm volatile("s_waitcnt lgkmcnt(" #n ")" ::: "memory")
; #define PG8_BAR __builtin_amdgcn_s_barrier()
; #define PG8_SCHED __builtin_amdgcn_sched_barrier(0)
; template <class Epi, class Sched, bool ALIGN_EPI = false, bool SP2 = false>
; __device__ __forceinline__ void gemm_phase(PG8_LAS unsigned char* lds, const Gemm g, const Sched& S, const Epi& E, const int wv) {
;     ...
;             PG8_LDA(At, 0, 1); PG8_STAGE(PG8_SB(0, 0), b2, voffB); PG8_STAGE(PG8_SB(0, 1), b2 + hstepB, voffB); PG8_STAGE(PG8_SA(0, 0), a2, voffA);
;             PG8_WAIT_V(8); PG8_WAIT_L(0); PG8_BAR; PG8_MMA(1, 0, At, B0); PG8_MMA(1, 1, At, B1); PG8_BAR; PG8_SCHED;
;             PG8_LDB(B0, 1, 0); PG8_LDB(B1, 1, 1); PG8_SCHED; PG8_LDA(At, 1, 0); PG8_STAGE(PG8_SA(0, 1), a2 + hstepA, voffA);
;             PG8_WAIT_V(8); PG8_WAIT_L(0); PG8_BAR; PG8_MMA(0, 0, At, B0); PG8_MMA(0, 1, At, B1); PG8_BAR; PG8_SCHED;
	s_add_i32 s48, s62, 0x10000
	s_mov_b32 m0, s48
	ds_read_b128 v[194:197], v211 offset:16384
	ds_read_b128 v[198:201], v211 offset:17408
	ds_read_b128 v[202:205], v211 offset:18432
	ds_read_b128 v[214:217], v211 offset:19456
	ds_read_b128 v[228:231], v211 offset:20480
	ds_read_b128 v[232:235], v211 offset:21504
	ds_read_b128 v[236:239], v211 offset:22528
	ds_read_b128 v[240:243], v211 offset:23552
	global_load_lds_dwordx4 v0, s[76:77]
	s_add_i32 m0, s48, 0x2000
	s_add_u32 s48, s76, s16
	s_addc_u32 s49, s77, s17
	s_add_i32 s53, s62, 0x14000
	global_load_lds_dwordx4 v174, s[76:77]
	s_mov_b32 m0, s53
	global_load_lds_dwordx4 v0, s[48:49]
	s_add_i32 m0, s53, 0x2000
	global_load_lds_dwordx4 v174, s[48:49]
	s_mov_b32 m0, s63
	global_load_lds_dwordx4 v170, s[46:47]
	s_mov_b32 m0, s64
	s_nop 0
	global_load_lds_dwordx4 v172, s[46:47]
	s_waitcnt vmcnt(8) lgkmcnt(0)
	s_barrier
	v_mfma_f32_16x16x32_bf16 v[86:89], v[138:141], v[194:197], v[86:89]
	v_mfma_f32_16x16x32_bf16 v[14:17], v[146:149], v[194:197], v[14:17]
	v_mfma_f32_16x16x32_bf16 v[70:73], v[138:141], v[202:205], v[70:73]
	v_mfma_f32_16x16x32_bf16 v[6:9], v[146:149], v[202:205], v[6:9]
	v_mfma_f32_16x16x32_bf16 v[102:105], v[138:141], v[228:231], v[102:105]
	v_mfma_f32_16x16x32_bf16 v[30:33], v[146:149], v[228:231], v[30:33]
	v_mfma_f32_16x16x32_bf16 v[98:101], v[138:141], v[236:239], v[98:101]
	v_mfma_f32_16x16x32_bf16 v[26:29], v[146:149], v[236:239], v[26:29]
	v_mfma_f32_16x16x32_bf16 v[86:89], v[142:145], v[198:201], v[86:89]
	v_mfma_f32_16x16x32_bf16 v[14:17], v[150:153], v[198:201], v[14:17]
	v_mfma_f32_16x16x32_bf16 v[70:73], v[142:145], v[214:217], v[70:73]
	v_mfma_f32_16x16x32_bf16 v[6:9], v[150:153], v[214:217], v[6:9]
	v_mfma_f32_16x16x32_bf16 v[102:105], v[142:145], v[232:235], v[102:105]
	v_mfma_f32_16x16x32_bf16 v[30:33], v[150:153], v[232:235], v[30:33]
	v_mfma_f32_16x16x32_bf16 v[98:101], v[142:145], v[240:243], v[98:101]
	v_mfma_f32_16x16x32_bf16 v[26:29], v[150:153], v[240:243], v[26:29]
	v_mfma_f32_16x16x32_bf16 v[82:85], v[154:157], v[194:197], v[82:85]
	v_mfma_f32_16x16x32_bf16 v[10:13], v[162:165], v[194:197], v[10:13]
	v_mfma_f32_16x16x32_bf16 v[66:69], v[154:157], v[202:205], v[66:69]
	v_mfma_f32_16x16x32_bf16 v[2:5], v[162:165], v[202:205], v[2:5]
	v_mfma_f32_16x16x32_bf16 v[94:97], v[154:157], v[228:231], v[94:97]
	v_mfma_f32_16x16x32_bf16 v[22:25], v[162:165], v[228:231], v[22:25]
	v_mfma_f32_16x16x32_bf16 v[90:93], v[154:157], v[236:239], v[90:93]
	v_mfma_f32_16x16x32_bf16 v[18:21], v[162:165], v[236:239], v[18:21]
	v_mfma_f32_16x16x32_bf16 v[82:85], v[158:161], v[198:201], v[82:85]
	v_mfma_f32_16x16x32_bf16 v[10:13], v[166:169], v[198:201], v[10:13]
	v_mfma_f32_16x16x32_bf16 v[66:69], v[158:161], v[214:217], v[66:69]
	v_mfma_f32_16x16x32_bf16 v[2:5], v[166:169], v[214:217], v[2:5]
	v_mfma_f32_16x16x32_bf16 v[94:97], v[158:161], v[232:235], v[94:97]
	v_mfma_f32_16x16x32_bf16 v[22:25], v[166:169], v[232:235], v[22:25]
	v_mfma_f32_16x16x32_bf16 v[90:93], v[158:161], v[240:243], v[90:93]
	v_mfma_f32_16x16x32_bf16 v[18:21], v[166:169], v[240:243], v[18:21]
	s_barrier
	ds_read_b128 v[138:141], v213
	ds_read_b128 v[142:145], v213 offset:1024
	ds_read_b128 v[146:149], v213 offset:2048
	ds_read_b128 v[150:153], v213 offset:3072
	ds_read_b128 v[154:157], v227
	ds_read_b128 v[158:161], v227 offset:1024
	ds_read_b128 v[162:165], v227 offset:2048
	ds_read_b128 v[166:169], v227 offset:3072
	s_mov_b32 m0, s65
	ds_read_b128 v[194:197], v211 offset:32768
	ds_read_b128 v[198:201], v211 offset:33792
	ds_read_b128 v[202:205], v211 offset:34816
	ds_read_b128 v[214:217], v211 offset:35840
	ds_read_b128 v[228:231], v211 offset:36864
	ds_read_b128 v[232:235], v211 offset:37888
	ds_read_b128 v[236:239], v211 offset:38912
	ds_read_b128 v[240:243], v211 offset:39936
	global_load_lds_dwordx4 v218, s[46:47]
	s_mov_b32 m0, s66
	s_nop 0
	global_load_lds_dwordx4 v219, s[46:47]
	s_waitcnt vmcnt(8) lgkmcnt(0)
	s_barrier
; #define PG8_STAGE(bufoff, gbase, voff) do { _Pragma("unroll") for (int _i = 0; _i < 2; ++_i) \
;         __builtin_amdgcn_global_load_lds((const unsigned*)((const char*)(gbase) + (voff)[_i]), (PG8_LAS unsigned*)(lds + (bufoff) + ldsw + _i * 8192), 16, 0, 0); } while (0)
; #define PG8_LDA(dst, b, h) do { _Pragma("unroll") for (int m = 0; m < 4; ++m) _Pragma("unroll") for (int k = 0; k < 2; ++k) dst[m][k] = *(const PG8_LAS bf16x8*)(lds + PG8_SA(b, h) + aoff + m * 2048 + k * 1024); } while (0)
; #define PG8_MMA(ai, bj, At, Bt) do { __builtin_amdgcn_s_setprio(1); _Pragma("unroll") for (int m = 0; m < 4; ++m) _Pragma("unroll") for (int n = 0; n < 2; ++n) _Pragma("unroll") for (int k = 0; k < 2; ++k) \
;         acc[ai][bj][m][n] = __builtin_amdgcn_mfma_f32_16x16x32_bf16(Bt[n][k], At[m][k], acc[ai][bj][m][n], 0, 0, 0); __builtin_amdgcn_s_setprio(0); } while (0)
; #define PG8_WAIT_V(n) asm volatile("s_waitcnt vmcnt(" #n ")" ::: "memory")
; #define PG8_WAIT_L(n) asm volatile("s_waitcnt lgkmcnt(" #n ")" ::: "memory")
; #define PG8_BAR __builtin_amdgcn_s_barrier()
; #define PG8_SCHED __builtin_amdgcn_sched_barrier(0)
; template <class Epi, class Sched, bool ALIGN_EPI = false, bool SP2 = false>
; __device__ __forceinline__ void gemm_phase(PG8_LAS unsigned char* lds, const Gemm g, const Sched& S, const Epi& E, const int wv) {
;     ...
;             PG8_WAIT_V(8); PG8_WAIT_L(0); PG8_BAR; PG8_MMA(0, 0, At, B0); PG8_MMA(0, 1, At, B1); PG8_BAR; PG8_SCHED;
;             PG8_LDA(At, 1, 1); PG8_STAGE(PG8_SB(1, 0), b3, voffB); PG8_STAGE(PG8_SB(1, 1), b3 + hstepB, voffB); PG8_STAGE(PG8_SA(1, 0), a3, voffA);
;             PG8_WAIT_V(8); PG8_WAIT_L(0); PG8_BAR; PG8_MMA(1, 0, At, B0); PG8_MMA(1, 1, At, B1); PG8_BAR; PG8_SCHED;
	v_mfma_f32_16x16x32_bf16 v[118:121], v[138:141], v[194:197], v[118:121]
	v_mfma_f32_16x16x32_bf16 v[46:49], v[146:149], v[194:197], v[46:49]
	v_mfma_f32_16x16x32_bf16 v[110:113], v[138:141], v[202:205], v[110:113]
	v_mfma_f32_16x16x32_bf16 v[38:41], v[146:149], v[202:205], v[38:41]
	v_mfma_f32_16x16x32_bf16 v[134:137], v[138:141], v[228:231], v[134:137]
	v_mfma_f32_16x16x32_bf16 v[62:65], v[146:149], v[228:231], v[62:65]
	v_mfma_f32_16x16x32_bf16 v[130:133], v[138:141], v[236:239], v[130:133]
	v_mfma_f32_16x16x32_bf16 v[58:61], v[146:149], v[236:239], v[58:61]
	v_mfma_f32_16x16x32_bf16 v[118:121], v[142:145], v[198:201], v[118:121]
	v_mfma_f32_16x16x32_bf16 v[46:49], v[150:153], v[198:201], v[46:49]
	v_mfma_f32_16x16x32_bf16 v[110:113], v[142:145], v[214:217], v[110:113]
	v_mfma_f32_16x16x32_bf16 v[38:41], v[150:153], v[214:217], v[38:41]
	v_mfma_f32_16x16x32_bf16 v[134:137], v[142:145], v[232:235], v[134:137]
	v_mfma_f32_16x16x32_bf16 v[62:65], v[150:153], v[232:235], v[62:65]
	v_mfma_f32_16x16x32_bf16 v[130:133], v[142:145], v[240:243], v[130:133]
	v_mfma_f32_16x16x32_bf16 v[58:61], v[150:153], v[240:243], v[58:61]
	v_mfma_f32_16x16x32_bf16 v[114:117], v[154:157], v[194:197], v[114:117]
	v_mfma_f32_16x16x32_bf16 v[42:45], v[162:165], v[194:197], v[42:45]
	v_mfma_f32_16x16x32_bf16 v[106:109], v[154:157], v[202:205], v[106:109]
	v_mfma_f32_16x16x32_bf16 v[34:37], v[162:165], v[202:205], v[34:37]
	v_mfma_f32_16x16x32_bf16 v[126:129], v[154:157], v[228:231], v[126:129]
	v_mfma_f32_16x16x32_bf16 v[54:57], v[162:165], v[228:231], v[54:57]
	v_mfma_f32_16x16x32_bf16 v[122:125], v[154:157], v[236:239], v[122:125]
	v_mfma_f32_16x16x32_bf16 v[50:53], v[162:165], v[236:239], v[50:53]
	v_mfma_f32_16x16x32_bf16 v[114:117], v[158:161], v[198:201], v[114:117]
	v_mfma_f32_16x16x32_bf16 v[42:45], v[166:169], v[198:201], v[42:45]
	v_mfma_f32_16x16x32_bf16 v[106:109], v[158:161], v[214:217], v[106:109]
	v_mfma_f32_16x16x32_bf16 v[34:37], v[166:169], v[214:217], v[34:37]
	v_mfma_f32_16x16x32_bf16 v[126:129], v[158:161], v[232:235], v[126:129]
	v_mfma_f32_16x16x32_bf16 v[54:57], v[166:169], v[232:235], v[54:57]
	v_mfma_f32_16x16x32_bf16 v[122:125], v[158:161], v[240:243], v[122:125]
	v_mfma_f32_16x16x32_bf16 v[50:53], v[166:169], v[240:243], v[50:53]
	s_barrier
	s_add_i32 m0, s62, 0x17f80
	ds_read_b128 v[194:197], v211 offset:49152
	ds_read_b128 v[198:201], v211 offset:50176
	ds_read_b128 v[202:205], v211 offset:51200
	ds_read_b128 v[214:217], v211 offset:52224
	ds_read_b128 v[228:231], v211 offset:53248
	ds_read_b128 v[232:235], v211 offset:54272
	ds_read_b128 v[236:239], v211 offset:55296
	ds_read_b128 v[240:243], v211 offset:56320
	global_load_lds_dwordx4 v0, s[76:77] offset:128
	s_add_i32 m0, s62, 0x19f80
	global_load_lds_dwordx4 v174, s[76:77] offset:128
	s_add_i32 m0, s62, 0x1bf80
	s_nop 0
	global_load_lds_dwordx4 v0, s[48:49] offset:128
	s_add_i32 m0, s62, 0x1df80
	s_nop 0
	global_load_lds_dwordx4 v174, s[48:49] offset:128
	s_add_i32 m0, s69, 0xffffff80
	s_nop 0
	global_load_lds_dwordx4 v170, s[46:47] offset:128
	s_add_i32 m0, s70, 0xffffff80
	s_nop 0
	global_load_lds_dwordx4 v172, s[46:47] offset:128
	s_waitcnt vmcnt(8) lgkmcnt(0)
	s_barrier
	v_mfma_f32_16x16x32_bf16 v[86:89], v[138:141], v[194:197], v[86:89]
	v_mfma_f32_16x16x32_bf16 v[14:17], v[146:149], v[194:197], v[14:17]
	v_mfma_f32_16x16x32_bf16 v[70:73], v[138:141], v[202:205], v[70:73]
	v_mfma_f32_16x16x32_bf16 v[6:9], v[146:149], v[202:205], v[6:9]
	v_mfma_f32_16x16x32_bf16 v[102:105], v[138:141], v[228:231], v[102:105]
	v_mfma_f32_16x16x32_bf16 v[30:33], v[146:149], v[228:231], v[30:33]
	v_mfma_f32_16x16x32_bf16 v[98:101], v[138:141], v[236:239], v[98:101]
	v_mfma_f32_16x16x32_bf16 v[26:29], v[146:149], v[236:239], v[26:29]
	v_mfma_f32_16x16x32_bf16 v[86:89], v[142:145], v[198:201], v[86:89]
	v_mfma_f32_16x16x32_bf16 v[14:17], v[150:153], v[198:201], v[14:17]
	v_mfma_f32_16x16x32_bf16 v[70:73], v[142:145], v[214:217], v[70:73]
	v_mfma_f32_16x16x32_bf16 v[6:9], v[150:153], v[214:217], v[6:9]
	v_mfma_f32_16x16x32_bf16 v[102:105], v[142:145], v[232:235], v[102:105]
	v_mfma_f32_16x16x32_bf16 v[30:33], v[150:153], v[232:235], v[30:33]
	v_mfma_f32_16x16x32_bf16 v[98:101], v[142:145], v[240:243], v[98:101]
	v_mfma_f32_16x16x32_bf16 v[26:29], v[150:153], v[240:243], v[26:29]
	v_mfma_f32_16x16x32_bf16 v[82:85], v[154:157], v[194:197], v[82:85]
	v_mfma_f32_16x16x32_bf16 v[10:13], v[162:165], v[194:197], v[10:13]
	v_mfma_f32_16x16x32_bf16 v[66:69], v[154:157], v[202:205], v[66:69]
	v_mfma_f32_16x16x32_bf16 v[2:5], v[162:165], v[202:205], v[2:5]
	v_mfma_f32_16x16x32_bf16 v[94:97], v[154:157], v[228:231], v[94:97]
	v_mfma_f32_16x16x32_bf16 v[22:25], v[162:165], v[228:231], v[22:25]
	v_mfma_f32_16x16x32_bf16 v[90:93], v[154:157], v[236:239], v[90:93]
	v_mfma_f32_16x16x32_bf16 v[18:21], v[162:165], v[236:239], v[18:21]
	v_mfma_f32_16x16x32_bf16 v[82:85], v[158:161], v[198:201], v[82:85]
	v_mfma_f32_16x16x32_bf16 v[10:13], v[166:169], v[198:201], v[10:13]
	v_mfma_f32_16x16x32_bf16 v[66:69], v[158:161], v[214:217], v[66:69]
	v_mfma_f32_16x16x32_bf16 v[2:5], v[166:169], v[214:217], v[2:5]
	v_mfma_f32_16x16x32_bf16 v[94:97], v[158:161], v[232:235], v[94:97]
	v_mfma_f32_16x16x32_bf16 v[22:25], v[166:169], v[232:235], v[22:25]
	v_mfma_f32_16x16x32_bf16 v[90:93], v[158:161], v[240:243], v[90:93]
	v_mfma_f32_16x16x32_bf16 v[18:21], v[166:169], v[240:243], v[18:21]
	s_barrier
	s_add_u32 s35, s35, 0x100
	s_addc_u32 s51, s51, 0
	s_cmp_ge_i32 s52, s67
	s_mov_b64 s[48:49], s[14:15]
	s_mov_b32 s46, s52
	s_cbranch_scc0 .LBB0_809
	s_setprio 0
	s_movk_i32 s75, 0x2000
	s_movk_i32 s76, 0x3000
	s_and_b64 vcc, exec, s[30:31]
	s_cbranch_vccz .LBB0_784

; #define PG8_STAGE(bufoff, gbase, voff) do { _Pragma("unroll") for (int _i = 0; _i < 2; ++_i) \
;         __builtin_amdgcn_global_load_lds((const unsigned*)((const char*)(gbase) + (voff)[_i]), (PG8_LAS unsigned*)(lds + (bufoff) + ldsw + _i * 8192), 16, 0, 0); } while (0)
; #define PG8_LDA(dst, b, h) do { _Pragma("unroll") for (int m = 0; m < 4; ++m) _Pragma("unroll") for (int k = 0; k < 2; ++k) dst[m][k] = *(const PG8_LAS bf16x8*)(lds + PG8_SA(b, h) + aoff + m * 2048 + k * 1024); } while (0)
; #define PG8_LDB(dst, b, h) do { _Pragma("unroll") for (int n = 0; n < 2; ++n) _Pragma("unroll") for (int k = 0; k < 2; ++k) dst[n][k] = *(const PG8_LAS bf16x8*)(lds + PG8_SB(b, h) + boff + n * 2048 + k * 1024); } while (0)
; #define PG8_MMA(ai, bj, At, Bt) do { __builtin_amdgcn_s_setprio(1); _Pragma("unroll") for (int m = 0; m < 4; ++m) _Pragma("unroll") for (int n = 0; n < 2; ++n) _Pragma("unroll") for (int k = 0; k < 2; ++k) \
;         acc[ai][bj][m][n] = __builtin_amdgcn_mfma_f32_16x16x32_bf16(Bt[n][k], At[m][k], acc[ai][bj][m][n], 0, 0, 0); __builtin_amdgcn_s_setprio(0); } while (0)
; #define PG8_WAIT_V(n) asm volatile("s_waitcnt vmcnt(" #n ")" ::: "memory")
; template <class Epi, class Sched, bool ALIGN_EPI = false, bool SP2 = false>
; __device__ __forceinline__ void gemm_phase(PG8_LAS unsigned char* lds, const Gemm g, const Sched& S, const Epi& E, const int wv) {
;     ...
;             const bool last = (t == nt - 2);
;             const char* a1 = cA + (size_t)(t + 1) * kstep;
;             const char* a2 = last ? nA : cA + (size_t)(t + 2) * kstep; const char* b2 = last ? nB : cB + (size_t)(t + 2) * kstep;
;             const char* a3 = a2 + kstep; const char* b3 = b2 + kstep;
;             if (last && has_next) S.a_ready(nxt);
;             if constexpr (SP2) {
;             PG8_LDB(B0, 0, 0); PG8_LDB(B1, 0, 1); PG8_SCHED; PG8_LDA(At, 0, 0); PG8_STAGE(PG8_SA(1, 1), a1 + hstepA, voffA);
;             PG8_WAIT_V(8); PG8_WAIT_L(0); PG8_BAR; PG8_MMA(0, 0, At, B0); PG8_MMA(0, 1, At, B1); PG8_BAR; PG8_SCHED;
;     ...
; #pragma unroll
;         for (int a = 0; a < 2; ++a)
; #pragma unroll
;             for (int b = 0; b < 2; ++b)
; #pragma unroll
;                 for (int m = 0; m < 4; ++m)
; #pragma unroll
;                     for (int n = 0; n < 2; ++n) acc[a][b][m][n] = (f32x4){0.f, 0.f, 0.f, 0.f};
;         cur = nxt; cA = nA; cB = nB; ++ui;
.LBB0_989:
	s_add_u32 s65, s34, 0x100
	v_mov_b32_e32 v2, 0
	s_addc_u32 s66, s35, 0
	s_mov_b32 s44, 0
	v_mov_b32_e32 v3, v2
	v_pk_mov_b32 v[4:5], v[2:3], v[2:3]
	v_pk_mov_b32 v[6:7], v[2:3], v[2:3]
	v_pk_mov_b32 v[8:9], v[2:3], v[2:3]
	v_pk_mov_b32 v[18:19], v[2:3], v[2:3]
	v_pk_mov_b32 v[20:21], v[2:3], v[2:3]
	v_pk_mov_b32 v[22:23], v[2:3], v[2:3]
	v_pk_mov_b32 v[24:25], v[2:3], v[2:3]
	v_pk_mov_b32 v[34:35], v[2:3], v[2:3]
	v_pk_mov_b32 v[36:37], v[2:3], v[2:3]
	v_pk_mov_b32 v[38:39], v[2:3], v[2:3]
	v_pk_mov_b32 v[40:41], v[2:3], v[2:3]
	v_pk_mov_b32 v[50:51], v[2:3], v[2:3]
	v_pk_mov_b32 v[52:53], v[2:3], v[2:3]
	v_pk_mov_b32 v[54:55], v[2:3], v[2:3]
	v_pk_mov_b32 v[56:57], v[2:3], v[2:3]
	v_pk_mov_b32 v[10:11], v[2:3], v[2:3]
	v_pk_mov_b32 v[12:13], v[2:3], v[2:3]
	v_pk_mov_b32 v[14:15], v[2:3], v[2:3]
	v_pk_mov_b32 v[16:17], v[2:3], v[2:3]
	v_pk_mov_b32 v[26:27], v[2:3], v[2:3]
	v_pk_mov_b32 v[28:29], v[2:3], v[2:3]
	v_pk_mov_b32 v[30:31], v[2:3], v[2:3]
	v_pk_mov_b32 v[32:33], v[2:3], v[2:3]
	v_pk_mov_b32 v[42:43], v[2:3], v[2:3]
	v_pk_mov_b32 v[44:45], v[2:3], v[2:3]
	v_pk_mov_b32 v[46:47], v[2:3], v[2:3]
	v_pk_mov_b32 v[48:49], v[2:3], v[2:3]
	v_pk_mov_b32 v[58:59], v[2:3], v[2:3]
	v_pk_mov_b32 v[60:61], v[2:3], v[2:3]
	v_pk_mov_b32 v[62:63], v[2:3], v[2:3]
	v_pk_mov_b32 v[64:65], v[2:3], v[2:3]
	v_pk_mov_b32 v[66:67], v[2:3], v[2:3]
	v_pk_mov_b32 v[68:69], v[2:3], v[2:3]
	v_pk_mov_b32 v[70:71], v[2:3], v[2:3]
	v_pk_mov_b32 v[72:73], v[2:3], v[2:3]
	v_pk_mov_b32 v[82:83], v[2:3], v[2:3]
	v_pk_mov_b32 v[84:85], v[2:3], v[2:3]
	v_pk_mov_b32 v[86:87], v[2:3], v[2:3]
	v_pk_mov_b32 v[88:89], v[2:3], v[2:3]
	v_pk_mov_b32 v[98:99], v[2:3], v[2:3]
	v_pk_mov_b32 v[100:101], v[2:3], v[2:3]
	v_pk_mov_b32 v[102:103], v[2:3], v[2:3]
	v_pk_mov_b32 v[104:105], v[2:3], v[2:3]
	v_pk_mov_b32 v[118:119], v[2:3], v[2:3]
	v_pk_mov_b32 v[120:121], v[2:3], v[2:3]
	v_pk_mov_b32 v[122:123], v[2:3], v[2:3]
	v_pk_mov_b32 v[124:125], v[2:3], v[2:3]
	v_pk_mov_b32 v[74:75], v[2:3], v[2:3]
	v_pk_mov_b32 v[76:77], v[2:3], v[2:3]
	v_pk_mov_b32 v[78:79], v[2:3], v[2:3]
	v_pk_mov_b32 v[80:81], v[2:3], v[2:3]
	v_pk_mov_b32 v[90:91], v[2:3], v[2:3]
	v_pk_mov_b32 v[92:93], v[2:3], v[2:3]
	v_pk_mov_b32 v[94:95], v[2:3], v[2:3]
	v_pk_mov_b32 v[96:97], v[2:3], v[2:3]
	v_pk_mov_b32 v[106:107], v[2:3], v[2:3]
	v_pk_mov_b32 v[108:109], v[2:3], v[2:3]
	v_pk_mov_b32 v[110:111], v[2:3], v[2:3]
	v_pk_mov_b32 v[112:113], v[2:3], v[2:3]
	v_pk_mov_b32 v[130:131], v[2:3], v[2:3]
	v_pk_mov_b32 v[132:133], v[2:3], v[2:3]
	v_pk_mov_b32 v[134:135], v[2:3], v[2:3]
	v_pk_mov_b32 v[136:137], v[2:3], v[2:3]
	v_add_u32_e32 v197, 0x10000, v230
	v_add_u32_e32 v201, 0x14000, v230
	v_add_u32_e32 v203, 0x18000, v230
	v_add_u32_e32 v216, 0x1c000, v230
	s_cmp_eq_u64 s[28:29], 0
	s_cbranch_scc0 .Lsp_skip_4
	s_setprio 1
.Lsp_skip_4:
.LBB0_990:
	s_add_i32 s67, s44, 2
	s_add_u32 s34, s30, 0x100
	s_addc_u32 s35, s31, 0
	s_cmp_eq_u32 s59, s44
	s_cselect_b32 s45, s13, s35
	s_cselect_b32 s44, s12, s34
	s_cselect_b32 s69, s15, s66
	s_cselect_b32 s68, s14, s65
	ds_read_b128 v[114:117], v197
	ds_read_b128 v[126:129], v197 offset:1024
	ds_read_b128 v[138:141], v197 offset:2048
	ds_read_b128 v[142:145], v197 offset:3072
	ds_read_b128 v[146:149], v201
	ds_read_b128 v[150:153], v201 offset:1024
	ds_read_b128 v[154:157], v201 offset:2048
	ds_read_b128 v[158:161], v201 offset:3072
	s_add_i32 m0, s52, 0xc000
	ds_read_b128 v[162:165], v235
	ds_read_b128 v[166:169], v235 offset:1024
	ds_read_b128 v[170:173], v235 offset:2048
	ds_read_b128 v[174:177], v235 offset:3072
	ds_read_b128 v[178:181], v235 offset:4096
	ds_read_b128 v[182:185], v235 offset:5120
	ds_read_b128 v[204:207], v235 offset:6144
	ds_read_b128 v[208:211], v235 offset:7168
	global_load_lds_dwordx4 v200, s[30:31]
	s_add_i32 m0, s52, 0xe000
	s_nop 0
	global_load_lds_dwordx4 v202, s[30:31]
	s_waitcnt vmcnt(8) lgkmcnt(0)
	s_barrier
	v_mfma_f32_16x16x32_bf16 v[134:137], v[114:117], v[162:165], v[134:137]
	v_mfma_f32_16x16x32_bf16 v[130:133], v[138:141], v[162:165], v[130:133]
	v_mfma_f32_16x16x32_bf16 v[110:113], v[114:117], v[170:173], v[110:113]
	v_mfma_f32_16x16x32_bf16 v[106:109], v[138:141], v[170:173], v[106:109]
	v_mfma_f32_16x16x32_bf16 v[94:97], v[114:117], v[178:181], v[94:97]
	v_mfma_f32_16x16x32_bf16 v[90:93], v[138:141], v[178:181], v[90:93]
	v_mfma_f32_16x16x32_bf16 v[78:81], v[114:117], v[204:207], v[78:81]
	v_mfma_f32_16x16x32_bf16 v[74:77], v[138:141], v[204:207], v[74:77]
	v_mfma_f32_16x16x32_bf16 v[134:137], v[126:129], v[166:169], v[134:137]
	v_mfma_f32_16x16x32_bf16 v[130:133], v[142:145], v[166:169], v[130:133]
	v_mfma_f32_16x16x32_bf16 v[110:113], v[126:129], v[174:177], v[110:113]
	v_mfma_f32_16x16x32_bf16 v[106:109], v[142:145], v[174:177], v[106:109]
	v_mfma_f32_16x16x32_bf16 v[94:97], v[126:129], v[182:185], v[94:97]
	v_mfma_f32_16x16x32_bf16 v[90:93], v[142:145], v[182:185], v[90:93]
	v_mfma_f32_16x16x32_bf16 v[78:81], v[126:129], v[208:211], v[78:81]
	v_mfma_f32_16x16x32_bf16 v[74:77], v[142:145], v[208:211], v[74:77]
	v_mfma_f32_16x16x32_bf16 v[122:125], v[146:149], v[162:165], v[122:125]
	v_mfma_f32_16x16x32_bf16 v[118:121], v[154:157], v[162:165], v[118:121]
	v_mfma_f32_16x16x32_bf16 v[102:105], v[146:149], v[170:173], v[102:105]
	v_mfma_f32_16x16x32_bf16 v[98:101], v[154:157], v[170:173], v[98:101]
	v_mfma_f32_16x16x32_bf16 v[86:89], v[146:149], v[178:181], v[86:89]
	v_mfma_f32_16x16x32_bf16 v[82:85], v[154:157], v[178:181], v[82:85]
	v_mfma_f32_16x16x32_bf16 v[70:73], v[146:149], v[204:207], v[70:73]
	v_mfma_f32_16x16x32_bf16 v[66:69], v[154:157], v[204:207], v[66:69]
	v_mfma_f32_16x16x32_bf16 v[122:125], v[150:153], v[166:169], v[122:125]
	v_mfma_f32_16x16x32_bf16 v[118:121], v[158:161], v[166:169], v[118:121]
	v_mfma_f32_16x16x32_bf16 v[102:105], v[150:153], v[174:177], v[102:105]
	v_mfma_f32_16x16x32_bf16 v[98:101], v[158:161], v[174:177], v[98:101]
	v_mfma_f32_16x16x32_bf16 v[86:89], v[150:153], v[182:185], v[86:89]
	v_mfma_f32_16x16x32_bf16 v[82:85], v[158:161], v[182:185], v[82:85]
	v_mfma_f32_16x16x32_bf16 v[70:73], v[150:153], v[208:211], v[70:73]
	v_mfma_f32_16x16x32_bf16 v[66:69], v[158:161], v[208:211], v[66:69]
	s_barrier
; #define PG8_STAGE(bufoff, gbase, voff) do { _Pragma("unroll") for (int _i = 0; _i < 2; ++_i) \
;         __builtin_amdgcn_global_load_lds((const unsigned*)((const char*)(gbase) + (voff)[_i]), (PG8_LAS unsigned*)(lds + (bufoff) + ldsw + _i * 8192), 16, 0, 0); } while (0)
; #define PG8_LDA(dst, b, h) do { _Pragma("unroll") for (int m = 0; m < 4; ++m) _Pragma("unroll") for (int k = 0; k < 2; ++k) dst[m][k] = *(const PG8_LAS bf16x8*)(lds + PG8_SA(b, h) + aoff + m * 2048 + k * 1024); } while (0)
; #define PG8_LDB(dst, b, h) do { _Pragma("unroll") for (int n = 0; n < 2; ++n) _Pragma("unroll") for (int k = 0; k < 2; ++k) dst[n][k] = *(const PG8_LAS bf16x8*)(lds + PG8_SB(b, h) + boff + n * 2048 + k * 1024); } while (0)
; #define PG8_MMA(ai, bj, At, Bt) do { __builtin_amdgcn_s_setprio(1); _Pragma("unroll") for (int m = 0; m < 4; ++m) _Pragma("unroll") for (int n = 0; n < 2; ++n) _Pragma("unroll") for (int k = 0; k < 2; ++k) \
;         acc[ai][bj][m][n] = __builtin_amdgcn_mfma_f32_16x16x32_bf16(Bt[n][k], At[m][k], acc[ai][bj][m][n], 0, 0, 0); __builtin_amdgcn_s_setprio(0); } while (0)
; #define PG8_WAIT_V(n) asm volatile("s_waitcnt vmcnt(" #n ")" ::: "memory")
; #define PG8_WAIT_L(n) asm volatile("s_waitcnt lgkmcnt(" #n ")" ::: "memory")
; #define PG8_BAR __builtin_amdgcn_s_barrier()
; #define PG8_SCHED __builtin_amdgcn_sched_barrier(0)
; template <class Epi, class Sched, bool ALIGN_EPI = false, bool SP2 = false>
; __device__ __forceinline__ void gemm_phase(PG8_LAS unsigned char* lds, const Gemm g, const Sched& S, const Epi& E, const int wv) {
;     ...
;             PG8_LDA(At, 0, 1); PG8_STAGE(PG8_SB(0, 0), b2, voffB); PG8_STAGE(PG8_SB(0, 1), b2 + hstepB, voffB); PG8_STAGE(PG8_SA(0, 0), a2, voffA);
;             PG8_WAIT_V(8); PG8_WAIT_L(0); PG8_BAR; PG8_MMA(1, 0, At, B0); PG8_MMA(1, 1, At, B1); PG8_BAR; PG8_SCHED;
;             PG8_LDB(B0, 1, 0); PG8_LDB(B1, 1, 1); PG8_SCHED; PG8_LDA(At, 1, 0); PG8_STAGE(PG8_SA(0, 1), a2 + hstepA, voffA);
;             PG8_WAIT_V(8); PG8_WAIT_L(0); PG8_BAR; PG8_MMA(0, 0, At, B0); PG8_MMA(0, 1, At, B1); PG8_BAR; PG8_SCHED;
	s_add_i32 s30, s47, 0x10000
	v_lshl_add_u64 v[190:191], s[68:69], 0, v[0:1]
	s_mov_b32 m0, s30
	ds_read_b128 v[162:165], v235 offset:16384
	ds_read_b128 v[166:169], v235 offset:17408
	ds_read_b128 v[170:173], v235 offset:18432
	ds_read_b128 v[174:177], v235 offset:19456
	ds_read_b128 v[178:181], v235 offset:20480
	ds_read_b128 v[182:185], v235 offset:21504
	ds_read_b128 v[204:207], v235 offset:22528
	ds_read_b128 v[208:211], v235 offset:23552
	global_load_lds_dwordx4 v[190:191], off
	s_add_i32 m0, s30, 0x2000
	s_add_u32 s30, s68, s2
	v_lshl_add_u64 v[192:193], s[68:69], 0, v[198:199]
	s_addc_u32 s31, s69, s3
	s_add_i32 s68, s47, 0x14000
	global_load_lds_dwordx4 v[192:193], off
	v_lshl_add_u64 v[212:213], s[30:31], 0, v[0:1]
	s_mov_b32 m0, s68
	v_lshl_add_u64 v[214:215], s[30:31], 0, v[198:199]
	global_load_lds_dwordx4 v[212:213], off
	s_add_i32 m0, s68, 0x2000
	global_load_lds_dwordx4 v[214:215], off
	s_mov_b32 m0, s52
	global_load_lds_dwordx4 v194, s[44:45]
	s_mov_b32 m0, s53
	s_nop 0
	global_load_lds_dwordx4 v196, s[44:45]
	s_waitcnt vmcnt(8) lgkmcnt(0)
	s_barrier
	v_mfma_f32_16x16x32_bf16 v[62:65], v[114:117], v[162:165], v[62:65]
	v_mfma_f32_16x16x32_bf16 v[58:61], v[138:141], v[162:165], v[58:61]
	v_mfma_f32_16x16x32_bf16 v[46:49], v[114:117], v[170:173], v[46:49]
	v_mfma_f32_16x16x32_bf16 v[42:45], v[138:141], v[170:173], v[42:45]
	v_mfma_f32_16x16x32_bf16 v[30:33], v[114:117], v[178:181], v[30:33]
	v_mfma_f32_16x16x32_bf16 v[26:29], v[138:141], v[178:181], v[26:29]
	v_mfma_f32_16x16x32_bf16 v[14:17], v[114:117], v[204:207], v[14:17]
	v_mfma_f32_16x16x32_bf16 v[10:13], v[138:141], v[204:207], v[10:13]
	v_mfma_f32_16x16x32_bf16 v[62:65], v[126:129], v[166:169], v[62:65]
	v_mfma_f32_16x16x32_bf16 v[58:61], v[142:145], v[166:169], v[58:61]
	v_mfma_f32_16x16x32_bf16 v[46:49], v[126:129], v[174:177], v[46:49]
	v_mfma_f32_16x16x32_bf16 v[42:45], v[142:145], v[174:177], v[42:45]
	v_mfma_f32_16x16x32_bf16 v[30:33], v[126:129], v[182:185], v[30:33]
	v_mfma_f32_16x16x32_bf16 v[26:29], v[142:145], v[182:185], v[26:29]
	v_mfma_f32_16x16x32_bf16 v[14:17], v[126:129], v[208:211], v[14:17]
	v_mfma_f32_16x16x32_bf16 v[10:13], v[142:145], v[208:211], v[10:13]
	v_mfma_f32_16x16x32_bf16 v[54:57], v[146:149], v[162:165], v[54:57]
	v_mfma_f32_16x16x32_bf16 v[50:53], v[154:157], v[162:165], v[50:53]
	v_mfma_f32_16x16x32_bf16 v[38:41], v[146:149], v[170:173], v[38:41]
	v_mfma_f32_16x16x32_bf16 v[34:37], v[154:157], v[170:173], v[34:37]
	v_mfma_f32_16x16x32_bf16 v[22:25], v[146:149], v[178:181], v[22:25]
	v_mfma_f32_16x16x32_bf16 v[18:21], v[154:157], v[178:181], v[18:21]
	v_mfma_f32_16x16x32_bf16 v[6:9], v[146:149], v[204:207], v[6:9]
	v_mfma_f32_16x16x32_bf16 v[2:5], v[154:157], v[204:207], v[2:5]
	v_mfma_f32_16x16x32_bf16 v[54:57], v[150:153], v[166:169], v[54:57]
	v_mfma_f32_16x16x32_bf16 v[50:53], v[158:161], v[166:169], v[50:53]
	v_mfma_f32_16x16x32_bf16 v[38:41], v[150:153], v[174:177], v[38:41]
	v_mfma_f32_16x16x32_bf16 v[34:37], v[158:161], v[174:177], v[34:37]
	v_mfma_f32_16x16x32_bf16 v[22:25], v[150:153], v[182:185], v[22:25]
	v_mfma_f32_16x16x32_bf16 v[18:21], v[158:161], v[182:185], v[18:21]
	v_mfma_f32_16x16x32_bf16 v[6:9], v[150:153], v[208:211], v[6:9]
	v_mfma_f32_16x16x32_bf16 v[2:5], v[158:161], v[208:211], v[2:5]
	s_barrier
	ds_read_b128 v[114:117], v203
	ds_read_b128 v[126:129], v203 offset:1024
	ds_read_b128 v[138:141], v203 offset:2048
	ds_read_b128 v[142:145], v203 offset:3072
	ds_read_b128 v[146:149], v216
	ds_read_b128 v[150:153], v216 offset:1024
	ds_read_b128 v[154:157], v216 offset:2048
	ds_read_b128 v[158:161], v216 offset:3072
	s_add_u32 s30, s44, 0x180000
	s_addc_u32 s31, s45, 0
	s_mov_b32 m0, s54
	ds_read_b128 v[162:165], v235 offset:32768
	ds_read_b128 v[166:169], v235 offset:33792
	ds_read_b128 v[170:173], v235 offset:34816
	ds_read_b128 v[174:177], v235 offset:35840
	ds_read_b128 v[178:181], v235 offset:36864
	ds_read_b128 v[182:185], v235 offset:37888
	ds_read_b128 v[204:207], v235 offset:38912
	ds_read_b128 v[208:211], v235 offset:39936
	global_load_lds_dwordx4 v194, s[30:31]
	s_mov_b32 m0, s55
	s_nop 0
	global_load_lds_dwordx4 v196, s[30:31]
	s_waitcnt vmcnt(8) lgkmcnt(0)
	s_barrier
; #define PG8_STAGE(bufoff, gbase, voff) do { _Pragma("unroll") for (int _i = 0; _i < 2; ++_i) \
;         __builtin_amdgcn_global_load_lds((const unsigned*)((const char*)(gbase) + (voff)[_i]), (PG8_LAS unsigned*)(lds + (bufoff) + ldsw + _i * 8192), 16, 0, 0); } while (0)
; #define PG8_LDA(dst, b, h) do { _Pragma("unroll") for (int m = 0; m < 4; ++m) _Pragma("unroll") for (int k = 0; k < 2; ++k) dst[m][k] = *(const PG8_LAS bf16x8*)(lds + PG8_SA(b, h) + aoff + m * 2048 + k * 1024); } while (0)
; #define PG8_MMA(ai, bj, At, Bt) do { __builtin_amdgcn_s_setprio(1); _Pragma("unroll") for (int m = 0; m < 4; ++m) _Pragma("unroll") for (int n = 0; n < 2; ++n) _Pragma("unroll") for (int k = 0; k < 2; ++k) \
;         acc[ai][bj][m][n] = __builtin_amdgcn_mfma_f32_16x16x32_bf16(Bt[n][k], At[m][k], acc[ai][bj][m][n], 0, 0, 0); __builtin_amdgcn_s_setprio(0); } while (0)
; #define PG8_WAIT_V(n) asm volatile("s_waitcnt vmcnt(" #n ")" ::: "memory")
; #define PG8_WAIT_L(n) asm volatile("s_waitcnt lgkmcnt(" #n ")" ::: "memory")
; #define PG8_BAR __builtin_amdgcn_s_barrier()
; #define PG8_SCHED __builtin_amdgcn_sched_barrier(0)
; template <class Epi, class Sched, bool ALIGN_EPI = false, bool SP2 = false>
; __device__ __forceinline__ void gemm_phase(PG8_LAS unsigned char* lds, const Gemm g, const Sched& S, const Epi& E, const int wv) {
;     ...
;         for (int t = 0; t < nt; t += 2) {
;     ...
;             PG8_WAIT_V(8); PG8_WAIT_L(0); PG8_BAR; PG8_MMA(0, 0, At, B0); PG8_MMA(0, 1, At, B1); PG8_BAR; PG8_SCHED;
;             PG8_LDA(At, 1, 1); PG8_STAGE(PG8_SB(1, 0), b3, voffB); PG8_STAGE(PG8_SB(1, 1), b3 + hstepB, voffB); PG8_STAGE(PG8_SA(1, 0), a3, voffA);
;             PG8_WAIT_V(8); PG8_WAIT_L(0); PG8_BAR; PG8_MMA(1, 0, At, B0); PG8_MMA(1, 1, At, B1); PG8_BAR; PG8_SCHED;
	v_mfma_f32_16x16x32_bf16 v[134:137], v[114:117], v[162:165], v[134:137]
	v_mfma_f32_16x16x32_bf16 v[130:133], v[138:141], v[162:165], v[130:133]
	v_mfma_f32_16x16x32_bf16 v[110:113], v[114:117], v[170:173], v[110:113]
	v_mfma_f32_16x16x32_bf16 v[106:109], v[138:141], v[170:173], v[106:109]
	v_mfma_f32_16x16x32_bf16 v[94:97], v[114:117], v[178:181], v[94:97]
	v_mfma_f32_16x16x32_bf16 v[90:93], v[138:141], v[178:181], v[90:93]
	v_mfma_f32_16x16x32_bf16 v[78:81], v[114:117], v[204:207], v[78:81]
	v_mfma_f32_16x16x32_bf16 v[74:77], v[138:141], v[204:207], v[74:77]
	v_mfma_f32_16x16x32_bf16 v[134:137], v[126:129], v[166:169], v[134:137]
	v_mfma_f32_16x16x32_bf16 v[130:133], v[142:145], v[166:169], v[130:133]
	v_mfma_f32_16x16x32_bf16 v[110:113], v[126:129], v[174:177], v[110:113]
	v_mfma_f32_16x16x32_bf16 v[106:109], v[142:145], v[174:177], v[106:109]
	v_mfma_f32_16x16x32_bf16 v[94:97], v[126:129], v[182:185], v[94:97]
	v_mfma_f32_16x16x32_bf16 v[90:93], v[142:145], v[182:185], v[90:93]
	v_mfma_f32_16x16x32_bf16 v[78:81], v[126:129], v[208:211], v[78:81]
	v_mfma_f32_16x16x32_bf16 v[74:77], v[142:145], v[208:211], v[74:77]
	v_mfma_f32_16x16x32_bf16 v[122:125], v[146:149], v[162:165], v[122:125]
	v_mfma_f32_16x16x32_bf16 v[118:121], v[154:157], v[162:165], v[118:121]
	v_mfma_f32_16x16x32_bf16 v[102:105], v[146:149], v[170:173], v[102:105]
	v_mfma_f32_16x16x32_bf16 v[98:101], v[154:157], v[170:173], v[98:101]
	v_mfma_f32_16x16x32_bf16 v[86:89], v[146:149], v[178:181], v[86:89]
	v_mfma_f32_16x16x32_bf16 v[82:85], v[154:157], v[178:181], v[82:85]
	v_mfma_f32_16x16x32_bf16 v[70:73], v[146:149], v[204:207], v[70:73]
	v_mfma_f32_16x16x32_bf16 v[66:69], v[154:157], v[204:207], v[66:69]
	v_mfma_f32_16x16x32_bf16 v[122:125], v[150:153], v[166:169], v[122:125]
	v_mfma_f32_16x16x32_bf16 v[118:121], v[158:161], v[166:169], v[118:121]
	v_mfma_f32_16x16x32_bf16 v[102:105], v[150:153], v[174:177], v[102:105]
	v_mfma_f32_16x16x32_bf16 v[98:101], v[158:161], v[174:177], v[98:101]
	v_mfma_f32_16x16x32_bf16 v[86:89], v[150:153], v[182:185], v[86:89]
	v_mfma_f32_16x16x32_bf16 v[82:85], v[158:161], v[182:185], v[82:85]
	v_mfma_f32_16x16x32_bf16 v[70:73], v[150:153], v[208:211], v[70:73]
	v_mfma_f32_16x16x32_bf16 v[66:69], v[158:161], v[208:211], v[66:69]
	s_barrier
	s_add_i32 s30, s47, 0x18000
	s_add_i32 m0, s30, 0xffffff80
	ds_read_b128 v[162:165], v235 offset:49152
	ds_read_b128 v[166:169], v235 offset:50176
	ds_read_b128 v[170:173], v235 offset:51200
	ds_read_b128 v[174:177], v235 offset:52224
	ds_read_b128 v[178:181], v235 offset:53248
	ds_read_b128 v[182:185], v235 offset:54272
	ds_read_b128 v[204:207], v235 offset:55296
	ds_read_b128 v[208:211], v235 offset:56320
	global_load_lds_dwordx4 v[190:191], off offset:128
	s_add_i32 m0, s30, 0x1f80
	s_add_i32 s30, s47, 0x1c000
	global_load_lds_dwordx4 v[192:193], off offset:128
	s_add_i32 m0, s30, 0xffffff80
	s_nop 0
	global_load_lds_dwordx4 v[212:213], off offset:128
	s_add_i32 m0, s30, 0x1f80
	s_nop 0
	global_load_lds_dwordx4 v[214:215], off offset:128
	s_add_i32 m0, s57, 0xffffff80
	s_nop 0
	global_load_lds_dwordx4 v194, s[44:45] offset:128
	s_add_i32 m0, s58, 0xffffff80
	s_nop 0
	global_load_lds_dwordx4 v196, s[44:45] offset:128
	s_waitcnt vmcnt(8) lgkmcnt(0)
	s_barrier
	v_mfma_f32_16x16x32_bf16 v[62:65], v[114:117], v[162:165], v[62:65]
	v_mfma_f32_16x16x32_bf16 v[58:61], v[138:141], v[162:165], v[58:61]
	v_mfma_f32_16x16x32_bf16 v[46:49], v[114:117], v[170:173], v[46:49]
	v_mfma_f32_16x16x32_bf16 v[42:45], v[138:141], v[170:173], v[42:45]
	v_mfma_f32_16x16x32_bf16 v[30:33], v[114:117], v[178:181], v[30:33]
	v_mfma_f32_16x16x32_bf16 v[26:29], v[138:141], v[178:181], v[26:29]
	v_mfma_f32_16x16x32_bf16 v[14:17], v[114:117], v[204:207], v[14:17]
	v_mfma_f32_16x16x32_bf16 v[10:13], v[138:141], v[204:207], v[10:13]
	v_mfma_f32_16x16x32_bf16 v[62:65], v[126:129], v[166:169], v[62:65]
	v_mfma_f32_16x16x32_bf16 v[58:61], v[142:145], v[166:169], v[58:61]
	v_mfma_f32_16x16x32_bf16 v[46:49], v[126:129], v[174:177], v[46:49]
	v_mfma_f32_16x16x32_bf16 v[42:45], v[142:145], v[174:177], v[42:45]
	v_mfma_f32_16x16x32_bf16 v[30:33], v[126:129], v[182:185], v[30:33]
	v_mfma_f32_16x16x32_bf16 v[26:29], v[142:145], v[182:185], v[26:29]
	v_mfma_f32_16x16x32_bf16 v[14:17], v[126:129], v[208:211], v[14:17]
	v_mfma_f32_16x16x32_bf16 v[10:13], v[142:145], v[208:211], v[10:13]
	v_mfma_f32_16x16x32_bf16 v[54:57], v[146:149], v[162:165], v[54:57]
	v_mfma_f32_16x16x32_bf16 v[50:53], v[154:157], v[162:165], v[50:53]
	v_mfma_f32_16x16x32_bf16 v[38:41], v[146:149], v[170:173], v[38:41]
	v_mfma_f32_16x16x32_bf16 v[34:37], v[154:157], v[170:173], v[34:37]
	v_mfma_f32_16x16x32_bf16 v[22:25], v[146:149], v[178:181], v[22:25]
	v_mfma_f32_16x16x32_bf16 v[18:21], v[154:157], v[178:181], v[18:21]
	v_mfma_f32_16x16x32_bf16 v[6:9], v[146:149], v[204:207], v[6:9]
	v_mfma_f32_16x16x32_bf16 v[2:5], v[154:157], v[204:207], v[2:5]
	v_mfma_f32_16x16x32_bf16 v[54:57], v[150:153], v[166:169], v[54:57]
	v_mfma_f32_16x16x32_bf16 v[50:53], v[158:161], v[166:169], v[50:53]
	v_mfma_f32_16x16x32_bf16 v[38:41], v[150:153], v[174:177], v[38:41]
	v_mfma_f32_16x16x32_bf16 v[34:37], v[158:161], v[174:177], v[34:37]
	v_mfma_f32_16x16x32_bf16 v[22:25], v[150:153], v[182:185], v[22:25]
	v_mfma_f32_16x16x32_bf16 v[18:21], v[158:161], v[182:185], v[18:21]
	v_mfma_f32_16x16x32_bf16 v[6:9], v[150:153], v[208:211], v[6:9]
	v_mfma_f32_16x16x32_bf16 v[2:5], v[158:161], v[208:211], v[2:5]
	s_barrier
	s_add_u32 s65, s65, 0x100
	s_addc_u32 s66, s66, 0
	s_cmp_ge_i32 s67, s56
	s_mov_b64 s[30:31], s[34:35]
	s_mov_b32 s44, s67
	s_cbranch_scc0 .LBB0_990
	s_setprio 0
	s_movk_i32 s68, 0x4000
	s_movk_i32 s69, 0x6000
	s_mov_b32 s70, 0x18000
	s_mov_b32 s71, 0x3f317217
	v_readlane_b32 s67, v255, 30
	s_and_b64 vcc, exec, s[28:29]
	s_cbranch_vccz .LBB0_966

;     __host__ __device__ bool next(int i, Unit& u) const { const int P = (i >> 1) * G + c; if (P >= 256) return false; u.pm = P >> 3; u.pn = (P & 7) + 8 * (i & 1); return true; }
; template <class Epi, class Sched, bool ALIGN_EPI = false, bool SP2 = false>
; __device__ __forceinline__ void gemm_phase(PG8_LAS unsigned char* lds, const Gemm g, const Sched& S, const Epi& E, const int wv) {
;     ...
;         const bool has_next = S.next(ui + 1, nxt);
;         const char* nA = has_next ? (const char*)g.A + (size_t)nxt.pm * tstepA + (g.amod ? (size_t)(nxt.pn % g.amod) * K * 2 : (size_t)0) : cA; const char* nB = has_next ? (const char*)g.Bt + (size_t)nxt.pn * tstepB : cB;
;         for (int t = 0; t < nt; t += 2) {
;             const bool last = (t == nt - 2);
;             const char* a1 = cA + (size_t)(t + 1) * kstep;
;             const char* a2 = last ? nA : cA + (size_t)(t + 2) * kstep; const char* b2 = last ? nB : cB + (size_t)(t + 2) * kstep;
;             const char* a3 = a2 + kstep; const char* b3 = b2 + kstep;
;     ...
; #pragma unroll
;         for (int a = 0; a < 2; ++a)
; #pragma unroll
;             for (int b = 0; b < 2; ++b)
; #pragma unroll
;                 for (int m = 0; m < 4; ++m)
; #pragma unroll
;                     for (int n = 0; n < 2; ++n) acc[a][b][m][n] = (f32x4){0.f, 0.f, 0.f, 0.f};
;         cur = nxt; cA = nA; cB = nB; ++ui;
.LBB0_1072:
	s_ashr_i32 s17, s16, 31
	s_lshl_b64 s[24:25], s[16:17], 20
	s_add_u32 s24, s43, s24
	v_mov_b32_e32 v133, 0
	s_addc_u32 s25, s44, s25
	s_andn2_b64 vcc, exec, s[12:13]
	v_mov_b32_e32 v132, v133
	v_pk_mov_b32 v[130:131], v[132:133], v[132:133]
	v_pk_mov_b32 v[128:129], v[132:133], v[132:133]
	v_pk_mov_b32 v[126:127], v[132:133], v[132:133]
	v_pk_mov_b32 v[116:117], v[132:133], v[132:133]
	v_pk_mov_b32 v[114:115], v[132:133], v[132:133]
	v_pk_mov_b32 v[112:113], v[132:133], v[132:133]
	v_pk_mov_b32 v[110:111], v[132:133], v[132:133]
	v_pk_mov_b32 v[100:101], v[132:133], v[132:133]
	v_pk_mov_b32 v[98:99], v[132:133], v[132:133]
	s_nop 0
	v_pk_mov_b32 v[96:97], v[132:133], v[132:133]
	v_pk_mov_b32 v[94:95], v[132:133], v[132:133]
	v_pk_mov_b32 v[84:85], v[132:133], v[132:133]
	v_pk_mov_b32 v[82:83], v[132:133], v[132:133]
	v_pk_mov_b32 v[80:81], v[132:133], v[132:133]
	v_pk_mov_b32 v[78:79], v[132:133], v[132:133]
	v_pk_mov_b32 v[124:125], v[132:133], v[132:133]
	v_pk_mov_b32 v[122:123], v[132:133], v[132:133]
	v_pk_mov_b32 v[120:121], v[132:133], v[132:133]
	v_pk_mov_b32 v[118:119], v[132:133], v[132:133]
	v_pk_mov_b32 v[108:109], v[132:133], v[132:133]
	v_pk_mov_b32 v[106:107], v[132:133], v[132:133]
	v_pk_mov_b32 v[104:105], v[132:133], v[132:133]
	v_pk_mov_b32 v[102:103], v[132:133], v[132:133]
	v_pk_mov_b32 v[92:93], v[132:133], v[132:133]
	v_pk_mov_b32 v[90:91], v[132:133], v[132:133]
	v_pk_mov_b32 v[88:89], v[132:133], v[132:133]
	v_pk_mov_b32 v[86:87], v[132:133], v[132:133]
	v_pk_mov_b32 v[76:77], v[132:133], v[132:133]
	v_pk_mov_b32 v[74:75], v[132:133], v[132:133]
	v_pk_mov_b32 v[72:73], v[132:133], v[132:133]
	v_pk_mov_b32 v[70:71], v[132:133], v[132:133]
	v_pk_mov_b32 v[68:69], v[132:133], v[132:133]
	v_pk_mov_b32 v[66:67], v[132:133], v[132:133]
	v_pk_mov_b32 v[64:65], v[132:133], v[132:133]
	v_pk_mov_b32 v[62:63], v[132:133], v[132:133]
	v_pk_mov_b32 v[52:53], v[132:133], v[132:133]
	v_pk_mov_b32 v[50:51], v[132:133], v[132:133]
	v_pk_mov_b32 v[48:49], v[132:133], v[132:133]
	v_pk_mov_b32 v[46:47], v[132:133], v[132:133]
	v_pk_mov_b32 v[36:37], v[132:133], v[132:133]
	v_pk_mov_b32 v[34:35], v[132:133], v[132:133]
	v_pk_mov_b32 v[32:33], v[132:133], v[132:133]
	v_pk_mov_b32 v[30:31], v[132:133], v[132:133]
	v_pk_mov_b32 v[20:21], v[132:133], v[132:133]
	v_pk_mov_b32 v[18:19], v[132:133], v[132:133]
	v_pk_mov_b32 v[16:17], v[132:133], v[132:133]
	v_pk_mov_b32 v[14:15], v[132:133], v[132:133]
	v_pk_mov_b32 v[60:61], v[132:133], v[132:133]
	v_pk_mov_b32 v[58:59], v[132:133], v[132:133]
	v_pk_mov_b32 v[56:57], v[132:133], v[132:133]
	v_pk_mov_b32 v[54:55], v[132:133], v[132:133]
	v_pk_mov_b32 v[44:45], v[132:133], v[132:133]
	v_pk_mov_b32 v[42:43], v[132:133], v[132:133]
	v_pk_mov_b32 v[40:41], v[132:133], v[132:133]
	v_pk_mov_b32 v[38:39], v[132:133], v[132:133]
	v_pk_mov_b32 v[28:29], v[132:133], v[132:133]
	v_pk_mov_b32 v[26:27], v[132:133], v[132:133]
	v_pk_mov_b32 v[24:25], v[132:133], v[132:133]
	v_pk_mov_b32 v[22:23], v[132:133], v[132:133]
	v_pk_mov_b32 v[12:13], v[132:133], v[132:133]
	v_pk_mov_b32 v[10:11], v[132:133], v[132:133]
	v_pk_mov_b32 v[8:9], v[132:133], v[132:133]
	v_pk_mov_b32 v[6:7], v[132:133], v[132:133]
	s_cbranch_vccnz .LBB0_1076
	s_and_b64 s[40:41], s[40:41], exec
	s_cselect_b32 s17, s25, s29
	s_cselect_b32 s40, s24, s28
	s_add_u32 s28, s28, 0x80080
	s_addc_u32 s29, s29, 0
	s_add_u32 s41, s30, 0x100
	v_mov_b32_e32 v6, 0
	s_addc_u32 s62, s31, 0
	s_mov_b32 s30, 0
	v_mov_b32_e32 v7, v6
	v_pk_mov_b32 v[8:9], v[6:7], v[6:7]
	v_pk_mov_b32 v[10:11], v[6:7], v[6:7]
	v_pk_mov_b32 v[12:13], v[6:7], v[6:7]
	v_pk_mov_b32 v[22:23], v[6:7], v[6:7]
	v_pk_mov_b32 v[24:25], v[6:7], v[6:7]
	v_pk_mov_b32 v[26:27], v[6:7], v[6:7]
	v_pk_mov_b32 v[28:29], v[6:7], v[6:7]
	v_pk_mov_b32 v[38:39], v[6:7], v[6:7]
	v_pk_mov_b32 v[40:41], v[6:7], v[6:7]
	v_pk_mov_b32 v[42:43], v[6:7], v[6:7]
	v_pk_mov_b32 v[44:45], v[6:7], v[6:7]
	v_pk_mov_b32 v[54:55], v[6:7], v[6:7]
	v_pk_mov_b32 v[56:57], v[6:7], v[6:7]
	v_pk_mov_b32 v[58:59], v[6:7], v[6:7]
	v_pk_mov_b32 v[60:61], v[6:7], v[6:7]
	v_pk_mov_b32 v[14:15], v[6:7], v[6:7]
	v_pk_mov_b32 v[16:17], v[6:7], v[6:7]
	v_pk_mov_b32 v[18:19], v[6:7], v[6:7]
	v_pk_mov_b32 v[20:21], v[6:7], v[6:7]
	v_pk_mov_b32 v[30:31], v[6:7], v[6:7]
	v_pk_mov_b32 v[32:33], v[6:7], v[6:7]
	v_pk_mov_b32 v[34:35], v[6:7], v[6:7]
	v_pk_mov_b32 v[36:37], v[6:7], v[6:7]
	v_pk_mov_b32 v[46:47], v[6:7], v[6:7]
	v_pk_mov_b32 v[48:49], v[6:7], v[6:7]
	v_pk_mov_b32 v[50:51], v[6:7], v[6:7]
	v_pk_mov_b32 v[52:53], v[6:7], v[6:7]
	v_pk_mov_b32 v[62:63], v[6:7], v[6:7]
	v_pk_mov_b32 v[64:65], v[6:7], v[6:7]
	v_pk_mov_b32 v[66:67], v[6:7], v[6:7]
	v_pk_mov_b32 v[68:69], v[6:7], v[6:7]
	v_pk_mov_b32 v[70:71], v[6:7], v[6:7]
	v_pk_mov_b32 v[72:73], v[6:7], v[6:7]
	v_pk_mov_b32 v[74:75], v[6:7], v[6:7]
	v_pk_mov_b32 v[76:77], v[6:7], v[6:7]
	v_pk_mov_b32 v[86:87], v[6:7], v[6:7]
	v_pk_mov_b32 v[88:89], v[6:7], v[6:7]
	v_pk_mov_b32 v[90:91], v[6:7], v[6:7]
	v_pk_mov_b32 v[92:93], v[6:7], v[6:7]
	v_pk_mov_b32 v[102:103], v[6:7], v[6:7]
	v_pk_mov_b32 v[104:105], v[6:7], v[6:7]
	v_pk_mov_b32 v[106:107], v[6:7], v[6:7]
	v_pk_mov_b32 v[108:109], v[6:7], v[6:7]
	v_pk_mov_b32 v[118:119], v[6:7], v[6:7]
	v_pk_mov_b32 v[120:121], v[6:7], v[6:7]
	v_pk_mov_b32 v[122:123], v[6:7], v[6:7]
	v_pk_mov_b32 v[124:125], v[6:7], v[6:7]
	v_pk_mov_b32 v[78:79], v[6:7], v[6:7]
	v_pk_mov_b32 v[80:81], v[6:7], v[6:7]
	v_pk_mov_b32 v[82:83], v[6:7], v[6:7]
	v_pk_mov_b32 v[84:85], v[6:7], v[6:7]
	v_pk_mov_b32 v[94:95], v[6:7], v[6:7]
	v_pk_mov_b32 v[96:97], v[6:7], v[6:7]
	v_pk_mov_b32 v[98:99], v[6:7], v[6:7]
	v_pk_mov_b32 v[100:101], v[6:7], v[6:7]
	v_pk_mov_b32 v[110:111], v[6:7], v[6:7]
	v_pk_mov_b32 v[112:113], v[6:7], v[6:7]
	v_pk_mov_b32 v[114:115], v[6:7], v[6:7]
	v_pk_mov_b32 v[116:117], v[6:7], v[6:7]
	v_pk_mov_b32 v[126:127], v[6:7], v[6:7]
	v_pk_mov_b32 v[128:129], v[6:7], v[6:7]
	v_pk_mov_b32 v[130:131], v[6:7], v[6:7]
	v_pk_mov_b32 v[132:133], v[6:7], v[6:7]
	v_add_u32_e32 v147, 0x10000, v157
	v_add_u32_e32 v149, 0x14000, v157
	v_add_u32_e32 v152, 0x18000, v157
	v_add_u32_e32 v154, 0x1c000, v157
	v_add_u32_e32 v0, 0x80000, v140
	v_add_u32_e32 v156, 0x80000, v136
	s_cmp_eq_u64 s[14:15], 0
	s_cbranch_scc0 .Lsp_skip_5
	s_setprio 1
; #define PG8_STAGE(bufoff, gbase, voff) do { _Pragma("unroll") for (int _i = 0; _i < 2; ++_i) \
;         __builtin_amdgcn_global_load_lds((const unsigned*)((const char*)(gbase) + (voff)[_i]), (PG8_LAS unsigned*)(lds + (bufoff) + ldsw + _i * 8192), 16, 0, 0); } while (0)
; #define PG8_LDA(dst, b, h) do { _Pragma("unroll") for (int m = 0; m < 4; ++m) _Pragma("unroll") for (int k = 0; k < 2; ++k) dst[m][k] = *(const PG8_LAS bf16x8*)(lds + PG8_SA(b, h) + aoff + m * 2048 + k * 1024); } while (0)
; #define PG8_LDB(dst, b, h) do { _Pragma("unroll") for (int n = 0; n < 2; ++n) _Pragma("unroll") for (int k = 0; k < 2; ++k) dst[n][k] = *(const PG8_LAS bf16x8*)(lds + PG8_SB(b, h) + boff + n * 2048 + k * 1024); } while (0)
; #define PG8_MMA(ai, bj, At, Bt) do { __builtin_amdgcn_s_setprio(1); _Pragma("unroll") for (int m = 0; m < 4; ++m) _Pragma("unroll") for (int n = 0; n < 2; ++n) _Pragma("unroll") for (int k = 0; k < 2; ++k) \
;         acc[ai][bj][m][n] = __builtin_amdgcn_mfma_f32_16x16x32_bf16(Bt[n][k], At[m][k], acc[ai][bj][m][n], 0, 0, 0); __builtin_amdgcn_s_setprio(0); } while (0)
; #define PG8_WAIT_V(n) asm volatile("s_waitcnt vmcnt(" #n ")" ::: "memory")
; #define PG8_WAIT_L(n) asm volatile("s_waitcnt lgkmcnt(" #n ")" ::: "memory")
; template <class Epi, class Sched, bool ALIGN_EPI = false, bool SP2 = false>
; __device__ __forceinline__ void gemm_phase(PG8_LAS unsigned char* lds, const Gemm g, const Sched& S, const Epi& E, const int wv) {
;     ...
;             const bool last = (t == nt - 2);
;             const char* a1 = cA + (size_t)(t + 1) * kstep;
;             const char* a2 = last ? nA : cA + (size_t)(t + 2) * kstep; const char* b2 = last ? nB : cB + (size_t)(t + 2) * kstep;
;             const char* a3 = a2 + kstep; const char* b3 = b2 + kstep;
;             if (last && has_next) S.a_ready(nxt);
;             if constexpr (SP2) {
;             PG8_LDB(B0, 0, 0); PG8_LDB(B1, 0, 1); PG8_SCHED; PG8_LDA(At, 0, 0); PG8_STAGE(PG8_SA(1, 1), a1 + hstepA, voffA);
;             PG8_WAIT_V(8); PG8_WAIT_L(0); PG8_BAR; PG8_MMA(0, 0, At, B0); PG8_MMA(0, 1, At, B1); PG8_BAR; PG8_SCHED;
;             PG8_LDA(At, 0, 1); PG8_STAGE(PG8_SB(0, 0), b2, voffB); PG8_STAGE(PG8_SB(0, 1), b2 + hstepB, voffB); PG8_STAGE(PG8_SA(0, 0), a2, voffA);
;             PG8_WAIT_V(8); PG8_WAIT_L(0); PG8_BAR; PG8_MMA(1, 0, At, B0); PG8_MMA(1, 1, At, B1); PG8_BAR; PG8_SCHED;
.Lsp_skip_5:
.LBB0_1074:
	s_add_i32 s63, s30, 2
	s_add_u32 s64, s28, 0xfff80080
	s_addc_u32 s31, s29, -1
	s_cmp_eq_u32 s57, s30
	s_cselect_b32 s31, s17, s31
	s_cselect_b32 s30, s40, s64
	s_cselect_b32 s65, s19, s62
	s_cselect_b32 s64, s18, s41
	ds_read_b128 v[164:167], v147
	ds_read_b128 v[168:171], v147 offset:1024
	ds_read_b128 v[172:175], v147 offset:2048
	ds_read_b128 v[176:179], v147 offset:3072
	ds_read_b128 v[180:183], v149
	ds_read_b128 v[194:197], v149 offset:1024
	ds_read_b128 v[198:201], v149 offset:2048
	ds_read_b128 v[202:205], v149 offset:3072
	s_add_i32 m0, s47, 0xc000
	ds_read_b128 v[206:209], v163
	ds_read_b128 v[210:213], v163 offset:1024
	ds_read_b128 v[214:217], v163 offset:2048
	ds_read_b128 v[228:231], v163 offset:3072
	ds_read_b128 v[232:235], v163 offset:4096
	ds_read_b128 v[236:239], v163 offset:5120
	ds_read_b128 v[240:243], v163 offset:6144
	ds_read_b128 v[244:247], v163 offset:7168
	global_load_lds_dwordx4 v146, s[28:29]
	s_add_i32 m0, s47, 0xe000
	s_nop 0
	global_load_lds_dwordx4 v148, s[28:29]
	s_waitcnt vmcnt(8) lgkmcnt(0)
	s_barrier
	v_mfma_f32_16x16x32_bf16 v[130:133], v[164:167], v[206:209], v[130:133]
	v_mfma_f32_16x16x32_bf16 v[126:129], v[172:175], v[206:209], v[126:129]
	v_mfma_f32_16x16x32_bf16 v[114:117], v[164:167], v[214:217], v[114:117]
	v_mfma_f32_16x16x32_bf16 v[110:113], v[172:175], v[214:217], v[110:113]
	v_mfma_f32_16x16x32_bf16 v[98:101], v[164:167], v[232:235], v[98:101]
	v_mfma_f32_16x16x32_bf16 v[94:97], v[172:175], v[232:235], v[94:97]
	v_mfma_f32_16x16x32_bf16 v[82:85], v[164:167], v[240:243], v[82:85]
	v_mfma_f32_16x16x32_bf16 v[78:81], v[172:175], v[240:243], v[78:81]
	v_mfma_f32_16x16x32_bf16 v[130:133], v[168:171], v[210:213], v[130:133]
	v_mfma_f32_16x16x32_bf16 v[126:129], v[176:179], v[210:213], v[126:129]
	v_mfma_f32_16x16x32_bf16 v[114:117], v[168:171], v[228:231], v[114:117]
	v_mfma_f32_16x16x32_bf16 v[110:113], v[176:179], v[228:231], v[110:113]
	v_mfma_f32_16x16x32_bf16 v[98:101], v[168:171], v[236:239], v[98:101]
	v_mfma_f32_16x16x32_bf16 v[94:97], v[176:179], v[236:239], v[94:97]
	v_mfma_f32_16x16x32_bf16 v[82:85], v[168:171], v[244:247], v[82:85]
	v_mfma_f32_16x16x32_bf16 v[78:81], v[176:179], v[244:247], v[78:81]
	v_mfma_f32_16x16x32_bf16 v[122:125], v[180:183], v[206:209], v[122:125]
	v_mfma_f32_16x16x32_bf16 v[118:121], v[198:201], v[206:209], v[118:121]
	v_mfma_f32_16x16x32_bf16 v[106:109], v[180:183], v[214:217], v[106:109]
	v_mfma_f32_16x16x32_bf16 v[102:105], v[198:201], v[214:217], v[102:105]
	v_mfma_f32_16x16x32_bf16 v[90:93], v[180:183], v[232:235], v[90:93]
	v_mfma_f32_16x16x32_bf16 v[86:89], v[198:201], v[232:235], v[86:89]
	v_mfma_f32_16x16x32_bf16 v[74:77], v[180:183], v[240:243], v[74:77]
	v_mfma_f32_16x16x32_bf16 v[70:73], v[198:201], v[240:243], v[70:73]
	v_mfma_f32_16x16x32_bf16 v[122:125], v[194:197], v[210:213], v[122:125]
	v_mfma_f32_16x16x32_bf16 v[118:121], v[202:205], v[210:213], v[118:121]
	v_mfma_f32_16x16x32_bf16 v[106:109], v[194:197], v[228:231], v[106:109]
	v_mfma_f32_16x16x32_bf16 v[102:105], v[202:205], v[228:231], v[102:105]
	v_mfma_f32_16x16x32_bf16 v[90:93], v[194:197], v[236:239], v[90:93]
	v_mfma_f32_16x16x32_bf16 v[86:89], v[202:205], v[236:239], v[86:89]
	v_mfma_f32_16x16x32_bf16 v[74:77], v[194:197], v[244:247], v[74:77]
	v_mfma_f32_16x16x32_bf16 v[70:73], v[202:205], v[244:247], v[70:73]
	s_barrier
	s_add_i32 s66, s45, 0x10000
	v_lshl_add_u64 v[150:151], s[64:65], 0, v[138:139]
	s_mov_b32 m0, s66
	ds_read_b128 v[206:209], v163 offset:16384
	ds_read_b128 v[210:213], v163 offset:17408
	ds_read_b128 v[214:217], v163 offset:18432
	ds_read_b128 v[228:231], v163 offset:19456
	ds_read_b128 v[232:235], v163 offset:20480
	ds_read_b128 v[236:239], v163 offset:21504
	ds_read_b128 v[240:243], v163 offset:22528
	ds_read_b128 v[244:247], v163 offset:23552
	global_load_lds_dwordx4 v[150:151], off
	s_add_i32 m0, s66, 0x2000
	v_lshl_add_u64 v[184:185], s[64:65], 0, v[134:135]
	s_add_u32 s64, s64, s0
	s_addc_u32 s65, s65, s1
	s_add_i32 s66, s45, 0x14000
	global_load_lds_dwordx4 v[184:185], off
	s_mov_b32 m0, s66
	global_load_lds_dwordx4 v138, s[64:65]
	s_add_i32 m0, s66, 0x2000
	global_load_lds_dwordx4 v134, s[64:65]
	s_mov_b32 m0, s47
	global_load_lds_dwordx4 v140, s[30:31]
	s_mov_b32 m0, s48
	s_nop 0
	global_load_lds_dwordx4 v136, s[30:31]
	s_waitcnt vmcnt(8) lgkmcnt(0)
	s_barrier
	v_mfma_f32_16x16x32_bf16 v[66:69], v[164:167], v[206:209], v[66:69]
	v_mfma_f32_16x16x32_bf16 v[62:65], v[172:175], v[206:209], v[62:65]
	v_mfma_f32_16x16x32_bf16 v[50:53], v[164:167], v[214:217], v[50:53]
	v_mfma_f32_16x16x32_bf16 v[46:49], v[172:175], v[214:217], v[46:49]
	v_mfma_f32_16x16x32_bf16 v[34:37], v[164:167], v[232:235], v[34:37]
	v_mfma_f32_16x16x32_bf16 v[30:33], v[172:175], v[232:235], v[30:33]
	v_mfma_f32_16x16x32_bf16 v[18:21], v[164:167], v[240:243], v[18:21]
	v_mfma_f32_16x16x32_bf16 v[14:17], v[172:175], v[240:243], v[14:17]
	v_mfma_f32_16x16x32_bf16 v[66:69], v[168:171], v[210:213], v[66:69]
	v_mfma_f32_16x16x32_bf16 v[62:65], v[176:179], v[210:213], v[62:65]
	v_mfma_f32_16x16x32_bf16 v[50:53], v[168:171], v[228:231], v[50:53]
	v_mfma_f32_16x16x32_bf16 v[46:49], v[176:179], v[228:231], v[46:49]
	v_mfma_f32_16x16x32_bf16 v[34:37], v[168:171], v[236:239], v[34:37]
	v_mfma_f32_16x16x32_bf16 v[30:33], v[176:179], v[236:239], v[30:33]
	v_mfma_f32_16x16x32_bf16 v[18:21], v[168:171], v[244:247], v[18:21]
	v_mfma_f32_16x16x32_bf16 v[14:17], v[176:179], v[244:247], v[14:17]
	v_mfma_f32_16x16x32_bf16 v[58:61], v[180:183], v[206:209], v[58:61]
	v_mfma_f32_16x16x32_bf16 v[54:57], v[198:201], v[206:209], v[54:57]
	v_mfma_f32_16x16x32_bf16 v[42:45], v[180:183], v[214:217], v[42:45]
	v_mfma_f32_16x16x32_bf16 v[38:41], v[198:201], v[214:217], v[38:41]
	v_mfma_f32_16x16x32_bf16 v[26:29], v[180:183], v[232:235], v[26:29]
	v_mfma_f32_16x16x32_bf16 v[22:25], v[198:201], v[232:235], v[22:25]
	v_mfma_f32_16x16x32_bf16 v[10:13], v[180:183], v[240:243], v[10:13]
	v_mfma_f32_16x16x32_bf16 v[6:9], v[198:201], v[240:243], v[6:9]
	v_mfma_f32_16x16x32_bf16 v[58:61], v[194:197], v[210:213], v[58:61]
	v_mfma_f32_16x16x32_bf16 v[54:57], v[202:205], v[210:213], v[54:57]
	v_mfma_f32_16x16x32_bf16 v[42:45], v[194:197], v[228:231], v[42:45]
	v_mfma_f32_16x16x32_bf16 v[38:41], v[202:205], v[228:231], v[38:41]
	v_mfma_f32_16x16x32_bf16 v[26:29], v[194:197], v[236:239], v[26:29]
	v_mfma_f32_16x16x32_bf16 v[22:25], v[202:205], v[236:239], v[22:25]
	v_mfma_f32_16x16x32_bf16 v[10:13], v[194:197], v[244:247], v[10:13]
	v_mfma_f32_16x16x32_bf16 v[6:9], v[202:205], v[244:247], v[6:9]
	s_barrier
; #define PG8_STAGE(bufoff, gbase, voff) do { _Pragma("unroll") for (int _i = 0; _i < 2; ++_i) \
;         __builtin_amdgcn_global_load_lds((const unsigned*)((const char*)(gbase) + (voff)[_i]), (PG8_LAS unsigned*)(lds + (bufoff) + ldsw + _i * 8192), 16, 0, 0); } while (0)
; #define PG8_LDA(dst, b, h) do { _Pragma("unroll") for (int m = 0; m < 4; ++m) _Pragma("unroll") for (int k = 0; k < 2; ++k) dst[m][k] = *(const PG8_LAS bf16x8*)(lds + PG8_SA(b, h) + aoff + m * 2048 + k * 1024); } while (0)
; #define PG8_LDB(dst, b, h) do { _Pragma("unroll") for (int n = 0; n < 2; ++n) _Pragma("unroll") for (int k = 0; k < 2; ++k) dst[n][k] = *(const PG8_LAS bf16x8*)(lds + PG8_SB(b, h) + boff + n * 2048 + k * 1024); } while (0)
; #define PG8_MMA(ai, bj, At, Bt) do { __builtin_amdgcn_s_setprio(1); _Pragma("unroll") for (int m = 0; m < 4; ++m) _Pragma("unroll") for (int n = 0; n < 2; ++n) _Pragma("unroll") for (int k = 0; k < 2; ++k) \
;         acc[ai][bj][m][n] = __builtin_amdgcn_mfma_f32_16x16x32_bf16(Bt[n][k], At[m][k], acc[ai][bj][m][n], 0, 0, 0); __builtin_amdgcn_s_setprio(0); } while (0)
; #define PG8_WAIT_V(n) asm volatile("s_waitcnt vmcnt(" #n ")" ::: "memory")
; #define PG8_WAIT_L(n) asm volatile("s_waitcnt lgkmcnt(" #n ")" ::: "memory")
; #define PG8_BAR __builtin_amdgcn_s_barrier()
; #define PG8_SCHED __builtin_amdgcn_sched_barrier(0)
; template <class Epi, class Sched, bool ALIGN_EPI = false, bool SP2 = false>
; __device__ __forceinline__ void gemm_phase(PG8_LAS unsigned char* lds, const Gemm g, const Sched& S, const Epi& E, const int wv) {
;     ...
;         for (int t = 0; t < nt; t += 2) {
;     ...
;             PG8_LDB(B0, 1, 0); PG8_LDB(B1, 1, 1); PG8_SCHED; PG8_LDA(At, 1, 0); PG8_STAGE(PG8_SA(0, 1), a2 + hstepA, voffA);
;             PG8_WAIT_V(8); PG8_WAIT_L(0); PG8_BAR; PG8_MMA(0, 0, At, B0); PG8_MMA(0, 1, At, B1); PG8_BAR; PG8_SCHED;
;             PG8_LDA(At, 1, 1); PG8_STAGE(PG8_SB(1, 0), b3, voffB); PG8_STAGE(PG8_SB(1, 1), b3 + hstepB, voffB); PG8_STAGE(PG8_SA(1, 0), a3, voffA);
;             PG8_WAIT_V(8); PG8_WAIT_L(0); PG8_BAR; PG8_MMA(1, 0, At, B0); PG8_MMA(1, 1, At, B1); PG8_BAR; PG8_SCHED;
	ds_read_b128 v[164:167], v152
	ds_read_b128 v[168:171], v152 offset:1024
	ds_read_b128 v[172:175], v152 offset:2048
	ds_read_b128 v[176:179], v152 offset:3072
	ds_read_b128 v[180:183], v154
	ds_read_b128 v[194:197], v154 offset:1024
	ds_read_b128 v[198:201], v154 offset:2048
	ds_read_b128 v[202:205], v154 offset:3072
	s_mov_b32 m0, s49
	ds_read_b128 v[206:209], v163 offset:32768
	ds_read_b128 v[210:213], v163 offset:33792
	ds_read_b128 v[214:217], v163 offset:34816
	ds_read_b128 v[228:231], v163 offset:35840
	ds_read_b128 v[232:235], v163 offset:36864
	ds_read_b128 v[236:239], v163 offset:37888
	ds_read_b128 v[240:243], v163 offset:38912
	ds_read_b128 v[244:247], v163 offset:39936
	global_load_lds_dwordx4 v0, s[30:31]
	s_mov_b32 m0, s50
	s_nop 0
	global_load_lds_dwordx4 v156, s[30:31]
	s_waitcnt vmcnt(8) lgkmcnt(0)
	s_barrier
	v_mfma_f32_16x16x32_bf16 v[130:133], v[164:167], v[206:209], v[130:133]
	v_mfma_f32_16x16x32_bf16 v[126:129], v[172:175], v[206:209], v[126:129]
	v_mfma_f32_16x16x32_bf16 v[114:117], v[164:167], v[214:217], v[114:117]
	v_mfma_f32_16x16x32_bf16 v[110:113], v[172:175], v[214:217], v[110:113]
	v_mfma_f32_16x16x32_bf16 v[98:101], v[164:167], v[232:235], v[98:101]
	v_mfma_f32_16x16x32_bf16 v[94:97], v[172:175], v[232:235], v[94:97]
	v_mfma_f32_16x16x32_bf16 v[82:85], v[164:167], v[240:243], v[82:85]
	v_mfma_f32_16x16x32_bf16 v[78:81], v[172:175], v[240:243], v[78:81]
	v_mfma_f32_16x16x32_bf16 v[130:133], v[168:171], v[210:213], v[130:133]
	v_mfma_f32_16x16x32_bf16 v[126:129], v[176:179], v[210:213], v[126:129]
	v_mfma_f32_16x16x32_bf16 v[114:117], v[168:171], v[228:231], v[114:117]
	v_mfma_f32_16x16x32_bf16 v[110:113], v[176:179], v[228:231], v[110:113]
	v_mfma_f32_16x16x32_bf16 v[98:101], v[168:171], v[236:239], v[98:101]
	v_mfma_f32_16x16x32_bf16 v[94:97], v[176:179], v[236:239], v[94:97]
	v_mfma_f32_16x16x32_bf16 v[82:85], v[168:171], v[244:247], v[82:85]
	v_mfma_f32_16x16x32_bf16 v[78:81], v[176:179], v[244:247], v[78:81]
	v_mfma_f32_16x16x32_bf16 v[122:125], v[180:183], v[206:209], v[122:125]
	v_mfma_f32_16x16x32_bf16 v[118:121], v[198:201], v[206:209], v[118:121]
	v_mfma_f32_16x16x32_bf16 v[106:109], v[180:183], v[214:217], v[106:109]
	v_mfma_f32_16x16x32_bf16 v[102:105], v[198:201], v[214:217], v[102:105]
	v_mfma_f32_16x16x32_bf16 v[90:93], v[180:183], v[232:235], v[90:93]
	v_mfma_f32_16x16x32_bf16 v[86:89], v[198:201], v[232:235], v[86:89]
	v_mfma_f32_16x16x32_bf16 v[74:77], v[180:183], v[240:243], v[74:77]
	v_mfma_f32_16x16x32_bf16 v[70:73], v[198:201], v[240:243], v[70:73]
	v_mfma_f32_16x16x32_bf16 v[122:125], v[194:197], v[210:213], v[122:125]
	v_mfma_f32_16x16x32_bf16 v[118:121], v[202:205], v[210:213], v[118:121]
	v_mfma_f32_16x16x32_bf16 v[106:109], v[194:197], v[228:231], v[106:109]
	v_mfma_f32_16x16x32_bf16 v[102:105], v[202:205], v[228:231], v[102:105]
	v_mfma_f32_16x16x32_bf16 v[90:93], v[194:197], v[236:239], v[90:93]
	v_mfma_f32_16x16x32_bf16 v[86:89], v[202:205], v[236:239], v[86:89]
	v_mfma_f32_16x16x32_bf16 v[74:77], v[194:197], v[244:247], v[74:77]
	v_mfma_f32_16x16x32_bf16 v[70:73], v[202:205], v[244:247], v[70:73]
	s_barrier
	s_add_i32 m0, s45, 0x17f80
	ds_read_b128 v[206:209], v163 offset:49152
	ds_read_b128 v[210:213], v163 offset:50176
	ds_read_b128 v[214:217], v163 offset:51200
	ds_read_b128 v[228:231], v163 offset:52224
	ds_read_b128 v[232:235], v163 offset:53248
	ds_read_b128 v[236:239], v163 offset:54272
	ds_read_b128 v[240:243], v163 offset:55296
	ds_read_b128 v[244:247], v163 offset:56320
	global_load_lds_dwordx4 v[150:151], off offset:128
	s_add_i32 m0, s45, 0x19f80
	global_load_lds_dwordx4 v[184:185], off offset:128
	s_add_i32 m0, s45, 0x1bf80
	s_nop 0
	global_load_lds_dwordx4 v138, s[64:65] offset:128
	s_add_i32 m0, s45, 0x1df80
	s_nop 0
	global_load_lds_dwordx4 v134, s[64:65] offset:128
	s_add_i32 m0, s53, 0xffffff80
	s_nop 0
	global_load_lds_dwordx4 v140, s[30:31] offset:128
	s_add_i32 m0, s54, 0xffffff80
	s_nop 0
	global_load_lds_dwordx4 v136, s[30:31] offset:128
	s_waitcnt vmcnt(8) lgkmcnt(0)
	s_barrier
	v_mfma_f32_16x16x32_bf16 v[66:69], v[164:167], v[206:209], v[66:69]
	v_mfma_f32_16x16x32_bf16 v[62:65], v[172:175], v[206:209], v[62:65]
	v_mfma_f32_16x16x32_bf16 v[50:53], v[164:167], v[214:217], v[50:53]
	v_mfma_f32_16x16x32_bf16 v[46:49], v[172:175], v[214:217], v[46:49]
	v_mfma_f32_16x16x32_bf16 v[34:37], v[164:167], v[232:235], v[34:37]
	v_mfma_f32_16x16x32_bf16 v[30:33], v[172:175], v[232:235], v[30:33]
	v_mfma_f32_16x16x32_bf16 v[18:21], v[164:167], v[240:243], v[18:21]
	v_mfma_f32_16x16x32_bf16 v[14:17], v[172:175], v[240:243], v[14:17]
	v_mfma_f32_16x16x32_bf16 v[66:69], v[168:171], v[210:213], v[66:69]
	v_mfma_f32_16x16x32_bf16 v[62:65], v[176:179], v[210:213], v[62:65]
	v_mfma_f32_16x16x32_bf16 v[50:53], v[168:171], v[228:231], v[50:53]
	v_mfma_f32_16x16x32_bf16 v[46:49], v[176:179], v[228:231], v[46:49]
	v_mfma_f32_16x16x32_bf16 v[34:37], v[168:171], v[236:239], v[34:37]
	v_mfma_f32_16x16x32_bf16 v[30:33], v[176:179], v[236:239], v[30:33]
	v_mfma_f32_16x16x32_bf16 v[18:21], v[168:171], v[244:247], v[18:21]
	v_mfma_f32_16x16x32_bf16 v[14:17], v[176:179], v[244:247], v[14:17]
	v_mfma_f32_16x16x32_bf16 v[58:61], v[180:183], v[206:209], v[58:61]
	v_mfma_f32_16x16x32_bf16 v[54:57], v[198:201], v[206:209], v[54:57]
	v_mfma_f32_16x16x32_bf16 v[42:45], v[180:183], v[214:217], v[42:45]
	v_mfma_f32_16x16x32_bf16 v[38:41], v[198:201], v[214:217], v[38:41]
	v_mfma_f32_16x16x32_bf16 v[26:29], v[180:183], v[232:235], v[26:29]
	v_mfma_f32_16x16x32_bf16 v[22:25], v[198:201], v[232:235], v[22:25]
	v_mfma_f32_16x16x32_bf16 v[10:13], v[180:183], v[240:243], v[10:13]
	v_mfma_f32_16x16x32_bf16 v[6:9], v[198:201], v[240:243], v[6:9]
	v_mfma_f32_16x16x32_bf16 v[58:61], v[194:197], v[210:213], v[58:61]
	v_mfma_f32_16x16x32_bf16 v[54:57], v[202:205], v[210:213], v[54:57]
	v_mfma_f32_16x16x32_bf16 v[42:45], v[194:197], v[228:231], v[42:45]
	v_mfma_f32_16x16x32_bf16 v[38:41], v[202:205], v[228:231], v[38:41]
	v_mfma_f32_16x16x32_bf16 v[26:29], v[194:197], v[236:239], v[26:29]
	v_mfma_f32_16x16x32_bf16 v[22:25], v[202:205], v[236:239], v[22:25]
	v_mfma_f32_16x16x32_bf16 v[10:13], v[194:197], v[244:247], v[10:13]
	v_mfma_f32_16x16x32_bf16 v[6:9], v[202:205], v[244:247], v[6:9]
	s_barrier
	s_add_u32 s28, s28, 0x100
	s_addc_u32 s29, s29, 0
	s_add_u32 s41, s41, 0x100
	s_addc_u32 s62, s62, 0
	s_cmp_ge_i32 s63, s55
	s_mov_b32 s30, s63
	s_cbranch_scc0 .LBB0_1074
	s_setprio 0
	v_readlane_b32 s67, v255, 30

; #define PG8_STAGE(bufoff, gbase, voff) do { _Pragma("unroll") for (int _i = 0; _i < 2; ++_i) \
;         __builtin_amdgcn_global_load_lds((const unsigned*)((const char*)(gbase) + (voff)[_i]), (PG8_LAS unsigned*)(lds + (bufoff) + ldsw + _i * 8192), 16, 0, 0); } while (0)
; #define PG8_LDA(dst, b, h) do { _Pragma("unroll") for (int m = 0; m < 4; ++m) _Pragma("unroll") for (int k = 0; k < 2; ++k) dst[m][k] = *(const PG8_LAS bf16x8*)(lds + PG8_SA(b, h) + aoff + m * 2048 + k * 1024); } while (0)
; #define PG8_LDB(dst, b, h) do { _Pragma("unroll") for (int n = 0; n < 2; ++n) _Pragma("unroll") for (int k = 0; k < 2; ++k) dst[n][k] = *(const PG8_LAS bf16x8*)(lds + PG8_SB(b, h) + boff + n * 2048 + k * 1024); } while (0)
; #define PG8_MMA(ai, bj, At, Bt) do { __builtin_amdgcn_s_setprio(1); _Pragma("unroll") for (int m = 0; m < 4; ++m) _Pragma("unroll") for (int n = 0; n < 2; ++n) _Pragma("unroll") for (int k = 0; k < 2; ++k) \
;         acc[ai][bj][m][n] = __builtin_amdgcn_mfma_f32_16x16x32_bf16(Bt[n][k], At[m][k], acc[ai][bj][m][n], 0, 0, 0); __builtin_amdgcn_s_setprio(0); } while (0)
; #define PG8_WAIT_V(n) asm volatile("s_waitcnt vmcnt(" #n ")" ::: "memory")
; template <class Epi, class Sched, bool ALIGN_EPI = false, bool SP2 = false>
; __device__ __forceinline__ void gemm_phase(PG8_LAS unsigned char* lds, const Gemm g, const Sched& S, const Epi& E, const int wv) {
;     ...
;             const bool last = (t == nt - 2);
;             const char* a1 = cA + (size_t)(t + 1) * kstep;
;             const char* a2 = last ? nA : cA + (size_t)(t + 2) * kstep; const char* b2 = last ? nB : cB + (size_t)(t + 2) * kstep;
;             const char* a3 = a2 + kstep; const char* b3 = b2 + kstep;
;             if (last && has_next) S.a_ready(nxt);
;             if constexpr (SP2) {
;             PG8_LDB(B0, 0, 0); PG8_LDB(B1, 0, 1); PG8_SCHED; PG8_LDA(At, 0, 0); PG8_STAGE(PG8_SA(1, 1), a1 + hstepA, voffA);
;             PG8_WAIT_V(8); PG8_WAIT_L(0); PG8_BAR; PG8_MMA(0, 0, At, B0); PG8_MMA(0, 1, At, B1); PG8_BAR; PG8_SCHED;
;     ...
; #pragma unroll
;         for (int a = 0; a < 2; ++a)
; #pragma unroll
;             for (int b = 0; b < 2; ++b)
; #pragma unroll
;                 for (int m = 0; m < 4; ++m)
; #pragma unroll
;                     for (int n = 0; n < 2; ++n) acc[a][b][m][n] = (f32x4){0.f, 0.f, 0.f, 0.f};
;         cur = nxt; cA = nA; cB = nB; ++ui;
.LBB0_1384:
	s_and_b64 s[44:45], s[44:45], exec
	s_cselect_b32 s13, s49, s53
	s_cselect_b32 s19, s48, s52
	s_add_u32 s44, s52, 0x40080
	s_addc_u32 s45, s53, 0
	s_add_u32 s54, s54, 0x100
	v_mov_b32_e32 v2, 0
	s_addc_u32 s55, s55, 0
	s_mov_b32 s52, 0
	v_mov_b32_e32 v3, v2
	v_pk_mov_b32 v[4:5], v[2:3], v[2:3]
	v_pk_mov_b32 v[6:7], v[2:3], v[2:3]
	v_pk_mov_b32 v[8:9], v[2:3], v[2:3]
	v_pk_mov_b32 v[18:19], v[2:3], v[2:3]
	v_pk_mov_b32 v[20:21], v[2:3], v[2:3]
	v_pk_mov_b32 v[22:23], v[2:3], v[2:3]
	v_pk_mov_b32 v[24:25], v[2:3], v[2:3]
	v_pk_mov_b32 v[34:35], v[2:3], v[2:3]
	v_pk_mov_b32 v[36:37], v[2:3], v[2:3]
	v_pk_mov_b32 v[38:39], v[2:3], v[2:3]
	v_pk_mov_b32 v[40:41], v[2:3], v[2:3]
	v_pk_mov_b32 v[50:51], v[2:3], v[2:3]
	v_pk_mov_b32 v[52:53], v[2:3], v[2:3]
	v_pk_mov_b32 v[54:55], v[2:3], v[2:3]
	v_pk_mov_b32 v[56:57], v[2:3], v[2:3]
	v_pk_mov_b32 v[10:11], v[2:3], v[2:3]
	v_pk_mov_b32 v[12:13], v[2:3], v[2:3]
	v_pk_mov_b32 v[14:15], v[2:3], v[2:3]
	v_pk_mov_b32 v[16:17], v[2:3], v[2:3]
	v_pk_mov_b32 v[26:27], v[2:3], v[2:3]
	v_pk_mov_b32 v[28:29], v[2:3], v[2:3]
	v_pk_mov_b32 v[30:31], v[2:3], v[2:3]
	v_pk_mov_b32 v[32:33], v[2:3], v[2:3]
	v_pk_mov_b32 v[42:43], v[2:3], v[2:3]
	v_pk_mov_b32 v[44:45], v[2:3], v[2:3]
	v_pk_mov_b32 v[46:47], v[2:3], v[2:3]
	v_pk_mov_b32 v[48:49], v[2:3], v[2:3]
	v_pk_mov_b32 v[58:59], v[2:3], v[2:3]
	v_pk_mov_b32 v[60:61], v[2:3], v[2:3]
	v_pk_mov_b32 v[62:63], v[2:3], v[2:3]
	v_pk_mov_b32 v[64:65], v[2:3], v[2:3]
	v_pk_mov_b32 v[66:67], v[2:3], v[2:3]
	v_pk_mov_b32 v[68:69], v[2:3], v[2:3]
	v_pk_mov_b32 v[70:71], v[2:3], v[2:3]
	v_pk_mov_b32 v[72:73], v[2:3], v[2:3]
	v_pk_mov_b32 v[82:83], v[2:3], v[2:3]
	v_pk_mov_b32 v[84:85], v[2:3], v[2:3]
	v_pk_mov_b32 v[86:87], v[2:3], v[2:3]
	v_pk_mov_b32 v[88:89], v[2:3], v[2:3]
	v_pk_mov_b32 v[98:99], v[2:3], v[2:3]
	v_pk_mov_b32 v[100:101], v[2:3], v[2:3]
	v_pk_mov_b32 v[102:103], v[2:3], v[2:3]
	v_pk_mov_b32 v[104:105], v[2:3], v[2:3]
	v_pk_mov_b32 v[118:119], v[2:3], v[2:3]
	v_pk_mov_b32 v[120:121], v[2:3], v[2:3]
	v_pk_mov_b32 v[122:123], v[2:3], v[2:3]
	v_pk_mov_b32 v[124:125], v[2:3], v[2:3]
	v_pk_mov_b32 v[74:75], v[2:3], v[2:3]
	v_pk_mov_b32 v[76:77], v[2:3], v[2:3]
	v_pk_mov_b32 v[78:79], v[2:3], v[2:3]
	v_pk_mov_b32 v[80:81], v[2:3], v[2:3]
	v_pk_mov_b32 v[90:91], v[2:3], v[2:3]
	v_pk_mov_b32 v[92:93], v[2:3], v[2:3]
	v_pk_mov_b32 v[94:95], v[2:3], v[2:3]
	v_pk_mov_b32 v[96:97], v[2:3], v[2:3]
	v_pk_mov_b32 v[106:107], v[2:3], v[2:3]
	v_pk_mov_b32 v[108:109], v[2:3], v[2:3]
	v_pk_mov_b32 v[110:111], v[2:3], v[2:3]
	v_pk_mov_b32 v[112:113], v[2:3], v[2:3]
	v_pk_mov_b32 v[130:131], v[2:3], v[2:3]
	v_pk_mov_b32 v[132:133], v[2:3], v[2:3]
	v_pk_mov_b32 v[134:135], v[2:3], v[2:3]
	v_pk_mov_b32 v[136:137], v[2:3], v[2:3]
	v_add_u32_e32 v201, 0x10000, v230
	v_add_u32_e32 v203, 0x14000, v230
	v_add_u32_e32 v236, 0x18000, v230
	v_add_u32_e32 v237, 0x1c000, v230
	v_add_u32_e32 v212, 0x40000, v194
	v_add_u32_e32 v213, 0x40000, v196
	s_cmp_eq_u64 s[46:47], 0
	s_cbranch_scc0 .Lsp_skip_6
	s_setprio 1
.Lsp_skip_6:
.LBB0_1385:
	s_add_i32 s70, s52, 2
	s_add_u32 s71, s44, 0xfffc0080
	s_addc_u32 s53, s45, -1
	s_cmp_eq_u32 s65, s52
	s_cselect_b32 s53, s13, s53
	s_cselect_b32 s52, s19, s71
	s_cselect_b32 s73, s15, s55
	s_cselect_b32 s72, s14, s54
	ds_read_b128 v[114:117], v201
	ds_read_b128 v[126:129], v201 offset:1024
	ds_read_b128 v[138:141], v201 offset:2048
	ds_read_b128 v[142:145], v201 offset:3072
	ds_read_b128 v[146:149], v203
	ds_read_b128 v[150:153], v203 offset:1024
	ds_read_b128 v[154:157], v203 offset:2048
	ds_read_b128 v[158:161], v203 offset:3072
	s_add_i32 m0, s51, 0xc000
	ds_read_b128 v[162:165], v235
	ds_read_b128 v[166:169], v235 offset:1024
	ds_read_b128 v[170:173], v235 offset:2048
	ds_read_b128 v[174:177], v235 offset:3072
	ds_read_b128 v[178:181], v235 offset:4096
	ds_read_b128 v[182:185], v235 offset:5120
	ds_read_b128 v[204:207], v235 offset:6144
	ds_read_b128 v[208:211], v235 offset:7168
	global_load_lds_dwordx4 v200, s[44:45]
	s_add_i32 m0, s51, 0xe000
	s_nop 0
	global_load_lds_dwordx4 v202, s[44:45]
	s_waitcnt vmcnt(8) lgkmcnt(0)
	s_barrier
	v_mfma_f32_16x16x32_bf16 v[134:137], v[114:117], v[162:165], v[134:137]
	v_mfma_f32_16x16x32_bf16 v[130:133], v[138:141], v[162:165], v[130:133]
	v_mfma_f32_16x16x32_bf16 v[110:113], v[114:117], v[170:173], v[110:113]
	v_mfma_f32_16x16x32_bf16 v[106:109], v[138:141], v[170:173], v[106:109]
	v_mfma_f32_16x16x32_bf16 v[94:97], v[114:117], v[178:181], v[94:97]
	v_mfma_f32_16x16x32_bf16 v[90:93], v[138:141], v[178:181], v[90:93]
	v_mfma_f32_16x16x32_bf16 v[78:81], v[114:117], v[204:207], v[78:81]
	v_mfma_f32_16x16x32_bf16 v[74:77], v[138:141], v[204:207], v[74:77]
	v_mfma_f32_16x16x32_bf16 v[134:137], v[126:129], v[166:169], v[134:137]
	v_mfma_f32_16x16x32_bf16 v[130:133], v[142:145], v[166:169], v[130:133]
	v_mfma_f32_16x16x32_bf16 v[110:113], v[126:129], v[174:177], v[110:113]
	v_mfma_f32_16x16x32_bf16 v[106:109], v[142:145], v[174:177], v[106:109]
	v_mfma_f32_16x16x32_bf16 v[94:97], v[126:129], v[182:185], v[94:97]
	v_mfma_f32_16x16x32_bf16 v[90:93], v[142:145], v[182:185], v[90:93]
	v_mfma_f32_16x16x32_bf16 v[78:81], v[126:129], v[208:211], v[78:81]
	v_mfma_f32_16x16x32_bf16 v[74:77], v[142:145], v[208:211], v[74:77]
	v_mfma_f32_16x16x32_bf16 v[122:125], v[146:149], v[162:165], v[122:125]
	v_mfma_f32_16x16x32_bf16 v[118:121], v[154:157], v[162:165], v[118:121]
	v_mfma_f32_16x16x32_bf16 v[102:105], v[146:149], v[170:173], v[102:105]
	v_mfma_f32_16x16x32_bf16 v[98:101], v[154:157], v[170:173], v[98:101]
	v_mfma_f32_16x16x32_bf16 v[86:89], v[146:149], v[178:181], v[86:89]
	v_mfma_f32_16x16x32_bf16 v[82:85], v[154:157], v[178:181], v[82:85]
	v_mfma_f32_16x16x32_bf16 v[70:73], v[146:149], v[204:207], v[70:73]
	v_mfma_f32_16x16x32_bf16 v[66:69], v[154:157], v[204:207], v[66:69]
	v_mfma_f32_16x16x32_bf16 v[122:125], v[150:153], v[166:169], v[122:125]
	v_mfma_f32_16x16x32_bf16 v[118:121], v[158:161], v[166:169], v[118:121]
	v_mfma_f32_16x16x32_bf16 v[102:105], v[150:153], v[174:177], v[102:105]
	v_mfma_f32_16x16x32_bf16 v[98:101], v[158:161], v[174:177], v[98:101]
	v_mfma_f32_16x16x32_bf16 v[86:89], v[150:153], v[182:185], v[86:89]
	v_mfma_f32_16x16x32_bf16 v[82:85], v[158:161], v[182:185], v[82:85]
	v_mfma_f32_16x16x32_bf16 v[70:73], v[150:153], v[208:211], v[70:73]
	v_mfma_f32_16x16x32_bf16 v[66:69], v[158:161], v[208:211], v[66:69]
	s_barrier
; #define PG8_STAGE(bufoff, gbase, voff) do { _Pragma("unroll") for (int _i = 0; _i < 2; ++_i) \
;         __builtin_amdgcn_global_load_lds((const unsigned*)((const char*)(gbase) + (voff)[_i]), (PG8_LAS unsigned*)(lds + (bufoff) + ldsw + _i * 8192), 16, 0, 0); } while (0)
; #define PG8_LDA(dst, b, h) do { _Pragma("unroll") for (int m = 0; m < 4; ++m) _Pragma("unroll") for (int k = 0; k < 2; ++k) dst[m][k] = *(const PG8_LAS bf16x8*)(lds + PG8_SA(b, h) + aoff + m * 2048 + k * 1024); } while (0)
; #define PG8_LDB(dst, b, h) do { _Pragma("unroll") for (int n = 0; n < 2; ++n) _Pragma("unroll") for (int k = 0; k < 2; ++k) dst[n][k] = *(const PG8_LAS bf16x8*)(lds + PG8_SB(b, h) + boff + n * 2048 + k * 1024); } while (0)
; #define PG8_MMA(ai, bj, At, Bt) do { __builtin_amdgcn_s_setprio(1); _Pragma("unroll") for (int m = 0; m < 4; ++m) _Pragma("unroll") for (int n = 0; n < 2; ++n) _Pragma("unroll") for (int k = 0; k < 2; ++k) \
;         acc[ai][bj][m][n] = __builtin_amdgcn_mfma_f32_16x16x32_bf16(Bt[n][k], At[m][k], acc[ai][bj][m][n], 0, 0, 0); __builtin_amdgcn_s_setprio(0); } while (0)
; #define PG8_WAIT_V(n) asm volatile("s_waitcnt vmcnt(" #n ")" ::: "memory")
; #define PG8_WAIT_L(n) asm volatile("s_waitcnt lgkmcnt(" #n ")" ::: "memory")
; #define PG8_BAR __builtin_amdgcn_s_barrier()
; #define PG8_SCHED __builtin_amdgcn_sched_barrier(0)
; template <class Epi, class Sched, bool ALIGN_EPI = false, bool SP2 = false>
; __device__ __forceinline__ void gemm_phase(PG8_LAS unsigned char* lds, const Gemm g, const Sched& S, const Epi& E, const int wv) {
;     ...
;             PG8_LDA(At, 0, 1); PG8_STAGE(PG8_SB(0, 0), b2, voffB); PG8_STAGE(PG8_SB(0, 1), b2 + hstepB, voffB); PG8_STAGE(PG8_SA(0, 0), a2, voffA);
;             PG8_WAIT_V(8); PG8_WAIT_L(0); PG8_BAR; PG8_MMA(1, 0, At, B0); PG8_MMA(1, 1, At, B1); PG8_BAR; PG8_SCHED;
;             PG8_LDB(B0, 1, 0); PG8_LDB(B1, 1, 1); PG8_SCHED; PG8_LDA(At, 1, 0); PG8_STAGE(PG8_SA(0, 1), a2 + hstepA, voffA);
;             PG8_WAIT_V(8); PG8_WAIT_L(0); PG8_BAR; PG8_MMA(0, 0, At, B0); PG8_MMA(0, 1, At, B1); PG8_BAR; PG8_SCHED;
	s_add_i32 s74, s3, 0x10000
	v_lshl_add_u64 v[190:191], s[72:73], 0, v[0:1]
	s_mov_b32 m0, s74
	ds_read_b128 v[162:165], v235 offset:16384
	ds_read_b128 v[166:169], v235 offset:17408
	ds_read_b128 v[170:173], v235 offset:18432
	ds_read_b128 v[174:177], v235 offset:19456
	ds_read_b128 v[178:181], v235 offset:20480
	ds_read_b128 v[182:185], v235 offset:21504
	ds_read_b128 v[204:207], v235 offset:22528
	ds_read_b128 v[208:211], v235 offset:23552
	global_load_lds_dwordx4 v[190:191], off
	s_add_i32 m0, s74, 0x2000
	v_lshl_add_u64 v[192:193], s[72:73], 0, v[198:199]
	s_add_u32 s72, s72, s24
	s_addc_u32 s73, s73, s25
	s_add_i32 s71, s3, 0x14000
	global_load_lds_dwordx4 v[192:193], off
	s_mov_b32 m0, s71
	global_load_lds_dwordx4 v0, s[72:73]
	s_add_i32 m0, s71, 0x2000
	global_load_lds_dwordx4 v198, s[72:73]
	s_mov_b32 m0, s51
	global_load_lds_dwordx4 v194, s[52:53]
	s_mov_b32 m0, s59
	s_nop 0
	global_load_lds_dwordx4 v196, s[52:53]
	s_waitcnt vmcnt(8) lgkmcnt(0)
	s_barrier
	v_mfma_f32_16x16x32_bf16 v[62:65], v[114:117], v[162:165], v[62:65]
	v_mfma_f32_16x16x32_bf16 v[58:61], v[138:141], v[162:165], v[58:61]
	v_mfma_f32_16x16x32_bf16 v[46:49], v[114:117], v[170:173], v[46:49]
	v_mfma_f32_16x16x32_bf16 v[42:45], v[138:141], v[170:173], v[42:45]
	v_mfma_f32_16x16x32_bf16 v[30:33], v[114:117], v[178:181], v[30:33]
	v_mfma_f32_16x16x32_bf16 v[26:29], v[138:141], v[178:181], v[26:29]
	v_mfma_f32_16x16x32_bf16 v[14:17], v[114:117], v[204:207], v[14:17]
	v_mfma_f32_16x16x32_bf16 v[10:13], v[138:141], v[204:207], v[10:13]
	v_mfma_f32_16x16x32_bf16 v[62:65], v[126:129], v[166:169], v[62:65]
	v_mfma_f32_16x16x32_bf16 v[58:61], v[142:145], v[166:169], v[58:61]
	v_mfma_f32_16x16x32_bf16 v[46:49], v[126:129], v[174:177], v[46:49]
	v_mfma_f32_16x16x32_bf16 v[42:45], v[142:145], v[174:177], v[42:45]
	v_mfma_f32_16x16x32_bf16 v[30:33], v[126:129], v[182:185], v[30:33]
	v_mfma_f32_16x16x32_bf16 v[26:29], v[142:145], v[182:185], v[26:29]
	v_mfma_f32_16x16x32_bf16 v[14:17], v[126:129], v[208:211], v[14:17]
	v_mfma_f32_16x16x32_bf16 v[10:13], v[142:145], v[208:211], v[10:13]
	v_mfma_f32_16x16x32_bf16 v[54:57], v[146:149], v[162:165], v[54:57]
	v_mfma_f32_16x16x32_bf16 v[50:53], v[154:157], v[162:165], v[50:53]
	v_mfma_f32_16x16x32_bf16 v[38:41], v[146:149], v[170:173], v[38:41]
	v_mfma_f32_16x16x32_bf16 v[34:37], v[154:157], v[170:173], v[34:37]
	v_mfma_f32_16x16x32_bf16 v[22:25], v[146:149], v[178:181], v[22:25]
	v_mfma_f32_16x16x32_bf16 v[18:21], v[154:157], v[178:181], v[18:21]
	v_mfma_f32_16x16x32_bf16 v[6:9], v[146:149], v[204:207], v[6:9]
	v_mfma_f32_16x16x32_bf16 v[2:5], v[154:157], v[204:207], v[2:5]
	v_mfma_f32_16x16x32_bf16 v[54:57], v[150:153], v[166:169], v[54:57]
	v_mfma_f32_16x16x32_bf16 v[50:53], v[158:161], v[166:169], v[50:53]
	v_mfma_f32_16x16x32_bf16 v[38:41], v[150:153], v[174:177], v[38:41]
	v_mfma_f32_16x16x32_bf16 v[34:37], v[158:161], v[174:177], v[34:37]
	v_mfma_f32_16x16x32_bf16 v[22:25], v[150:153], v[182:185], v[22:25]
	v_mfma_f32_16x16x32_bf16 v[18:21], v[158:161], v[182:185], v[18:21]
	v_mfma_f32_16x16x32_bf16 v[6:9], v[150:153], v[208:211], v[6:9]
	v_mfma_f32_16x16x32_bf16 v[2:5], v[158:161], v[208:211], v[2:5]
	s_barrier
	ds_read_b128 v[114:117], v236
	ds_read_b128 v[126:129], v236 offset:1024
	ds_read_b128 v[138:141], v236 offset:2048
	ds_read_b128 v[142:145], v236 offset:3072
	ds_read_b128 v[146:149], v237
	ds_read_b128 v[150:153], v237 offset:1024
	ds_read_b128 v[154:157], v237 offset:2048
	ds_read_b128 v[158:161], v237 offset:3072
	s_mov_b32 m0, s60
	ds_read_b128 v[162:165], v235 offset:32768
	ds_read_b128 v[166:169], v235 offset:33792
	ds_read_b128 v[170:173], v235 offset:34816
	ds_read_b128 v[174:177], v235 offset:35840
	ds_read_b128 v[178:181], v235 offset:36864
	ds_read_b128 v[182:185], v235 offset:37888
	ds_read_b128 v[204:207], v235 offset:38912
	ds_read_b128 v[208:211], v235 offset:39936
	global_load_lds_dwordx4 v212, s[52:53]
	s_mov_b32 m0, s61
	s_nop 0
	global_load_lds_dwordx4 v213, s[52:53]
	s_waitcnt vmcnt(8) lgkmcnt(0)
	s_barrier
; #define PG8_STAGE(bufoff, gbase, voff) do { _Pragma("unroll") for (int _i = 0; _i < 2; ++_i) \
;         __builtin_amdgcn_global_load_lds((const unsigned*)((const char*)(gbase) + (voff)[_i]), (PG8_LAS unsigned*)(lds + (bufoff) + ldsw + _i * 8192), 16, 0, 0); } while (0)
; #define PG8_LDA(dst, b, h) do { _Pragma("unroll") for (int m = 0; m < 4; ++m) _Pragma("unroll") for (int k = 0; k < 2; ++k) dst[m][k] = *(const PG8_LAS bf16x8*)(lds + PG8_SA(b, h) + aoff + m * 2048 + k * 1024); } while (0)
; #define PG8_MMA(ai, bj, At, Bt) do { __builtin_amdgcn_s_setprio(1); _Pragma("unroll") for (int m = 0; m < 4; ++m) _Pragma("unroll") for (int n = 0; n < 2; ++n) _Pragma("unroll") for (int k = 0; k < 2; ++k) \
;         acc[ai][bj][m][n] = __builtin_amdgcn_mfma_f32_16x16x32_bf16(Bt[n][k], At[m][k], acc[ai][bj][m][n], 0, 0, 0); __builtin_amdgcn_s_setprio(0); } while (0)
; #define PG8_WAIT_V(n) asm volatile("s_waitcnt vmcnt(" #n ")" ::: "memory")
; #define PG8_WAIT_L(n) asm volatile("s_waitcnt lgkmcnt(" #n ")" ::: "memory")
; #define PG8_BAR __builtin_amdgcn_s_barrier()
; #define PG8_SCHED __builtin_amdgcn_sched_barrier(0)
; template <class Epi, class Sched, bool ALIGN_EPI = false, bool SP2 = false>
; __device__ __forceinline__ void gemm_phase(PG8_LAS unsigned char* lds, const Gemm g, const Sched& S, const Epi& E, const int wv) {
;     ...
;         for (int t = 0; t < nt; t += 2) {
;     ...
;             PG8_WAIT_V(8); PG8_WAIT_L(0); PG8_BAR; PG8_MMA(0, 0, At, B0); PG8_MMA(0, 1, At, B1); PG8_BAR; PG8_SCHED;
;             PG8_LDA(At, 1, 1); PG8_STAGE(PG8_SB(1, 0), b3, voffB); PG8_STAGE(PG8_SB(1, 1), b3 + hstepB, voffB); PG8_STAGE(PG8_SA(1, 0), a3, voffA);
;             PG8_WAIT_V(8); PG8_WAIT_L(0); PG8_BAR; PG8_MMA(1, 0, At, B0); PG8_MMA(1, 1, At, B1); PG8_BAR; PG8_SCHED;
	v_mfma_f32_16x16x32_bf16 v[134:137], v[114:117], v[162:165], v[134:137]
	v_mfma_f32_16x16x32_bf16 v[130:133], v[138:141], v[162:165], v[130:133]
	v_mfma_f32_16x16x32_bf16 v[110:113], v[114:117], v[170:173], v[110:113]
	v_mfma_f32_16x16x32_bf16 v[106:109], v[138:141], v[170:173], v[106:109]
	v_mfma_f32_16x16x32_bf16 v[94:97], v[114:117], v[178:181], v[94:97]
	v_mfma_f32_16x16x32_bf16 v[90:93], v[138:141], v[178:181], v[90:93]
	v_mfma_f32_16x16x32_bf16 v[78:81], v[114:117], v[204:207], v[78:81]
	v_mfma_f32_16x16x32_bf16 v[74:77], v[138:141], v[204:207], v[74:77]
	v_mfma_f32_16x16x32_bf16 v[134:137], v[126:129], v[166:169], v[134:137]
	v_mfma_f32_16x16x32_bf16 v[130:133], v[142:145], v[166:169], v[130:133]
	v_mfma_f32_16x16x32_bf16 v[110:113], v[126:129], v[174:177], v[110:113]
	v_mfma_f32_16x16x32_bf16 v[106:109], v[142:145], v[174:177], v[106:109]
	v_mfma_f32_16x16x32_bf16 v[94:97], v[126:129], v[182:185], v[94:97]
	v_mfma_f32_16x16x32_bf16 v[90:93], v[142:145], v[182:185], v[90:93]
	v_mfma_f32_16x16x32_bf16 v[78:81], v[126:129], v[208:211], v[78:81]
	v_mfma_f32_16x16x32_bf16 v[74:77], v[142:145], v[208:211], v[74:77]
	v_mfma_f32_16x16x32_bf16 v[122:125], v[146:149], v[162:165], v[122:125]
	v_mfma_f32_16x16x32_bf16 v[118:121], v[154:157], v[162:165], v[118:121]
	v_mfma_f32_16x16x32_bf16 v[102:105], v[146:149], v[170:173], v[102:105]
	v_mfma_f32_16x16x32_bf16 v[98:101], v[154:157], v[170:173], v[98:101]
	v_mfma_f32_16x16x32_bf16 v[86:89], v[146:149], v[178:181], v[86:89]
	v_mfma_f32_16x16x32_bf16 v[82:85], v[154:157], v[178:181], v[82:85]
	v_mfma_f32_16x16x32_bf16 v[70:73], v[146:149], v[204:207], v[70:73]
	v_mfma_f32_16x16x32_bf16 v[66:69], v[154:157], v[204:207], v[66:69]
	v_mfma_f32_16x16x32_bf16 v[122:125], v[150:153], v[166:169], v[122:125]
	v_mfma_f32_16x16x32_bf16 v[118:121], v[158:161], v[166:169], v[118:121]
	v_mfma_f32_16x16x32_bf16 v[102:105], v[150:153], v[174:177], v[102:105]
	v_mfma_f32_16x16x32_bf16 v[98:101], v[158:161], v[174:177], v[98:101]
	v_mfma_f32_16x16x32_bf16 v[86:89], v[150:153], v[182:185], v[86:89]
	v_mfma_f32_16x16x32_bf16 v[82:85], v[158:161], v[182:185], v[82:85]
	v_mfma_f32_16x16x32_bf16 v[70:73], v[150:153], v[208:211], v[70:73]
	v_mfma_f32_16x16x32_bf16 v[66:69], v[158:161], v[208:211], v[66:69]
	s_barrier
	s_add_i32 m0, s3, 0x17f80
	ds_read_b128 v[162:165], v235 offset:49152
	ds_read_b128 v[166:169], v235 offset:50176
	ds_read_b128 v[170:173], v235 offset:51200
	ds_read_b128 v[174:177], v235 offset:52224
	ds_read_b128 v[178:181], v235 offset:53248
	ds_read_b128 v[182:185], v235 offset:54272
	ds_read_b128 v[204:207], v235 offset:55296
	ds_read_b128 v[208:211], v235 offset:56320
	global_load_lds_dwordx4 v[190:191], off offset:128
	s_add_i32 m0, s3, 0x19f80
	global_load_lds_dwordx4 v[192:193], off offset:128
	s_add_i32 m0, s3, 0x1bf80
	s_nop 0
	global_load_lds_dwordx4 v0, s[72:73] offset:128
	s_add_i32 m0, s3, 0x1df80
	s_nop 0
	global_load_lds_dwordx4 v198, s[72:73] offset:128
	s_add_i32 m0, s63, 0xffffff80
	s_nop 0
	global_load_lds_dwordx4 v194, s[52:53] offset:128
	s_add_i32 m0, s64, 0xffffff80
	s_nop 0
	global_load_lds_dwordx4 v196, s[52:53] offset:128
	s_waitcnt vmcnt(8) lgkmcnt(0)
	s_barrier
	v_mfma_f32_16x16x32_bf16 v[62:65], v[114:117], v[162:165], v[62:65]
	v_mfma_f32_16x16x32_bf16 v[58:61], v[138:141], v[162:165], v[58:61]
	v_mfma_f32_16x16x32_bf16 v[46:49], v[114:117], v[170:173], v[46:49]
	v_mfma_f32_16x16x32_bf16 v[42:45], v[138:141], v[170:173], v[42:45]
	v_mfma_f32_16x16x32_bf16 v[30:33], v[114:117], v[178:181], v[30:33]
	v_mfma_f32_16x16x32_bf16 v[26:29], v[138:141], v[178:181], v[26:29]
	v_mfma_f32_16x16x32_bf16 v[14:17], v[114:117], v[204:207], v[14:17]
	v_mfma_f32_16x16x32_bf16 v[10:13], v[138:141], v[204:207], v[10:13]
	v_mfma_f32_16x16x32_bf16 v[62:65], v[126:129], v[166:169], v[62:65]
	v_mfma_f32_16x16x32_bf16 v[58:61], v[142:145], v[166:169], v[58:61]
	v_mfma_f32_16x16x32_bf16 v[46:49], v[126:129], v[174:177], v[46:49]
	v_mfma_f32_16x16x32_bf16 v[42:45], v[142:145], v[174:177], v[42:45]
	v_mfma_f32_16x16x32_bf16 v[30:33], v[126:129], v[182:185], v[30:33]
	v_mfma_f32_16x16x32_bf16 v[26:29], v[142:145], v[182:185], v[26:29]
	v_mfma_f32_16x16x32_bf16 v[14:17], v[126:129], v[208:211], v[14:17]
	v_mfma_f32_16x16x32_bf16 v[10:13], v[142:145], v[208:211], v[10:13]
	v_mfma_f32_16x16x32_bf16 v[54:57], v[146:149], v[162:165], v[54:57]
	v_mfma_f32_16x16x32_bf16 v[50:53], v[154:157], v[162:165], v[50:53]
	v_mfma_f32_16x16x32_bf16 v[38:41], v[146:149], v[170:173], v[38:41]
	v_mfma_f32_16x16x32_bf16 v[34:37], v[154:157], v[170:173], v[34:37]
	v_mfma_f32_16x16x32_bf16 v[22:25], v[146:149], v[178:181], v[22:25]
	v_mfma_f32_16x16x32_bf16 v[18:21], v[154:157], v[178:181], v[18:21]
	v_mfma_f32_16x16x32_bf16 v[6:9], v[146:149], v[204:207], v[6:9]
	v_mfma_f32_16x16x32_bf16 v[2:5], v[154:157], v[204:207], v[2:5]
	v_mfma_f32_16x16x32_bf16 v[54:57], v[150:153], v[166:169], v[54:57]
	v_mfma_f32_16x16x32_bf16 v[50:53], v[158:161], v[166:169], v[50:53]
	v_mfma_f32_16x16x32_bf16 v[38:41], v[150:153], v[174:177], v[38:41]
	v_mfma_f32_16x16x32_bf16 v[34:37], v[158:161], v[174:177], v[34:37]
	v_mfma_f32_16x16x32_bf16 v[22:25], v[150:153], v[182:185], v[22:25]
	v_mfma_f32_16x16x32_bf16 v[18:21], v[158:161], v[182:185], v[18:21]
	v_mfma_f32_16x16x32_bf16 v[6:9], v[150:153], v[208:211], v[6:9]
	v_mfma_f32_16x16x32_bf16 v[2:5], v[158:161], v[208:211], v[2:5]
	s_barrier
	s_add_u32 s44, s44, 0x100
	s_addc_u32 s45, s45, 0
	s_add_u32 s54, s54, 0x100
	s_addc_u32 s55, s55, 0
	s_cmp_ge_i32 s70, s62
	s_mov_b32 s52, s70
	s_cbranch_scc0 .LBB0_1385
	s_setprio 0
	s_mov_b32 s72, 0x10000
	s_mov_b32 s73, 0x12000
	s_mov_b32 s74, 0x14000
	s_mov_b32 s70, 0x18000
	s_mov_b32 s71, 0x3f317217
	s_and_b64 vcc, exec, s[46:47]
	s_cbranch_vccz .LBB0_1361

; #define PG8_STAGE(bufoff, gbase, voff) do { _Pragma("unroll") for (int _i = 0; _i < 2; ++_i) \
;         __builtin_amdgcn_global_load_lds((const unsigned*)((const char*)(gbase) + (voff)[_i]), (PG8_LAS unsigned*)(lds + (bufoff) + ldsw + _i * 8192), 16, 0, 0); } while (0)
; #define PG8_LDA(dst, b, h) do { _Pragma("unroll") for (int m = 0; m < 4; ++m) _Pragma("unroll") for (int k = 0; k < 2; ++k) dst[m][k] = *(const PG8_LAS bf16x8*)(lds + PG8_SA(b, h) + aoff + m * 2048 + k * 1024); } while (0)
; #define PG8_LDB(dst, b, h) do { _Pragma("unroll") for (int n = 0; n < 2; ++n) _Pragma("unroll") for (int k = 0; k < 2; ++k) dst[n][k] = *(const PG8_LAS bf16x8*)(lds + PG8_SB(b, h) + boff + n * 2048 + k * 1024); } while (0)
; #define PG8_MMA(ai, bj, At, Bt) do { __builtin_amdgcn_s_setprio(1); _Pragma("unroll") for (int m = 0; m < 4; ++m) _Pragma("unroll") for (int n = 0; n < 2; ++n) _Pragma("unroll") for (int k = 0; k < 2; ++k) \
;         acc[ai][bj][m][n] = __builtin_amdgcn_mfma_f32_16x16x32_bf16(Bt[n][k], At[m][k], acc[ai][bj][m][n], 0, 0, 0); __builtin_amdgcn_s_setprio(0); } while (0)
; #define PG8_WAIT_V(n) asm volatile("s_waitcnt vmcnt(" #n ")" ::: "memory")
; #define PG8_WAIT_L(n) asm volatile("s_waitcnt lgkmcnt(" #n ")" ::: "memory")
; template <class Epi, class Sched, bool ALIGN_EPI = false, bool SP2 = false>
; __device__ __forceinline__ void gemm_phase(PG8_LAS unsigned char* lds, const Gemm g, const Sched& S, const Epi& E, const int wv) {
;     ...
;             const bool last = (t == nt - 2);
;             const char* a1 = cA + (size_t)(t + 1) * kstep;
;             const char* a2 = last ? nA : cA + (size_t)(t + 2) * kstep; const char* b2 = last ? nB : cB + (size_t)(t + 2) * kstep;
;             const char* a3 = a2 + kstep; const char* b3 = b2 + kstep;
;             if (last && has_next) S.a_ready(nxt);
;             if constexpr (SP2) {
;             PG8_LDB(B0, 0, 0); PG8_LDB(B1, 0, 1); PG8_SCHED; PG8_LDA(At, 0, 0); PG8_STAGE(PG8_SA(1, 1), a1 + hstepA, voffA);
;             PG8_WAIT_V(8); PG8_WAIT_L(0); PG8_BAR; PG8_MMA(0, 0, At, B0); PG8_MMA(0, 1, At, B1); PG8_BAR; PG8_SCHED;
;             PG8_LDA(At, 0, 1); PG8_STAGE(PG8_SB(0, 0), b2, voffB); PG8_STAGE(PG8_SB(0, 1), b2 + hstepB, voffB); PG8_STAGE(PG8_SA(0, 0), a2, voffA);
;             PG8_WAIT_V(8); PG8_WAIT_L(0); PG8_BAR; PG8_MMA(1, 0, At, B0); PG8_MMA(1, 1, At, B1); PG8_BAR; PG8_SCHED;
.Lsp_skip_7:
.LBB0_1495:
	s_add_i32 s52, s46, 2
	s_add_u32 s14, s48, 0x100
	s_addc_u32 s15, s49, 0
	s_cmp_eq_u32 s72, s46
	s_cselect_b32 s47, s11, s15
	s_cselect_b32 s46, s13, s14
	s_cselect_b32 s77, s87, s51
	s_cselect_b32 s76, s86, s35
	ds_read_b128 v[138:141], v192
	ds_read_b128 v[142:145], v192 offset:1024
	ds_read_b128 v[146:149], v192 offset:2048
	ds_read_b128 v[150:153], v192 offset:3072
	ds_read_b128 v[154:157], v193
	ds_read_b128 v[158:161], v193 offset:1024
	ds_read_b128 v[162:165], v193 offset:2048
	ds_read_b128 v[166:169], v193 offset:3072
	s_add_i32 m0, s64, 0xc000
	ds_read_b128 v[194:197], v211
	ds_read_b128 v[198:201], v211 offset:1024
	ds_read_b128 v[202:205], v211 offset:2048
	ds_read_b128 v[214:217], v211 offset:3072
	ds_read_b128 v[228:231], v211 offset:4096
	ds_read_b128 v[232:235], v211 offset:5120
	ds_read_b128 v[236:239], v211 offset:6144
	ds_read_b128 v[240:243], v211 offset:7168
	global_load_lds_dwordx4 v182, s[48:49]
	v_lshl_add_u64 v[190:191], s[48:49], 0, v[184:185]
	s_add_i32 m0, s64, 0xe000
	s_nop 0
	global_load_lds_dwordx4 v[190:191], off
	s_waitcnt vmcnt(8) lgkmcnt(0)
	s_barrier
	v_mfma_f32_16x16x32_bf16 v[118:121], v[138:141], v[194:197], v[118:121]
	v_mfma_f32_16x16x32_bf16 v[46:49], v[146:149], v[194:197], v[46:49]
	v_mfma_f32_16x16x32_bf16 v[110:113], v[138:141], v[202:205], v[110:113]
	v_mfma_f32_16x16x32_bf16 v[38:41], v[146:149], v[202:205], v[38:41]
	v_mfma_f32_16x16x32_bf16 v[134:137], v[138:141], v[228:231], v[134:137]
	v_mfma_f32_16x16x32_bf16 v[62:65], v[146:149], v[228:231], v[62:65]
	v_mfma_f32_16x16x32_bf16 v[130:133], v[138:141], v[236:239], v[130:133]
	v_mfma_f32_16x16x32_bf16 v[58:61], v[146:149], v[236:239], v[58:61]
	v_mfma_f32_16x16x32_bf16 v[118:121], v[142:145], v[198:201], v[118:121]
	v_mfma_f32_16x16x32_bf16 v[46:49], v[150:153], v[198:201], v[46:49]
	v_mfma_f32_16x16x32_bf16 v[110:113], v[142:145], v[214:217], v[110:113]
	v_mfma_f32_16x16x32_bf16 v[38:41], v[150:153], v[214:217], v[38:41]
	v_mfma_f32_16x16x32_bf16 v[134:137], v[142:145], v[232:235], v[134:137]
	v_mfma_f32_16x16x32_bf16 v[62:65], v[150:153], v[232:235], v[62:65]
	v_mfma_f32_16x16x32_bf16 v[130:133], v[142:145], v[240:243], v[130:133]
	v_mfma_f32_16x16x32_bf16 v[58:61], v[150:153], v[240:243], v[58:61]
	v_mfma_f32_16x16x32_bf16 v[114:117], v[154:157], v[194:197], v[114:117]
	v_mfma_f32_16x16x32_bf16 v[42:45], v[162:165], v[194:197], v[42:45]
	v_mfma_f32_16x16x32_bf16 v[106:109], v[154:157], v[202:205], v[106:109]
	v_mfma_f32_16x16x32_bf16 v[34:37], v[162:165], v[202:205], v[34:37]
	v_mfma_f32_16x16x32_bf16 v[126:129], v[154:157], v[228:231], v[126:129]
	v_mfma_f32_16x16x32_bf16 v[54:57], v[162:165], v[228:231], v[54:57]
	v_mfma_f32_16x16x32_bf16 v[122:125], v[154:157], v[236:239], v[122:125]
	v_mfma_f32_16x16x32_bf16 v[50:53], v[162:165], v[236:239], v[50:53]
	v_mfma_f32_16x16x32_bf16 v[114:117], v[158:161], v[198:201], v[114:117]
	v_mfma_f32_16x16x32_bf16 v[42:45], v[166:169], v[198:201], v[42:45]
	v_mfma_f32_16x16x32_bf16 v[106:109], v[158:161], v[214:217], v[106:109]
	v_mfma_f32_16x16x32_bf16 v[34:37], v[166:169], v[214:217], v[34:37]
	v_mfma_f32_16x16x32_bf16 v[126:129], v[158:161], v[232:235], v[126:129]
	v_mfma_f32_16x16x32_bf16 v[54:57], v[166:169], v[232:235], v[54:57]
	v_mfma_f32_16x16x32_bf16 v[122:125], v[158:161], v[240:243], v[122:125]
	v_mfma_f32_16x16x32_bf16 v[50:53], v[166:169], v[240:243], v[50:53]
	s_barrier
	s_add_i32 s48, s63, 0x10000
	s_mov_b32 m0, s48
	ds_read_b128 v[194:197], v211 offset:16384
	ds_read_b128 v[198:201], v211 offset:17408
	ds_read_b128 v[202:205], v211 offset:18432
	ds_read_b128 v[214:217], v211 offset:19456
	ds_read_b128 v[228:231], v211 offset:20480
	ds_read_b128 v[232:235], v211 offset:21504
	ds_read_b128 v[236:239], v211 offset:22528
	ds_read_b128 v[240:243], v211 offset:23552
	global_load_lds_dwordx4 v0, s[76:77]
	s_add_i32 m0, s48, 0x2000
	s_add_u32 s48, s76, s16
	s_addc_u32 s49, s77, s17
	s_add_i32 s53, s63, 0x14000
	global_load_lds_dwordx4 v174, s[76:77]
	s_mov_b32 m0, s53
	global_load_lds_dwordx4 v0, s[48:49]
	s_add_i32 m0, s53, 0x2000
	global_load_lds_dwordx4 v174, s[48:49]
	s_mov_b32 m0, s64
	global_load_lds_dwordx4 v170, s[46:47]
	s_mov_b32 m0, s65
	s_nop 0
	global_load_lds_dwordx4 v172, s[46:47]
	s_waitcnt vmcnt(8) lgkmcnt(0)
	s_barrier
	v_mfma_f32_16x16x32_bf16 v[86:89], v[138:141], v[194:197], v[86:89]
	v_mfma_f32_16x16x32_bf16 v[14:17], v[146:149], v[194:197], v[14:17]
	v_mfma_f32_16x16x32_bf16 v[70:73], v[138:141], v[202:205], v[70:73]
	v_mfma_f32_16x16x32_bf16 v[6:9], v[146:149], v[202:205], v[6:9]
	v_mfma_f32_16x16x32_bf16 v[102:105], v[138:141], v[228:231], v[102:105]
	v_mfma_f32_16x16x32_bf16 v[30:33], v[146:149], v[228:231], v[30:33]
	v_mfma_f32_16x16x32_bf16 v[98:101], v[138:141], v[236:239], v[98:101]
	v_mfma_f32_16x16x32_bf16 v[26:29], v[146:149], v[236:239], v[26:29]
	v_mfma_f32_16x16x32_bf16 v[86:89], v[142:145], v[198:201], v[86:89]
	v_mfma_f32_16x16x32_bf16 v[14:17], v[150:153], v[198:201], v[14:17]
	v_mfma_f32_16x16x32_bf16 v[70:73], v[142:145], v[214:217], v[70:73]
	v_mfma_f32_16x16x32_bf16 v[6:9], v[150:153], v[214:217], v[6:9]
	v_mfma_f32_16x16x32_bf16 v[102:105], v[142:145], v[232:235], v[102:105]
	v_mfma_f32_16x16x32_bf16 v[30:33], v[150:153], v[232:235], v[30:33]
	v_mfma_f32_16x16x32_bf16 v[98:101], v[142:145], v[240:243], v[98:101]
	v_mfma_f32_16x16x32_bf16 v[26:29], v[150:153], v[240:243], v[26:29]
	v_mfma_f32_16x16x32_bf16 v[82:85], v[154:157], v[194:197], v[82:85]
	v_mfma_f32_16x16x32_bf16 v[10:13], v[162:165], v[194:197], v[10:13]
	v_mfma_f32_16x16x32_bf16 v[66:69], v[154:157], v[202:205], v[66:69]
	v_mfma_f32_16x16x32_bf16 v[2:5], v[162:165], v[202:205], v[2:5]
	v_mfma_f32_16x16x32_bf16 v[94:97], v[154:157], v[228:231], v[94:97]
	v_mfma_f32_16x16x32_bf16 v[22:25], v[162:165], v[228:231], v[22:25]
	v_mfma_f32_16x16x32_bf16 v[90:93], v[154:157], v[236:239], v[90:93]
	v_mfma_f32_16x16x32_bf16 v[18:21], v[162:165], v[236:239], v[18:21]
	v_mfma_f32_16x16x32_bf16 v[82:85], v[158:161], v[198:201], v[82:85]
	v_mfma_f32_16x16x32_bf16 v[10:13], v[166:169], v[198:201], v[10:13]
	v_mfma_f32_16x16x32_bf16 v[66:69], v[158:161], v[214:217], v[66:69]
	v_mfma_f32_16x16x32_bf16 v[2:5], v[166:169], v[214:217], v[2:5]
	v_mfma_f32_16x16x32_bf16 v[94:97], v[158:161], v[232:235], v[94:97]
	v_mfma_f32_16x16x32_bf16 v[22:25], v[166:169], v[232:235], v[22:25]
	v_mfma_f32_16x16x32_bf16 v[90:93], v[158:161], v[240:243], v[90:93]
	v_mfma_f32_16x16x32_bf16 v[18:21], v[166:169], v[240:243], v[18:21]
	s_barrier
; #define PG8_STAGE(bufoff, gbase, voff) do { _Pragma("unroll") for (int _i = 0; _i < 2; ++_i) \
;         __builtin_amdgcn_global_load_lds((const unsigned*)((const char*)(gbase) + (voff)[_i]), (PG8_LAS unsigned*)(lds + (bufoff) + ldsw + _i * 8192), 16, 0, 0); } while (0)
; #define PG8_LDA(dst, b, h) do { _Pragma("unroll") for (int m = 0; m < 4; ++m) _Pragma("unroll") for (int k = 0; k < 2; ++k) dst[m][k] = *(const PG8_LAS bf16x8*)(lds + PG8_SA(b, h) + aoff + m * 2048 + k * 1024); } while (0)
; #define PG8_LDB(dst, b, h) do { _Pragma("unroll") for (int n = 0; n < 2; ++n) _Pragma("unroll") for (int k = 0; k < 2; ++k) dst[n][k] = *(const PG8_LAS bf16x8*)(lds + PG8_SB(b, h) + boff + n * 2048 + k * 1024); } while (0)
; #define PG8_MMA(ai, bj, At, Bt) do { __builtin_amdgcn_s_setprio(1); _Pragma("unroll") for (int m = 0; m < 4; ++m) _Pragma("unroll") for (int n = 0; n < 2; ++n) _Pragma("unroll") for (int k = 0; k < 2; ++k) \
;         acc[ai][bj][m][n] = __builtin_amdgcn_mfma_f32_16x16x32_bf16(Bt[n][k], At[m][k], acc[ai][bj][m][n], 0, 0, 0); __builtin_amdgcn_s_setprio(0); } while (0)
; #define PG8_WAIT_V(n) asm volatile("s_waitcnt vmcnt(" #n ")" ::: "memory")
; #define PG8_WAIT_L(n) asm volatile("s_waitcnt lgkmcnt(" #n ")" ::: "memory")
; #define PG8_BAR __builtin_amdgcn_s_barrier()
; #define PG8_SCHED __builtin_amdgcn_sched_barrier(0)
; template <class Epi, class Sched, bool ALIGN_EPI = false, bool SP2 = false>
; __device__ __forceinline__ void gemm_phase(PG8_LAS unsigned char* lds, const Gemm g, const Sched& S, const Epi& E, const int wv) {
;     ...
;         for (int t = 0; t < nt; t += 2) {
;     ...
;             PG8_LDB(B0, 1, 0); PG8_LDB(B1, 1, 1); PG8_SCHED; PG8_LDA(At, 1, 0); PG8_STAGE(PG8_SA(0, 1), a2 + hstepA, voffA);
;             PG8_WAIT_V(8); PG8_WAIT_L(0); PG8_BAR; PG8_MMA(0, 0, At, B0); PG8_MMA(0, 1, At, B1); PG8_BAR; PG8_SCHED;
;             PG8_LDA(At, 1, 1); PG8_STAGE(PG8_SB(1, 0), b3, voffB); PG8_STAGE(PG8_SB(1, 1), b3 + hstepB, voffB); PG8_STAGE(PG8_SA(1, 0), a3, voffA);
;             PG8_WAIT_V(8); PG8_WAIT_L(0); PG8_BAR; PG8_MMA(1, 0, At, B0); PG8_MMA(1, 1, At, B1); PG8_BAR; PG8_SCHED;
	ds_read_b128 v[138:141], v213
	ds_read_b128 v[142:145], v213 offset:1024
	ds_read_b128 v[146:149], v213 offset:2048
	ds_read_b128 v[150:153], v213 offset:3072
	ds_read_b128 v[154:157], v227
	ds_read_b128 v[158:161], v227 offset:1024
	ds_read_b128 v[162:165], v227 offset:2048
	ds_read_b128 v[166:169], v227 offset:3072
	s_mov_b32 m0, s66
	ds_read_b128 v[194:197], v211 offset:32768
	ds_read_b128 v[198:201], v211 offset:33792
	ds_read_b128 v[202:205], v211 offset:34816
	ds_read_b128 v[214:217], v211 offset:35840
	ds_read_b128 v[228:231], v211 offset:36864
	ds_read_b128 v[232:235], v211 offset:37888
	ds_read_b128 v[236:239], v211 offset:38912
	ds_read_b128 v[240:243], v211 offset:39936
	global_load_lds_dwordx4 v218, s[46:47]
	s_mov_b32 m0, s67
	s_nop 0
	global_load_lds_dwordx4 v219, s[46:47]
	s_waitcnt vmcnt(8) lgkmcnt(0)
	s_barrier
	v_mfma_f32_16x16x32_bf16 v[118:121], v[138:141], v[194:197], v[118:121]
	v_mfma_f32_16x16x32_bf16 v[46:49], v[146:149], v[194:197], v[46:49]
	v_mfma_f32_16x16x32_bf16 v[110:113], v[138:141], v[202:205], v[110:113]
	v_mfma_f32_16x16x32_bf16 v[38:41], v[146:149], v[202:205], v[38:41]
	v_mfma_f32_16x16x32_bf16 v[134:137], v[138:141], v[228:231], v[134:137]
	v_mfma_f32_16x16x32_bf16 v[62:65], v[146:149], v[228:231], v[62:65]
	v_mfma_f32_16x16x32_bf16 v[130:133], v[138:141], v[236:239], v[130:133]
	v_mfma_f32_16x16x32_bf16 v[58:61], v[146:149], v[236:239], v[58:61]
	v_mfma_f32_16x16x32_bf16 v[118:121], v[142:145], v[198:201], v[118:121]
	v_mfma_f32_16x16x32_bf16 v[46:49], v[150:153], v[198:201], v[46:49]
	v_mfma_f32_16x16x32_bf16 v[110:113], v[142:145], v[214:217], v[110:113]
	v_mfma_f32_16x16x32_bf16 v[38:41], v[150:153], v[214:217], v[38:41]
	v_mfma_f32_16x16x32_bf16 v[134:137], v[142:145], v[232:235], v[134:137]
	v_mfma_f32_16x16x32_bf16 v[62:65], v[150:153], v[232:235], v[62:65]
	v_mfma_f32_16x16x32_bf16 v[130:133], v[142:145], v[240:243], v[130:133]
	v_mfma_f32_16x16x32_bf16 v[58:61], v[150:153], v[240:243], v[58:61]
	v_mfma_f32_16x16x32_bf16 v[114:117], v[154:157], v[194:197], v[114:117]
	v_mfma_f32_16x16x32_bf16 v[42:45], v[162:165], v[194:197], v[42:45]
	v_mfma_f32_16x16x32_bf16 v[106:109], v[154:157], v[202:205], v[106:109]
	v_mfma_f32_16x16x32_bf16 v[34:37], v[162:165], v[202:205], v[34:37]
	v_mfma_f32_16x16x32_bf16 v[126:129], v[154:157], v[228:231], v[126:129]
	v_mfma_f32_16x16x32_bf16 v[54:57], v[162:165], v[228:231], v[54:57]
	v_mfma_f32_16x16x32_bf16 v[122:125], v[154:157], v[236:239], v[122:125]
	v_mfma_f32_16x16x32_bf16 v[50:53], v[162:165], v[236:239], v[50:53]
	v_mfma_f32_16x16x32_bf16 v[114:117], v[158:161], v[198:201], v[114:117]
	v_mfma_f32_16x16x32_bf16 v[42:45], v[166:169], v[198:201], v[42:45]
	v_mfma_f32_16x16x32_bf16 v[106:109], v[158:161], v[214:217], v[106:109]
	v_mfma_f32_16x16x32_bf16 v[34:37], v[166:169], v[214:217], v[34:37]
	v_mfma_f32_16x16x32_bf16 v[126:129], v[158:161], v[232:235], v[126:129]
	v_mfma_f32_16x16x32_bf16 v[54:57], v[166:169], v[232:235], v[54:57]
	v_mfma_f32_16x16x32_bf16 v[122:125], v[158:161], v[240:243], v[122:125]
	v_mfma_f32_16x16x32_bf16 v[50:53], v[166:169], v[240:243], v[50:53]
	s_barrier
	s_add_i32 m0, s63, 0x17f80
	ds_read_b128 v[194:197], v211 offset:49152
	ds_read_b128 v[198:201], v211 offset:50176
	ds_read_b128 v[202:205], v211 offset:51200
	ds_read_b128 v[214:217], v211 offset:52224
	ds_read_b128 v[228:231], v211 offset:53248
	ds_read_b128 v[232:235], v211 offset:54272
	ds_read_b128 v[236:239], v211 offset:55296
	ds_read_b128 v[240:243], v211 offset:56320
	global_load_lds_dwordx4 v0, s[76:77] offset:128
	s_add_i32 m0, s63, 0x19f80
	global_load_lds_dwordx4 v174, s[76:77] offset:128
	s_add_i32 m0, s63, 0x1bf80
	s_nop 0
	global_load_lds_dwordx4 v0, s[48:49] offset:128
	s_add_i32 m0, s63, 0x1df80
	s_nop 0
	global_load_lds_dwordx4 v174, s[48:49] offset:128
	s_add_i32 m0, s70, 0xffffff80
	s_nop 0
	global_load_lds_dwordx4 v170, s[46:47] offset:128
	s_add_i32 m0, s71, 0xffffff80
	s_nop 0
	global_load_lds_dwordx4 v172, s[46:47] offset:128
	s_waitcnt vmcnt(8) lgkmcnt(0)
	s_barrier
	v_mfma_f32_16x16x32_bf16 v[86:89], v[138:141], v[194:197], v[86:89]
	v_mfma_f32_16x16x32_bf16 v[14:17], v[146:149], v[194:197], v[14:17]
	v_mfma_f32_16x16x32_bf16 v[70:73], v[138:141], v[202:205], v[70:73]
	v_mfma_f32_16x16x32_bf16 v[6:9], v[146:149], v[202:205], v[6:9]
	v_mfma_f32_16x16x32_bf16 v[102:105], v[138:141], v[228:231], v[102:105]
	v_mfma_f32_16x16x32_bf16 v[30:33], v[146:149], v[228:231], v[30:33]
	v_mfma_f32_16x16x32_bf16 v[98:101], v[138:141], v[236:239], v[98:101]
	v_mfma_f32_16x16x32_bf16 v[26:29], v[146:149], v[236:239], v[26:29]
	v_mfma_f32_16x16x32_bf16 v[86:89], v[142:145], v[198:201], v[86:89]
	v_mfma_f32_16x16x32_bf16 v[14:17], v[150:153], v[198:201], v[14:17]
	v_mfma_f32_16x16x32_bf16 v[70:73], v[142:145], v[214:217], v[70:73]
	v_mfma_f32_16x16x32_bf16 v[6:9], v[150:153], v[214:217], v[6:9]
	v_mfma_f32_16x16x32_bf16 v[102:105], v[142:145], v[232:235], v[102:105]
	v_mfma_f32_16x16x32_bf16 v[30:33], v[150:153], v[232:235], v[30:33]
	v_mfma_f32_16x16x32_bf16 v[98:101], v[142:145], v[240:243], v[98:101]
	v_mfma_f32_16x16x32_bf16 v[26:29], v[150:153], v[240:243], v[26:29]
	v_mfma_f32_16x16x32_bf16 v[82:85], v[154:157], v[194:197], v[82:85]
	v_mfma_f32_16x16x32_bf16 v[10:13], v[162:165], v[194:197], v[10:13]
	v_mfma_f32_16x16x32_bf16 v[66:69], v[154:157], v[202:205], v[66:69]
	v_mfma_f32_16x16x32_bf16 v[2:5], v[162:165], v[202:205], v[2:5]
	v_mfma_f32_16x16x32_bf16 v[94:97], v[154:157], v[228:231], v[94:97]
	v_mfma_f32_16x16x32_bf16 v[22:25], v[162:165], v[228:231], v[22:25]
	v_mfma_f32_16x16x32_bf16 v[90:93], v[154:157], v[236:239], v[90:93]
	v_mfma_f32_16x16x32_bf16 v[18:21], v[162:165], v[236:239], v[18:21]
	v_mfma_f32_16x16x32_bf16 v[82:85], v[158:161], v[198:201], v[82:85]
	v_mfma_f32_16x16x32_bf16 v[10:13], v[166:169], v[198:201], v[10:13]
	v_mfma_f32_16x16x32_bf16 v[66:69], v[158:161], v[214:217], v[66:69]
	v_mfma_f32_16x16x32_bf16 v[2:5], v[166:169], v[214:217], v[2:5]
	v_mfma_f32_16x16x32_bf16 v[94:97], v[158:161], v[232:235], v[94:97]
	v_mfma_f32_16x16x32_bf16 v[22:25], v[166:169], v[232:235], v[22:25]
	v_mfma_f32_16x16x32_bf16 v[90:93], v[158:161], v[240:243], v[90:93]
	v_mfma_f32_16x16x32_bf16 v[18:21], v[166:169], v[240:243], v[18:21]
	s_barrier
	s_add_u32 s35, s35, 0x100
	s_addc_u32 s51, s51, 0
	s_cmp_ge_i32 s52, s68
	s_mov_b64 s[48:49], s[14:15]
	s_mov_b32 s46, s52
	s_cbranch_scc0 .LBB0_1495
	s_setprio 0
	s_movk_i32 s78, 0x7ff
	s_movk_i32 s76, 0x3000
	s_and_b64 vcc, exec, s[30:31]
	s_cbranch_vccz .LBB0_1470

; #define PG8_STAGE(bufoff, gbase, voff) do { _Pragma("unroll") for (int _i = 0; _i < 2; ++_i) \
;         __builtin_amdgcn_global_load_lds((const unsigned*)((const char*)(gbase) + (voff)[_i]), (PG8_LAS unsigned*)(lds + (bufoff) + ldsw + _i * 8192), 16, 0, 0); } while (0)
; #define PG8_LDA(dst, b, h) do { _Pragma("unroll") for (int m = 0; m < 4; ++m) _Pragma("unroll") for (int k = 0; k < 2; ++k) dst[m][k] = *(const PG8_LAS bf16x8*)(lds + PG8_SA(b, h) + aoff + m * 2048 + k * 1024); } while (0)
; #define PG8_LDB(dst, b, h) do { _Pragma("unroll") for (int n = 0; n < 2; ++n) _Pragma("unroll") for (int k = 0; k < 2; ++k) dst[n][k] = *(const PG8_LAS bf16x8*)(lds + PG8_SB(b, h) + boff + n * 2048 + k * 1024); } while (0)
; #define PG8_MMA(ai, bj, At, Bt) do { __builtin_amdgcn_s_setprio(1); _Pragma("unroll") for (int m = 0; m < 4; ++m) _Pragma("unroll") for (int n = 0; n < 2; ++n) _Pragma("unroll") for (int k = 0; k < 2; ++k) \
;         acc[ai][bj][m][n] = __builtin_amdgcn_mfma_f32_16x16x32_bf16(Bt[n][k], At[m][k], acc[ai][bj][m][n], 0, 0, 0); __builtin_amdgcn_s_setprio(0); } while (0)
; #define PG8_WAIT_V(n) asm volatile("s_waitcnt vmcnt(" #n ")" ::: "memory")
; #define PG8_WAIT_L(n) asm volatile("s_waitcnt lgkmcnt(" #n ")" ::: "memory")
; template <class Epi, class Sched, bool ALIGN_EPI = false, bool SP2 = false>
; __device__ __forceinline__ void gemm_phase(PG8_LAS unsigned char* lds, const Gemm g, const Sched& S, const Epi& E, const int wv) {
;     ...
;             const bool last = (t == nt - 2);
;             const char* a1 = cA + (size_t)(t + 1) * kstep;
;             const char* a2 = last ? nA : cA + (size_t)(t + 2) * kstep; const char* b2 = last ? nB : cB + (size_t)(t + 2) * kstep;
;             const char* a3 = a2 + kstep; const char* b3 = b2 + kstep;
;             if (last && has_next) S.a_ready(nxt);
;             if constexpr (SP2) {
;             PG8_LDB(B0, 0, 0); PG8_LDB(B1, 0, 1); PG8_SCHED; PG8_LDA(At, 0, 0); PG8_STAGE(PG8_SA(1, 1), a1 + hstepA, voffA);
;             PG8_WAIT_V(8); PG8_WAIT_L(0); PG8_BAR; PG8_MMA(0, 0, At, B0); PG8_MMA(0, 1, At, B1); PG8_BAR; PG8_SCHED;
;             PG8_LDA(At, 0, 1); PG8_STAGE(PG8_SB(0, 0), b2, voffB); PG8_STAGE(PG8_SB(0, 1), b2 + hstepB, voffB); PG8_STAGE(PG8_SA(0, 0), a2, voffA);
;             PG8_WAIT_V(8); PG8_WAIT_L(0); PG8_BAR; PG8_MMA(1, 0, At, B0); PG8_MMA(1, 1, At, B1); PG8_BAR; PG8_SCHED;
.Lsp_skip_8:
.LBB0_1676:
	s_add_i32 s67, s44, 2
	s_add_u32 s34, s30, 0x100
	s_addc_u32 s35, s31, 0
	s_cmp_eq_u32 s59, s44
	s_cselect_b32 s45, s13, s35
	s_cselect_b32 s44, s12, s34
	s_cselect_b32 s69, s15, s66
	s_cselect_b32 s68, s14, s65
	ds_read_b128 v[114:117], v197
	ds_read_b128 v[126:129], v197 offset:1024
	ds_read_b128 v[138:141], v197 offset:2048
	ds_read_b128 v[142:145], v197 offset:3072
	ds_read_b128 v[146:149], v201
	ds_read_b128 v[150:153], v201 offset:1024
	ds_read_b128 v[154:157], v201 offset:2048
	ds_read_b128 v[158:161], v201 offset:3072
	s_add_i32 m0, s52, 0xc000
	ds_read_b128 v[162:165], v235
	ds_read_b128 v[166:169], v235 offset:1024
	ds_read_b128 v[170:173], v235 offset:2048
	ds_read_b128 v[174:177], v235 offset:3072
	ds_read_b128 v[178:181], v235 offset:4096
	ds_read_b128 v[182:185], v235 offset:5120
	ds_read_b128 v[204:207], v235 offset:6144
	ds_read_b128 v[208:211], v235 offset:7168
	global_load_lds_dwordx4 v200, s[30:31]
	s_add_i32 m0, s52, 0xe000
	s_nop 0
	global_load_lds_dwordx4 v202, s[30:31]
	s_waitcnt vmcnt(8) lgkmcnt(0)
	s_barrier
	v_mfma_f32_16x16x32_bf16 v[134:137], v[114:117], v[162:165], v[134:137]
	v_mfma_f32_16x16x32_bf16 v[130:133], v[138:141], v[162:165], v[130:133]
	v_mfma_f32_16x16x32_bf16 v[110:113], v[114:117], v[170:173], v[110:113]
	v_mfma_f32_16x16x32_bf16 v[106:109], v[138:141], v[170:173], v[106:109]
	v_mfma_f32_16x16x32_bf16 v[94:97], v[114:117], v[178:181], v[94:97]
	v_mfma_f32_16x16x32_bf16 v[90:93], v[138:141], v[178:181], v[90:93]
	v_mfma_f32_16x16x32_bf16 v[78:81], v[114:117], v[204:207], v[78:81]
	v_mfma_f32_16x16x32_bf16 v[74:77], v[138:141], v[204:207], v[74:77]
	v_mfma_f32_16x16x32_bf16 v[134:137], v[126:129], v[166:169], v[134:137]
	v_mfma_f32_16x16x32_bf16 v[130:133], v[142:145], v[166:169], v[130:133]
	v_mfma_f32_16x16x32_bf16 v[110:113], v[126:129], v[174:177], v[110:113]
	v_mfma_f32_16x16x32_bf16 v[106:109], v[142:145], v[174:177], v[106:109]
	v_mfma_f32_16x16x32_bf16 v[94:97], v[126:129], v[182:185], v[94:97]
	v_mfma_f32_16x16x32_bf16 v[90:93], v[142:145], v[182:185], v[90:93]
	v_mfma_f32_16x16x32_bf16 v[78:81], v[126:129], v[208:211], v[78:81]
	v_mfma_f32_16x16x32_bf16 v[74:77], v[142:145], v[208:211], v[74:77]
	v_mfma_f32_16x16x32_bf16 v[122:125], v[146:149], v[162:165], v[122:125]
	v_mfma_f32_16x16x32_bf16 v[118:121], v[154:157], v[162:165], v[118:121]
	v_mfma_f32_16x16x32_bf16 v[102:105], v[146:149], v[170:173], v[102:105]
	v_mfma_f32_16x16x32_bf16 v[98:101], v[154:157], v[170:173], v[98:101]
	v_mfma_f32_16x16x32_bf16 v[86:89], v[146:149], v[178:181], v[86:89]
	v_mfma_f32_16x16x32_bf16 v[82:85], v[154:157], v[178:181], v[82:85]
	v_mfma_f32_16x16x32_bf16 v[70:73], v[146:149], v[204:207], v[70:73]
	v_mfma_f32_16x16x32_bf16 v[66:69], v[154:157], v[204:207], v[66:69]
	v_mfma_f32_16x16x32_bf16 v[122:125], v[150:153], v[166:169], v[122:125]
	v_mfma_f32_16x16x32_bf16 v[118:121], v[158:161], v[166:169], v[118:121]
	v_mfma_f32_16x16x32_bf16 v[102:105], v[150:153], v[174:177], v[102:105]
	v_mfma_f32_16x16x32_bf16 v[98:101], v[158:161], v[174:177], v[98:101]
	v_mfma_f32_16x16x32_bf16 v[86:89], v[150:153], v[182:185], v[86:89]
	v_mfma_f32_16x16x32_bf16 v[82:85], v[158:161], v[182:185], v[82:85]
	v_mfma_f32_16x16x32_bf16 v[70:73], v[150:153], v[208:211], v[70:73]
	v_mfma_f32_16x16x32_bf16 v[66:69], v[158:161], v[208:211], v[66:69]
	s_barrier
	s_add_i32 s30, s47, 0x10000
	v_lshl_add_u64 v[190:191], s[68:69], 0, v[0:1]
	s_mov_b32 m0, s30
	ds_read_b128 v[162:165], v235 offset:16384
	ds_read_b128 v[166:169], v235 offset:17408
	ds_read_b128 v[170:173], v235 offset:18432
	ds_read_b128 v[174:177], v235 offset:19456
	ds_read_b128 v[178:181], v235 offset:20480
	ds_read_b128 v[182:185], v235 offset:21504
	ds_read_b128 v[204:207], v235 offset:22528
	ds_read_b128 v[208:211], v235 offset:23552
	global_load_lds_dwordx4 v[190:191], off
	s_add_i32 m0, s30, 0x2000
	s_add_u32 s30, s68, s2
	v_lshl_add_u64 v[192:193], s[68:69], 0, v[198:199]
	s_addc_u32 s31, s69, s3
	s_add_i32 s68, s47, 0x14000
	global_load_lds_dwordx4 v[192:193], off
	v_lshl_add_u64 v[212:213], s[30:31], 0, v[0:1]
	s_mov_b32 m0, s68
	v_lshl_add_u64 v[214:215], s[30:31], 0, v[198:199]
	global_load_lds_dwordx4 v[212:213], off
	s_add_i32 m0, s68, 0x2000
	global_load_lds_dwordx4 v[214:215], off
	s_mov_b32 m0, s52
	global_load_lds_dwordx4 v194, s[44:45]
	s_mov_b32 m0, s53
	s_nop 0
	global_load_lds_dwordx4 v196, s[44:45]
	s_waitcnt vmcnt(8) lgkmcnt(0)
	s_barrier
	v_mfma_f32_16x16x32_bf16 v[62:65], v[114:117], v[162:165], v[62:65]
	v_mfma_f32_16x16x32_bf16 v[58:61], v[138:141], v[162:165], v[58:61]
	v_mfma_f32_16x16x32_bf16 v[46:49], v[114:117], v[170:173], v[46:49]
	v_mfma_f32_16x16x32_bf16 v[42:45], v[138:141], v[170:173], v[42:45]
	v_mfma_f32_16x16x32_bf16 v[30:33], v[114:117], v[178:181], v[30:33]
	v_mfma_f32_16x16x32_bf16 v[26:29], v[138:141], v[178:181], v[26:29]
	v_mfma_f32_16x16x32_bf16 v[14:17], v[114:117], v[204:207], v[14:17]
	v_mfma_f32_16x16x32_bf16 v[10:13], v[138:141], v[204:207], v[10:13]
	v_mfma_f32_16x16x32_bf16 v[62:65], v[126:129], v[166:169], v[62:65]
	v_mfma_f32_16x16x32_bf16 v[58:61], v[142:145], v[166:169], v[58:61]
	v_mfma_f32_16x16x32_bf16 v[46:49], v[126:129], v[174:177], v[46:49]
	v_mfma_f32_16x16x32_bf16 v[42:45], v[142:145], v[174:177], v[42:45]
	v_mfma_f32_16x16x32_bf16 v[30:33], v[126:129], v[182:185], v[30:33]
	v_mfma_f32_16x16x32_bf16 v[26:29], v[142:145], v[182:185], v[26:29]
	v_mfma_f32_16x16x32_bf16 v[14:17], v[126:129], v[208:211], v[14:17]
	v_mfma_f32_16x16x32_bf16 v[10:13], v[142:145], v[208:211], v[10:13]
	v_mfma_f32_16x16x32_bf16 v[54:57], v[146:149], v[162:165], v[54:57]
	v_mfma_f32_16x16x32_bf16 v[50:53], v[154:157], v[162:165], v[50:53]
	v_mfma_f32_16x16x32_bf16 v[38:41], v[146:149], v[170:173], v[38:41]
	v_mfma_f32_16x16x32_bf16 v[34:37], v[154:157], v[170:173], v[34:37]
	v_mfma_f32_16x16x32_bf16 v[22:25], v[146:149], v[178:181], v[22:25]
	v_mfma_f32_16x16x32_bf16 v[18:21], v[154:157], v[178:181], v[18:21]
	v_mfma_f32_16x16x32_bf16 v[6:9], v[146:149], v[204:207], v[6:9]
	v_mfma_f32_16x16x32_bf16 v[2:5], v[154:157], v[204:207], v[2:5]
	v_mfma_f32_16x16x32_bf16 v[54:57], v[150:153], v[166:169], v[54:57]
	v_mfma_f32_16x16x32_bf16 v[50:53], v[158:161], v[166:169], v[50:53]
	v_mfma_f32_16x16x32_bf16 v[38:41], v[150:153], v[174:177], v[38:41]
	v_mfma_f32_16x16x32_bf16 v[34:37], v[158:161], v[174:177], v[34:37]
	v_mfma_f32_16x16x32_bf16 v[22:25], v[150:153], v[182:185], v[22:25]
	v_mfma_f32_16x16x32_bf16 v[18:21], v[158:161], v[182:185], v[18:21]
	v_mfma_f32_16x16x32_bf16 v[6:9], v[150:153], v[208:211], v[6:9]
	v_mfma_f32_16x16x32_bf16 v[2:5], v[158:161], v[208:211], v[2:5]
	s_barrier
; #define PG8_STAGE(bufoff, gbase, voff) do { _Pragma("unroll") for (int _i = 0; _i < 2; ++_i) \
;         __builtin_amdgcn_global_load_lds((const unsigned*)((const char*)(gbase) + (voff)[_i]), (PG8_LAS unsigned*)(lds + (bufoff) + ldsw + _i * 8192), 16, 0, 0); } while (0)
; #define PG8_LDA(dst, b, h) do { _Pragma("unroll") for (int m = 0; m < 4; ++m) _Pragma("unroll") for (int k = 0; k < 2; ++k) dst[m][k] = *(const PG8_LAS bf16x8*)(lds + PG8_SA(b, h) + aoff + m * 2048 + k * 1024); } while (0)
; #define PG8_LDB(dst, b, h) do { _Pragma("unroll") for (int n = 0; n < 2; ++n) _Pragma("unroll") for (int k = 0; k < 2; ++k) dst[n][k] = *(const PG8_LAS bf16x8*)(lds + PG8_SB(b, h) + boff + n * 2048 + k * 1024); } while (0)
; #define PG8_MMA(ai, bj, At, Bt) do { __builtin_amdgcn_s_setprio(1); _Pragma("unroll") for (int m = 0; m < 4; ++m) _Pragma("unroll") for (int n = 0; n < 2; ++n) _Pragma("unroll") for (int k = 0; k < 2; ++k) \
;         acc[ai][bj][m][n] = __builtin_amdgcn_mfma_f32_16x16x32_bf16(Bt[n][k], At[m][k], acc[ai][bj][m][n], 0, 0, 0); __builtin_amdgcn_s_setprio(0); } while (0)
; #define PG8_WAIT_V(n) asm volatile("s_waitcnt vmcnt(" #n ")" ::: "memory")
; #define PG8_WAIT_L(n) asm volatile("s_waitcnt lgkmcnt(" #n ")" ::: "memory")
; #define PG8_BAR __builtin_amdgcn_s_barrier()
; #define PG8_SCHED __builtin_amdgcn_sched_barrier(0)
; template <class Epi, class Sched, bool ALIGN_EPI = false, bool SP2 = false>
; __device__ __forceinline__ void gemm_phase(PG8_LAS unsigned char* lds, const Gemm g, const Sched& S, const Epi& E, const int wv) {
;     ...
;         for (int t = 0; t < nt; t += 2) {
;     ...
;             PG8_LDB(B0, 1, 0); PG8_LDB(B1, 1, 1); PG8_SCHED; PG8_LDA(At, 1, 0); PG8_STAGE(PG8_SA(0, 1), a2 + hstepA, voffA);
;             PG8_WAIT_V(8); PG8_WAIT_L(0); PG8_BAR; PG8_MMA(0, 0, At, B0); PG8_MMA(0, 1, At, B1); PG8_BAR; PG8_SCHED;
;             PG8_LDA(At, 1, 1); PG8_STAGE(PG8_SB(1, 0), b3, voffB); PG8_STAGE(PG8_SB(1, 1), b3 + hstepB, voffB); PG8_STAGE(PG8_SA(1, 0), a3, voffA);
;             PG8_WAIT_V(8); PG8_WAIT_L(0); PG8_BAR; PG8_MMA(1, 0, At, B0); PG8_MMA(1, 1, At, B1); PG8_BAR; PG8_SCHED;
	ds_read_b128 v[114:117], v203
	ds_read_b128 v[126:129], v203 offset:1024
	ds_read_b128 v[138:141], v203 offset:2048
	ds_read_b128 v[142:145], v203 offset:3072
	ds_read_b128 v[146:149], v216
	ds_read_b128 v[150:153], v216 offset:1024
	ds_read_b128 v[154:157], v216 offset:2048
	ds_read_b128 v[158:161], v216 offset:3072
	s_add_u32 s30, s44, 0x180000
	s_addc_u32 s31, s45, 0
	s_mov_b32 m0, s54
	ds_read_b128 v[162:165], v235 offset:32768
	ds_read_b128 v[166:169], v235 offset:33792
	ds_read_b128 v[170:173], v235 offset:34816
	ds_read_b128 v[174:177], v235 offset:35840
	ds_read_b128 v[178:181], v235 offset:36864
	ds_read_b128 v[182:185], v235 offset:37888
	ds_read_b128 v[204:207], v235 offset:38912
	ds_read_b128 v[208:211], v235 offset:39936
	global_load_lds_dwordx4 v194, s[30:31]
	s_mov_b32 m0, s55
	s_nop 0
	global_load_lds_dwordx4 v196, s[30:31]
	s_waitcnt vmcnt(8) lgkmcnt(0)
	s_barrier
	v_mfma_f32_16x16x32_bf16 v[134:137], v[114:117], v[162:165], v[134:137]
	v_mfma_f32_16x16x32_bf16 v[130:133], v[138:141], v[162:165], v[130:133]
	v_mfma_f32_16x16x32_bf16 v[110:113], v[114:117], v[170:173], v[110:113]
	v_mfma_f32_16x16x32_bf16 v[106:109], v[138:141], v[170:173], v[106:109]
	v_mfma_f32_16x16x32_bf16 v[94:97], v[114:117], v[178:181], v[94:97]
	v_mfma_f32_16x16x32_bf16 v[90:93], v[138:141], v[178:181], v[90:93]
	v_mfma_f32_16x16x32_bf16 v[78:81], v[114:117], v[204:207], v[78:81]
	v_mfma_f32_16x16x32_bf16 v[74:77], v[138:141], v[204:207], v[74:77]
	v_mfma_f32_16x16x32_bf16 v[134:137], v[126:129], v[166:169], v[134:137]
	v_mfma_f32_16x16x32_bf16 v[130:133], v[142:145], v[166:169], v[130:133]
	v_mfma_f32_16x16x32_bf16 v[110:113], v[126:129], v[174:177], v[110:113]
	v_mfma_f32_16x16x32_bf16 v[106:109], v[142:145], v[174:177], v[106:109]
	v_mfma_f32_16x16x32_bf16 v[94:97], v[126:129], v[182:185], v[94:97]
	v_mfma_f32_16x16x32_bf16 v[90:93], v[142:145], v[182:185], v[90:93]
	v_mfma_f32_16x16x32_bf16 v[78:81], v[126:129], v[208:211], v[78:81]
	v_mfma_f32_16x16x32_bf16 v[74:77], v[142:145], v[208:211], v[74:77]
	v_mfma_f32_16x16x32_bf16 v[122:125], v[146:149], v[162:165], v[122:125]
	v_mfma_f32_16x16x32_bf16 v[118:121], v[154:157], v[162:165], v[118:121]
	v_mfma_f32_16x16x32_bf16 v[102:105], v[146:149], v[170:173], v[102:105]
	v_mfma_f32_16x16x32_bf16 v[98:101], v[154:157], v[170:173], v[98:101]
	v_mfma_f32_16x16x32_bf16 v[86:89], v[146:149], v[178:181], v[86:89]
	v_mfma_f32_16x16x32_bf16 v[82:85], v[154:157], v[178:181], v[82:85]
	v_mfma_f32_16x16x32_bf16 v[70:73], v[146:149], v[204:207], v[70:73]
	v_mfma_f32_16x16x32_bf16 v[66:69], v[154:157], v[204:207], v[66:69]
	v_mfma_f32_16x16x32_bf16 v[122:125], v[150:153], v[166:169], v[122:125]
	v_mfma_f32_16x16x32_bf16 v[118:121], v[158:161], v[166:169], v[118:121]
	v_mfma_f32_16x16x32_bf16 v[102:105], v[150:153], v[174:177], v[102:105]
	v_mfma_f32_16x16x32_bf16 v[98:101], v[158:161], v[174:177], v[98:101]
	v_mfma_f32_16x16x32_bf16 v[86:89], v[150:153], v[182:185], v[86:89]
	v_mfma_f32_16x16x32_bf16 v[82:85], v[158:161], v[182:185], v[82:85]
	v_mfma_f32_16x16x32_bf16 v[70:73], v[150:153], v[208:211], v[70:73]
	v_mfma_f32_16x16x32_bf16 v[66:69], v[158:161], v[208:211], v[66:69]
	s_barrier
	s_add_i32 s30, s47, 0x18000
	s_add_i32 m0, s30, 0xffffff80
	ds_read_b128 v[162:165], v235 offset:49152
	ds_read_b128 v[166:169], v235 offset:50176
	ds_read_b128 v[170:173], v235 offset:51200
	ds_read_b128 v[174:177], v235 offset:52224
	ds_read_b128 v[178:181], v235 offset:53248
	ds_read_b128 v[182:185], v235 offset:54272
	ds_read_b128 v[204:207], v235 offset:55296
	ds_read_b128 v[208:211], v235 offset:56320
	global_load_lds_dwordx4 v[190:191], off offset:128
	s_add_i32 m0, s30, 0x1f80
	s_add_i32 s30, s47, 0x1c000
	global_load_lds_dwordx4 v[192:193], off offset:128
	s_add_i32 m0, s30, 0xffffff80
	s_nop 0
	global_load_lds_dwordx4 v[212:213], off offset:128
	s_add_i32 m0, s30, 0x1f80
	s_nop 0
	global_load_lds_dwordx4 v[214:215], off offset:128
	s_add_i32 m0, s57, 0xffffff80
	s_nop 0
	global_load_lds_dwordx4 v194, s[44:45] offset:128
	s_add_i32 m0, s58, 0xffffff80
	s_nop 0
	global_load_lds_dwordx4 v196, s[44:45] offset:128
	s_waitcnt vmcnt(8) lgkmcnt(0)
	s_barrier
	v_mfma_f32_16x16x32_bf16 v[62:65], v[114:117], v[162:165], v[62:65]
	v_mfma_f32_16x16x32_bf16 v[58:61], v[138:141], v[162:165], v[58:61]
	v_mfma_f32_16x16x32_bf16 v[46:49], v[114:117], v[170:173], v[46:49]
	v_mfma_f32_16x16x32_bf16 v[42:45], v[138:141], v[170:173], v[42:45]
	v_mfma_f32_16x16x32_bf16 v[30:33], v[114:117], v[178:181], v[30:33]
	v_mfma_f32_16x16x32_bf16 v[26:29], v[138:141], v[178:181], v[26:29]
	v_mfma_f32_16x16x32_bf16 v[14:17], v[114:117], v[204:207], v[14:17]
	v_mfma_f32_16x16x32_bf16 v[10:13], v[138:141], v[204:207], v[10:13]
	v_mfma_f32_16x16x32_bf16 v[62:65], v[126:129], v[166:169], v[62:65]
	v_mfma_f32_16x16x32_bf16 v[58:61], v[142:145], v[166:169], v[58:61]
	v_mfma_f32_16x16x32_bf16 v[46:49], v[126:129], v[174:177], v[46:49]
	v_mfma_f32_16x16x32_bf16 v[42:45], v[142:145], v[174:177], v[42:45]
	v_mfma_f32_16x16x32_bf16 v[30:33], v[126:129], v[182:185], v[30:33]
	v_mfma_f32_16x16x32_bf16 v[26:29], v[142:145], v[182:185], v[26:29]
	v_mfma_f32_16x16x32_bf16 v[14:17], v[126:129], v[208:211], v[14:17]
	v_mfma_f32_16x16x32_bf16 v[10:13], v[142:145], v[208:211], v[10:13]
	v_mfma_f32_16x16x32_bf16 v[54:57], v[146:149], v[162:165], v[54:57]
	v_mfma_f32_16x16x32_bf16 v[50:53], v[154:157], v[162:165], v[50:53]
	v_mfma_f32_16x16x32_bf16 v[38:41], v[146:149], v[170:173], v[38:41]
	v_mfma_f32_16x16x32_bf16 v[34:37], v[154:157], v[170:173], v[34:37]
	v_mfma_f32_16x16x32_bf16 v[22:25], v[146:149], v[178:181], v[22:25]
	v_mfma_f32_16x16x32_bf16 v[18:21], v[154:157], v[178:181], v[18:21]
	v_mfma_f32_16x16x32_bf16 v[6:9], v[146:149], v[204:207], v[6:9]
	v_mfma_f32_16x16x32_bf16 v[2:5], v[154:157], v[204:207], v[2:5]
	v_mfma_f32_16x16x32_bf16 v[54:57], v[150:153], v[166:169], v[54:57]
	v_mfma_f32_16x16x32_bf16 v[50:53], v[158:161], v[166:169], v[50:53]
	v_mfma_f32_16x16x32_bf16 v[38:41], v[150:153], v[174:177], v[38:41]
	v_mfma_f32_16x16x32_bf16 v[34:37], v[158:161], v[174:177], v[34:37]
	v_mfma_f32_16x16x32_bf16 v[22:25], v[150:153], v[182:185], v[22:25]
	v_mfma_f32_16x16x32_bf16 v[18:21], v[158:161], v[182:185], v[18:21]
	v_mfma_f32_16x16x32_bf16 v[6:9], v[150:153], v[208:211], v[6:9]
	v_mfma_f32_16x16x32_bf16 v[2:5], v[158:161], v[208:211], v[2:5]
	s_barrier
	s_add_u32 s65, s65, 0x100
	s_addc_u32 s66, s66, 0
	s_cmp_ge_i32 s67, s56
	s_mov_b64 s[30:31], s[34:35]
	s_mov_b32 s44, s67
	s_cbranch_scc0 .LBB0_1676
	s_setprio 0
	s_movk_i32 s68, 0x4000
	s_movk_i32 s69, 0x6000
	s_mov_b32 s70, 0x18000
	s_mov_b32 s71, 0x3f317217
	s_and_b64 vcc, exec, s[28:29]
	s_cbranch_vccz .LBB0_1652
